# v22 + next tile's first 16 LDS fragment reads issued at the tile-loop header, ahead of the tile-setup scalar code; bit-identical
# speedup vs baseline: 1.0027x; 1.0027x over previous
; #define PG8_STAGE(bufoff, gbase, voff) do { _Pragma("unroll") for (int _i = 0; _i < 2; ++_i) \
;         __builtin_amdgcn_global_load_lds((const unsigned*)((const char*)(gbase) + (voff)[_i]), (PG8_LAS unsigned*)(lds + (bufoff) + ldsw + _i * 8192), 16, 0, 0); } while (0)
; #define PG8_LDA(dst, b, h) do { _Pragma("unroll") for (int m = 0; m < 4; ++m) _Pragma("unroll") for (int k = 0; k < 2; ++k) dst[m][k] = *(const PG8_LAS bf16x8*)(lds + PG8_SA(b, h) + aoff + m * 2048 + k * 1024); } while (0)
; #define PG8_WAIT_V(n) asm volatile("s_waitcnt vmcnt(" #n ")" ::: "memory")
; #define PG8_BAR __builtin_amdgcn_s_barrier()
;     __host__ __device__ bool next(int i, Unit& u) const {
;         const long L = (long)i * G + c; if (L >= nwg) return false;
;         int wgid = (int)L; { const int q = nwg / NXCD, r = nwg % NXCD, xcd = wgid % NXCD, off = wgid / NXCD; wgid = (xcd < r ? xcd * (q + 1) : r * (q + 1) + (xcd - r) * q) + off; }
;         const int nig = WGM * nN, gid = wgid / nig, fm = gid * WGM, gsz = (nM - fm) < WGM ? (nM - fm) : WGM;
;         u.pm = fm + ((wgid % nig) % gsz); u.pn = (wgid % nig) / gsz; return true;
;     }
; template <class Epi, class Sched, bool ALIGN_EPI = false, bool SP2 = false>
; __device__ __forceinline__ void gemm_phase(PG8_LAS unsigned char* lds, const Gemm g, const Sched& S, const Epi& E) {
;     ...
;         const bool has_next = S.next(ui + 1, nxt);
;         const char* nA = has_next ? (const char*)g.A + (size_t)nxt.pm * tstepA : cA; const char* nB = has_next ? (const char*)g.Bt + (size_t)nxt.pn * tstep : cB;
;         for (int t = 0; t < nt; t += 2) {
;             const bool last = (t == nt - 2);
;             const char* a1 = cA + (size_t)(t + 1) * kstepA;
;             const char* a2 = last ? nA : cA + (size_t)(t + 2) * kstepA; const char* b2 = last ? nB : cB + (size_t)(t + 2) * kstep;
;             const char* a3 = a2 + kstepA; const char* b3 = b2 + kstep;
;             if (last && has_next) S.a_ready(nxt);
;             if constexpr (SP2) {
;             PG8_LDB(B0, 0, 0); PG8_LDB(B1, 0, 1); PG8_SCHED; PG8_LDA(At, 0, 0); PG8_STAGE(PG8_SA(1, 1), a1 + hstepA, voffA);
;             PG8_WAIT_V(8); PG8_WAIT_L(0); PG8_BAR; PG8_MMA(0, 0, At, B0); PG8_MMA(0, 1, At, B1); PG8_BAR; PG8_SCHED;
;             PG8_LDA(At, 0, 1); PG8_STAGE(PG8_SB(0, 0), b2, voffB); PG8_STAGE(PG8_SB(0, 1), b2 + hstep, voffB); PG8_STAGE(PG8_SA(0, 0), a2, voffA);
.LBB0_193:
	v_add_u32_e32 v244, 0x10000, v143
	v_add_u32_e32 v245, 0x14000, v143
	ds_read_b128 v[138:141], v244
	ds_read_b128 v[146:149], v244 offset:1024
	ds_read_b128 v[150:153], v244 offset:2048
	ds_read_b128 v[154:157], v244 offset:3072
	ds_read_b128 v[158:161], v245
	ds_read_b128 v[162:165], v245 offset:1024
	ds_read_b128 v[170:173], v245 offset:2048
	ds_read_b128 v[188:191], v245 offset:3072
	ds_read_b128 v[192:195], v145
	ds_read_b128 v[196:199], v145 offset:1024
	ds_read_b128 v[200:203], v145 offset:2048
	ds_read_b128 v[204:207], v145 offset:3072
	ds_read_b128 v[208:211], v145 offset:4096
	ds_read_b128 v[212:215], v145 offset:5120
	ds_read_b128 v[216:219], v145 offset:6144
	ds_read_b128 v[220:223], v145 offset:7168
	s_add_i32 s51, s51, 1
	s_mul_i32 s25, s51, s11
	s_mul_hi_u32 s27, s51, s10
	s_add_i32 s27, s27, s25
	s_mul_i32 s25, s51, s10
	s_add_u32 s38, s25, s93
	s_addc_u32 s39, s27, s9
	v_mov_b64_e32 v[0:1], 0x600
	v_cmp_lt_i64_e64 s[36:37], s[38:39], v[0:1]
	v_mov_b64_e32 v[0:1], 0x5ff
	v_cmp_gt_i64_e32 vcc, s[38:39], v[0:1]
	s_cbranch_vccnz .LBB0_195
	s_ashr_i32 s24, s38, 31
	s_lshr_b32 s24, s24, 29
	s_add_i32 s24, s38, s24
	s_ashr_i32 s25, s24, 3
	s_and_b32 s24, s24, -8
	s_sub_i32 s24, s38, s24
	s_cmp_lt_i32 s24, 0
	s_movk_i32 s26, 0xc1
	s_cselect_b32 s26, s26, 0xc0
	s_mul_i32 s24, s24, s26
	s_add_i32 s24, s24, s25
	s_mul_hi_i32 s25, s24, 0x2aaaaaab
	s_lshr_b32 s26, s25, 31
	s_ashr_i32 s25, s25, 3
	s_add_i32 s25, s25, s26
	s_lshl_b32 s26, s25, 3
	s_sub_i32 s27, 0x100, s26
	s_min_i32 s27, s27, 8
	s_abs_i32 s38, s27
	v_cvt_f32_u32_e32 v0, s38
	s_sub_i32 s40, 0, s38
	s_mul_i32 s25, s25, 48
	s_sub_i32 s25, s24, s25
	v_rcp_iflag_f32_e32 v0, v0
	s_abs_i32 s24, s25
	s_xor_b32 s39, s25, s27
	s_ashr_i32 s39, s39, 31
	v_mul_f32_e32 v0, 0x4f7ffffe, v0
	v_cvt_u32_f32_e32 v0, v0
	s_nop 0
	v_readfirstlane_b32 s41, v0
	s_mul_i32 s40, s40, s41
	s_mul_hi_u32 s40, s41, s40
	s_add_i32 s41, s41, s40
	s_mul_hi_u32 s40, s24, s41
	s_mul_i32 s41, s40, s38
	s_sub_i32 s24, s24, s41
	s_add_i32 s46, s40, 1
	s_sub_i32 s41, s24, s38
	s_cmp_ge_u32 s24, s38
	s_cselect_b32 s40, s46, s40
	s_cselect_b32 s24, s41, s24
	s_add_i32 s41, s40, 1
	s_cmp_ge_u32 s24, s38
	s_cselect_b32 s24, s41, s40
	s_xor_b32 s24, s24, s39
	s_sub_i32 s24, s24, s39
	s_mul_i32 s27, s24, s27
	s_sub_i32 s25, s25, s27
	s_add_i32 s26, s26, s25
.LBB0_195:
	s_ashr_i32 s27, s26, 31
	s_lshl_b64 s[38:39], s[26:27], 19
	s_add_u32 s38, s20, s38
	s_addc_u32 s39, s21, s39
	s_and_b64 s[40:41], s[36:37], exec
	s_cselect_b32 s27, s39, s45
	s_cselect_b32 s54, s38, s44
	s_ashr_i32 s25, s24, 31
	s_lshl_b64 s[40:41], s[24:25], 19
	s_add_u32 s40, s2, s40
	s_addc_u32 s41, s3, s41
	s_and_b64 s[46:47], s[36:37], exec
	s_cselect_b32 s25, s41, s43
	s_cselect_b32 s55, s40, s42
	s_add_u32 s56, s42, 0x100
	s_addc_u32 s57, s43, 0
	s_add_u32 s42, s44, 0x40080
	s_addc_u32 s43, s45, 0
	s_mov_b32 s58, -2
	s_add_u32 s44, s42, 0xfffc0080
	s_addc_u32 s45, s43, -1
	s_add_i32 s59, 0, 0x10000
	s_cmp_eq_u32 s58, 12
	s_cselect_b32 s47, s27, s45
	s_cselect_b32 s46, s54, s44
	s_cselect_b32 s45, s25, s57
	s_cselect_b32 s44, s55, s56
	s_add_i32 s62, 0, 0x14000
	v_lshl_add_u64 v[166:167], s[42:43], 0, v[136:137]
	s_add_i32 m0, s7, 0xc000
	global_load_lds_dwordx4 v[166:167], off
	v_lshl_add_u64 v[166:167], s[42:43], 0, v[134:135]
	s_add_i32 m0, s7, 0xe000
	s_nop 0
	global_load_lds_dwordx4 v[166:167], off
	s_waitcnt vmcnt(8)
	s_waitcnt lgkmcnt(0)
	s_barrier
	s_setprio 1
	s_waitcnt lgkmcnt(0)
	v_mfma_f32_16x16x32_bf16 v[124:127], v[138:141], v[192:195], 0
	v_mfma_f32_16x16x32_bf16 v[120:123], v[150:153], v[192:195], 0
	v_mfma_f32_16x16x32_bf16 v[116:119], v[138:141], v[200:203], 0
	v_mfma_f32_16x16x32_bf16 v[108:111], v[150:153], v[200:203], 0
	v_mfma_f32_16x16x32_bf16 v[100:103], v[138:141], v[208:211], 0
	v_mfma_f32_16x16x32_bf16 v[92:95], v[150:153], v[208:211], 0
	v_mfma_f32_16x16x32_bf16 v[84:87], v[138:141], v[216:219], 0
	v_mfma_f32_16x16x32_bf16 v[76:79], v[150:153], v[216:219], 0
	v_mfma_f32_16x16x32_bf16 v[124:127], v[146:149], v[196:199], v[124:127]
	v_mfma_f32_16x16x32_bf16 v[120:123], v[154:157], v[196:199], v[120:123]
	v_mfma_f32_16x16x32_bf16 v[116:119], v[146:149], v[204:207], v[116:119]
	v_mfma_f32_16x16x32_bf16 v[108:111], v[154:157], v[204:207], v[108:111]
	v_mfma_f32_16x16x32_bf16 v[100:103], v[146:149], v[212:215], v[100:103]
	v_mfma_f32_16x16x32_bf16 v[92:95], v[154:157], v[212:215], v[92:95]
	v_mfma_f32_16x16x32_bf16 v[84:87], v[146:149], v[220:223], v[84:87]
	v_mfma_f32_16x16x32_bf16 v[76:79], v[154:157], v[220:223], v[76:79]
	s_setprio 0
	s_setprio 1
	v_mfma_f32_16x16x32_bf16 v[112:115], v[158:161], v[192:195], 0
	v_mfma_f32_16x16x32_bf16 v[104:107], v[170:173], v[192:195], 0
	v_mfma_f32_16x16x32_bf16 v[96:99], v[158:161], v[200:203], 0
	v_mfma_f32_16x16x32_bf16 v[88:91], v[170:173], v[200:203], 0
	v_mfma_f32_16x16x32_bf16 v[80:83], v[158:161], v[208:211], 0
	v_mfma_f32_16x16x32_bf16 v[72:75], v[170:173], v[208:211], 0
	v_mfma_f32_16x16x32_bf16 v[68:71], v[158:161], v[216:219], 0
	v_mfma_f32_16x16x32_bf16 v[64:67], v[170:173], v[216:219], 0
	v_mfma_f32_16x16x32_bf16 v[112:115], v[162:165], v[196:199], v[112:115]
	v_mfma_f32_16x16x32_bf16 v[104:107], v[188:191], v[196:199], v[104:107]
	v_mfma_f32_16x16x32_bf16 v[96:99], v[162:165], v[204:207], v[96:99]
	v_mfma_f32_16x16x32_bf16 v[88:91], v[188:191], v[204:207], v[88:91]
	v_mfma_f32_16x16x32_bf16 v[80:83], v[162:165], v[212:215], v[80:83]
	s_add_i32 s59, s59, s6
	v_mfma_f32_16x16x32_bf16 v[72:75], v[188:191], v[212:215], v[72:75]
	v_lshl_add_u64 v[166:167], s[44:45], 0, v[168:169]
	v_mfma_f32_16x16x32_bf16 v[68:71], v[162:165], v[220:223], v[68:71]
	s_mov_b32 m0, s59
	v_mfma_f32_16x16x32_bf16 v[64:67], v[188:191], v[220:223], v[64:67]
	s_setprio 0
	s_barrier
; #define PG8_STAGE(bufoff, gbase, voff) do { _Pragma("unroll") for (int _i = 0; _i < 2; ++_i) \
;         __builtin_amdgcn_global_load_lds((const unsigned*)((const char*)(gbase) + (voff)[_i]), (PG8_LAS unsigned*)(lds + (bufoff) + ldsw + _i * 8192), 16, 0, 0); } while (0)
; #define PG8_LDA(dst, b, h) do { _Pragma("unroll") for (int m = 0; m < 4; ++m) _Pragma("unroll") for (int k = 0; k < 2; ++k) dst[m][k] = *(const PG8_LAS bf16x8*)(lds + PG8_SA(b, h) + aoff + m * 2048 + k * 1024); } while (0)
; #define PG8_LDB(dst, b, h) do { _Pragma("unroll") for (int n = 0; n < 2; ++n) _Pragma("unroll") for (int k = 0; k < 2; ++k) dst[n][k] = *(const PG8_LAS bf16x8*)(lds + PG8_SB(b, h) + boff + n * 2048 + k * 1024); } while (0)
; #define PG8_MMA(ai, bj, At, Bt) do { __builtin_amdgcn_s_setprio(1); _Pragma("unroll") for (int m = 0; m < 4; ++m) _Pragma("unroll") for (int n = 0; n < 2; ++n) _Pragma("unroll") for (int k = 0; k < 2; ++k) \
;         acc[ai][bj][m][n] = __builtin_amdgcn_mfma_f32_16x16x32_bf16(Bt[n][k], At[m][k], acc[ai][bj][m][n], 0, 0, 0); __builtin_amdgcn_s_setprio(0); } while (0)
; #define PG8_WAIT_V(n) asm volatile("s_waitcnt vmcnt(" #n ")" ::: "memory")
; #define PG8_WAIT_L(n) asm volatile("s_waitcnt lgkmcnt(" #n ")" ::: "memory")
; #define PG8_BAR __builtin_amdgcn_s_barrier()
; #define PG8_SCHED __builtin_amdgcn_sched_barrier(0)
; template <class Epi, class Sched, bool ALIGN_EPI = false, bool SP2 = false>
; __device__ __forceinline__ void gemm_phase(PG8_LAS unsigned char* lds, const Gemm g, const Sched& S, const Epi& E) {
;     ...
;             PG8_LDA(At, 0, 1); PG8_STAGE(PG8_SB(0, 0), b2, voffB); PG8_STAGE(PG8_SB(0, 1), b2 + hstep, voffB); PG8_STAGE(PG8_SA(0, 0), a2, voffA);
;             PG8_WAIT_V(8); PG8_WAIT_L(0); PG8_BAR; PG8_MMA(1, 0, At, B0); PG8_MMA(1, 1, At, B1); PG8_BAR; PG8_SCHED;
;             PG8_LDB(B0, 1, 0); PG8_LDB(B1, 1, 1); PG8_SCHED; PG8_LDA(At, 1, 0); PG8_STAGE(PG8_SA(0, 1), a2 + hstepA, voffA);
;             PG8_WAIT_V(8); PG8_WAIT_L(0); PG8_BAR; PG8_MMA(0, 0, At, B0); PG8_MMA(0, 1, At, B1); PG8_BAR; PG8_SCHED;
;             PG8_LDA(At, 1, 1); PG8_STAGE(PG8_SB(1, 0), b3, voffB); PG8_STAGE(PG8_SB(1, 1), b3 + hstep, voffB); PG8_STAGE(PG8_SA(1, 0), a3, voffA);
	ds_read_b128 v[192:195], v145 offset:16384
	ds_read_b128 v[196:199], v145 offset:17408
	ds_read_b128 v[200:203], v145 offset:18432
	ds_read_b128 v[204:207], v145 offset:19456
	ds_read_b128 v[208:211], v145 offset:20480
	ds_read_b128 v[212:215], v145 offset:21504
	ds_read_b128 v[216:219], v145 offset:22528
	ds_read_b128 v[220:223], v145 offset:23552
	global_load_lds_dwordx4 v[166:167], off
	s_add_i32 m0, s59, 0x2000
	s_add_u32 s60, s44, 0x40000
	v_lshl_add_u64 v[178:179], s[44:45], 0, v[128:129]
	s_addc_u32 s61, s45, 0
	s_add_i32 s59, s62, s6
	global_load_lds_dwordx4 v[178:179], off
	v_lshl_add_u64 v[224:225], s[60:61], 0, v[168:169]
	s_mov_b32 m0, s59
	v_lshl_add_u64 v[234:235], s[46:47], 0, v[130:131]
	global_load_lds_dwordx4 v[224:225], off
	v_lshl_add_u64 v[224:225], s[60:61], 0, v[128:129]
	s_add_i32 m0, s59, 0x2000
	s_nop 0
	global_load_lds_dwordx4 v[224:225], off
	v_lshl_add_u64 v[224:225], s[46:47], 0, v[132:133]
	s_mov_b32 m0, s7
	s_nop 0
	global_load_lds_dwordx4 v[224:225], off
	s_mov_b32 m0, s34
	s_nop 0
	global_load_lds_dwordx4 v[234:235], off
	s_waitcnt vmcnt(8)
	s_waitcnt lgkmcnt(0)
	s_barrier
	s_setprio 1
	s_waitcnt lgkmcnt(0)
	v_mfma_f32_16x16x32_bf16 v[60:63], v[138:141], v[192:195], 0
	v_mfma_f32_16x16x32_bf16 v[56:59], v[150:153], v[192:195], 0
	v_mfma_f32_16x16x32_bf16 v[52:55], v[138:141], v[200:203], 0
	v_mfma_f32_16x16x32_bf16 v[44:47], v[150:153], v[200:203], 0
	v_mfma_f32_16x16x32_bf16 v[36:39], v[138:141], v[208:211], 0
	v_mfma_f32_16x16x32_bf16 v[28:31], v[150:153], v[208:211], 0
	v_mfma_f32_16x16x32_bf16 v[20:23], v[138:141], v[216:219], 0
	v_mfma_f32_16x16x32_bf16 v[12:15], v[150:153], v[216:219], 0
	v_mfma_f32_16x16x32_bf16 v[60:63], v[146:149], v[196:199], v[60:63]
	v_mfma_f32_16x16x32_bf16 v[56:59], v[154:157], v[196:199], v[56:59]
	v_mfma_f32_16x16x32_bf16 v[52:55], v[146:149], v[204:207], v[52:55]
	v_mfma_f32_16x16x32_bf16 v[44:47], v[154:157], v[204:207], v[44:47]
	v_mfma_f32_16x16x32_bf16 v[36:39], v[146:149], v[212:215], v[36:39]
	v_mfma_f32_16x16x32_bf16 v[28:31], v[154:157], v[212:215], v[28:31]
	v_mfma_f32_16x16x32_bf16 v[20:23], v[146:149], v[220:223], v[20:23]
	v_mfma_f32_16x16x32_bf16 v[12:15], v[154:157], v[220:223], v[12:15]
	s_setprio 0
	s_setprio 1
	v_mfma_f32_16x16x32_bf16 v[48:51], v[158:161], v[192:195], 0
	v_mfma_f32_16x16x32_bf16 v[40:43], v[170:173], v[192:195], 0
	v_mfma_f32_16x16x32_bf16 v[32:35], v[158:161], v[200:203], 0
	v_mfma_f32_16x16x32_bf16 v[24:27], v[170:173], v[200:203], 0
	v_mfma_f32_16x16x32_bf16 v[16:19], v[158:161], v[208:211], 0
	v_mfma_f32_16x16x32_bf16 v[8:11], v[170:173], v[208:211], 0
	v_mfma_f32_16x16x32_bf16 v[4:7], v[158:161], v[216:219], 0
	v_mfma_f32_16x16x32_bf16 v[0:3], v[170:173], v[216:219], 0
	v_mfma_f32_16x16x32_bf16 v[48:51], v[162:165], v[196:199], v[48:51]
	v_mfma_f32_16x16x32_bf16 v[40:43], v[188:191], v[196:199], v[40:43]
	v_mfma_f32_16x16x32_bf16 v[32:35], v[162:165], v[204:207], v[32:35]
	v_mfma_f32_16x16x32_bf16 v[24:27], v[188:191], v[204:207], v[24:27]
	s_add_i32 s59, 0, 0x18000
	v_mfma_f32_16x16x32_bf16 v[16:19], v[162:165], v[212:215], v[16:19]
	s_add_i32 s60, 0, 0x1c000
	v_mfma_f32_16x16x32_bf16 v[8:11], v[188:191], v[212:215], v[8:11]
	v_add_u32_e32 v240, s59, v143
	v_mfma_f32_16x16x32_bf16 v[4:7], v[162:165], v[220:223], v[4:7]
	v_add_u32_e32 v241, s60, v143
	v_mfma_f32_16x16x32_bf16 v[0:3], v[188:191], v[220:223], v[0:3]
	s_setprio 0
	s_barrier
	ds_read_b128 v[138:141], v240
	ds_read_b128 v[146:149], v240 offset:1024
	ds_read_b128 v[150:153], v240 offset:2048
	ds_read_b128 v[154:157], v240 offset:3072
	ds_read_b128 v[158:161], v241
	ds_read_b128 v[162:165], v241 offset:1024
	ds_read_b128 v[170:173], v241 offset:2048
	ds_read_b128 v[188:191], v241 offset:3072
	s_add_u32 s46, s46, 0x40000
	s_addc_u32 s47, s47, 0
	s_mov_b32 m0, s35
	v_lshl_add_u64 v[236:237], s[46:47], 0, v[132:133]
	ds_read_b128 v[192:195], v145 offset:32768
	ds_read_b128 v[196:199], v145 offset:33792
	ds_read_b128 v[200:203], v145 offset:34816
	ds_read_b128 v[204:207], v145 offset:35840
	ds_read_b128 v[208:211], v145 offset:36864
	ds_read_b128 v[212:215], v145 offset:37888
	ds_read_b128 v[216:219], v145 offset:38912
	ds_read_b128 v[220:223], v145 offset:39936
	global_load_lds_dwordx4 v[236:237], off
	v_lshl_add_u64 v[236:237], s[46:47], 0, v[130:131]
	s_mov_b32 m0, s48
	s_nop 0
	global_load_lds_dwordx4 v[236:237], off
	s_waitcnt vmcnt(8)
	s_waitcnt lgkmcnt(0)
	s_barrier
; #define PG8_STAGE(bufoff, gbase, voff) do { _Pragma("unroll") for (int _i = 0; _i < 2; ++_i) \
;         __builtin_amdgcn_global_load_lds((const unsigned*)((const char*)(gbase) + (voff)[_i]), (PG8_LAS unsigned*)(lds + (bufoff) + ldsw + _i * 8192), 16, 0, 0); } while (0)
; #define PG8_LDA(dst, b, h) do { _Pragma("unroll") for (int m = 0; m < 4; ++m) _Pragma("unroll") for (int k = 0; k < 2; ++k) dst[m][k] = *(const PG8_LAS bf16x8*)(lds + PG8_SA(b, h) + aoff + m * 2048 + k * 1024); } while (0)
; #define PG8_MMA(ai, bj, At, Bt) do { __builtin_amdgcn_s_setprio(1); _Pragma("unroll") for (int m = 0; m < 4; ++m) _Pragma("unroll") for (int n = 0; n < 2; ++n) _Pragma("unroll") for (int k = 0; k < 2; ++k) \
;         acc[ai][bj][m][n] = __builtin_amdgcn_mfma_f32_16x16x32_bf16(Bt[n][k], At[m][k], acc[ai][bj][m][n], 0, 0, 0); __builtin_amdgcn_s_setprio(0); } while (0)
; #define PG8_WAIT_V(n) asm volatile("s_waitcnt vmcnt(" #n ")" ::: "memory")
; #define PG8_WAIT_L(n) asm volatile("s_waitcnt lgkmcnt(" #n ")" ::: "memory")
; #define PG8_BAR __builtin_amdgcn_s_barrier()
; #define PG8_SCHED __builtin_amdgcn_sched_barrier(0)
; template <class Epi, class Sched, bool ALIGN_EPI = false, bool SP2 = false>
; __device__ __forceinline__ void gemm_phase(PG8_LAS unsigned char* lds, const Gemm g, const Sched& S, const Epi& E) {
;     ...
;         for (int t = 0; t < nt; t += 2) {
;             const bool last = (t == nt - 2);
;             const char* a1 = cA + (size_t)(t + 1) * kstepA;
;             const char* a2 = last ? nA : cA + (size_t)(t + 2) * kstepA; const char* b2 = last ? nB : cB + (size_t)(t + 2) * kstep;
;             const char* a3 = a2 + kstepA; const char* b3 = b2 + kstep;
;     ...
;             PG8_WAIT_V(8); PG8_WAIT_L(0); PG8_BAR; PG8_MMA(0, 0, At, B0); PG8_MMA(0, 1, At, B1); PG8_BAR; PG8_SCHED;
;             PG8_LDA(At, 1, 1); PG8_STAGE(PG8_SB(1, 0), b3, voffB); PG8_STAGE(PG8_SB(1, 1), b3 + hstep, voffB); PG8_STAGE(PG8_SA(1, 0), a3, voffA);
;             PG8_WAIT_V(8); PG8_WAIT_L(0); PG8_BAR; PG8_MMA(1, 0, At, B0); PG8_MMA(1, 1, At, B1); PG8_BAR; PG8_SCHED;
	s_setprio 1
	s_waitcnt lgkmcnt(0)
	v_mfma_f32_16x16x32_bf16 v[124:127], v[138:141], v[192:195], v[124:127]
	v_mfma_f32_16x16x32_bf16 v[120:123], v[150:153], v[192:195], v[120:123]
	v_mfma_f32_16x16x32_bf16 v[116:119], v[138:141], v[200:203], v[116:119]
	v_mfma_f32_16x16x32_bf16 v[108:111], v[150:153], v[200:203], v[108:111]
	v_mfma_f32_16x16x32_bf16 v[100:103], v[138:141], v[208:211], v[100:103]
	v_mfma_f32_16x16x32_bf16 v[92:95], v[150:153], v[208:211], v[92:95]
	v_mfma_f32_16x16x32_bf16 v[84:87], v[138:141], v[216:219], v[84:87]
	v_mfma_f32_16x16x32_bf16 v[76:79], v[150:153], v[216:219], v[76:79]
	v_mfma_f32_16x16x32_bf16 v[124:127], v[146:149], v[196:199], v[124:127]
	v_mfma_f32_16x16x32_bf16 v[120:123], v[154:157], v[196:199], v[120:123]
	v_mfma_f32_16x16x32_bf16 v[116:119], v[146:149], v[204:207], v[116:119]
	v_mfma_f32_16x16x32_bf16 v[108:111], v[154:157], v[204:207], v[108:111]
	v_mfma_f32_16x16x32_bf16 v[100:103], v[146:149], v[212:215], v[100:103]
	v_mfma_f32_16x16x32_bf16 v[92:95], v[154:157], v[212:215], v[92:95]
	v_mfma_f32_16x16x32_bf16 v[84:87], v[146:149], v[220:223], v[84:87]
	v_mfma_f32_16x16x32_bf16 v[76:79], v[154:157], v[220:223], v[76:79]
	s_setprio 0
	s_setprio 1
	v_mfma_f32_16x16x32_bf16 v[112:115], v[158:161], v[192:195], v[112:115]
	v_mfma_f32_16x16x32_bf16 v[104:107], v[170:173], v[192:195], v[104:107]
	v_mfma_f32_16x16x32_bf16 v[96:99], v[158:161], v[200:203], v[96:99]
	v_mfma_f32_16x16x32_bf16 v[88:91], v[170:173], v[200:203], v[88:91]
	v_mfma_f32_16x16x32_bf16 v[80:83], v[158:161], v[208:211], v[80:83]
	v_mfma_f32_16x16x32_bf16 v[72:75], v[170:173], v[208:211], v[72:75]
	v_mfma_f32_16x16x32_bf16 v[68:71], v[158:161], v[216:219], v[68:71]
	v_mfma_f32_16x16x32_bf16 v[64:67], v[170:173], v[216:219], v[64:67]
	v_mfma_f32_16x16x32_bf16 v[112:115], v[162:165], v[196:199], v[112:115]
	v_mfma_f32_16x16x32_bf16 v[104:107], v[188:191], v[196:199], v[104:107]
	v_mfma_f32_16x16x32_bf16 v[96:99], v[162:165], v[204:207], v[96:99]
	v_mfma_f32_16x16x32_bf16 v[88:91], v[188:191], v[204:207], v[88:91]
	v_mfma_f32_16x16x32_bf16 v[80:83], v[162:165], v[212:215], v[80:83]
	s_add_i32 s46, s59, s6
	v_mfma_f32_16x16x32_bf16 v[72:75], v[188:191], v[212:215], v[72:75]
	v_lshl_add_u64 v[166:167], v[166:167], 0, s[30:31]
	v_mfma_f32_16x16x32_bf16 v[68:71], v[162:165], v[220:223], v[68:71]
	s_mov_b32 m0, s46
	v_mfma_f32_16x16x32_bf16 v[64:67], v[188:191], v[220:223], v[64:67]
	s_setprio 0
	s_barrier
	ds_read_b128 v[192:195], v145 offset:49152
	ds_read_b128 v[196:199], v145 offset:50176
	ds_read_b128 v[200:203], v145 offset:51200
	ds_read_b128 v[204:207], v145 offset:52224
	ds_read_b128 v[208:211], v145 offset:53248
	ds_read_b128 v[212:215], v145 offset:54272
	ds_read_b128 v[216:219], v145 offset:55296
	ds_read_b128 v[220:223], v145 offset:56320
	global_load_lds_dwordx4 v[166:167], off
	s_add_i32 m0, s46, 0x2000
	s_add_u32 s44, s44, 0x40080
	v_lshl_add_u64 v[166:167], v[178:179], 0, s[30:31]
	s_addc_u32 s45, s45, 0
	s_add_i32 s46, s60, s6
	global_load_lds_dwordx4 v[166:167], off
	v_lshl_add_u64 v[166:167], s[44:45], 0, v[168:169]
	s_mov_b32 m0, s46
	s_nop 0
	global_load_lds_dwordx4 v[166:167], off
	v_lshl_add_u64 v[166:167], s[44:45], 0, v[128:129]
	s_add_i32 m0, s46, 0x2000
	s_nop 0
	global_load_lds_dwordx4 v[166:167], off
	v_lshl_add_u64 v[166:167], v[224:225], 0, s[30:31]
	s_mov_b32 m0, s49
	s_nop 0
	global_load_lds_dwordx4 v[166:167], off
	v_lshl_add_u64 v[166:167], v[234:235], 0, s[30:31]
	s_mov_b32 m0, s50
	s_nop 0
	global_load_lds_dwordx4 v[166:167], off
	s_waitcnt vmcnt(8)
	s_waitcnt lgkmcnt(0)
	s_barrier
	s_setprio 1
	s_waitcnt lgkmcnt(0)
	v_mfma_f32_16x16x32_bf16 v[60:63], v[138:141], v[192:195], v[60:63]
	v_mfma_f32_16x16x32_bf16 v[56:59], v[150:153], v[192:195], v[56:59]
	v_mfma_f32_16x16x32_bf16 v[52:55], v[138:141], v[200:203], v[52:55]
	v_mfma_f32_16x16x32_bf16 v[44:47], v[150:153], v[200:203], v[44:47]
	v_mfma_f32_16x16x32_bf16 v[36:39], v[138:141], v[208:211], v[36:39]
	v_mfma_f32_16x16x32_bf16 v[28:31], v[150:153], v[208:211], v[28:31]
	v_mfma_f32_16x16x32_bf16 v[20:23], v[138:141], v[216:219], v[20:23]
	v_mfma_f32_16x16x32_bf16 v[12:15], v[150:153], v[216:219], v[12:15]
	v_mfma_f32_16x16x32_bf16 v[60:63], v[146:149], v[196:199], v[60:63]
	v_mfma_f32_16x16x32_bf16 v[56:59], v[154:157], v[196:199], v[56:59]
	v_mfma_f32_16x16x32_bf16 v[52:55], v[146:149], v[204:207], v[52:55]
	v_mfma_f32_16x16x32_bf16 v[44:47], v[154:157], v[204:207], v[44:47]
	v_mfma_f32_16x16x32_bf16 v[36:39], v[146:149], v[212:215], v[36:39]
	v_mfma_f32_16x16x32_bf16 v[28:31], v[154:157], v[212:215], v[28:31]
	v_mfma_f32_16x16x32_bf16 v[20:23], v[146:149], v[220:223], v[20:23]
	v_mfma_f32_16x16x32_bf16 v[12:15], v[154:157], v[220:223], v[12:15]
	s_add_i32 s58, s58, 2
	s_setprio 0
	s_setprio 1
	v_mfma_f32_16x16x32_bf16 v[48:51], v[158:161], v[192:195], v[48:51]
	s_add_u32 s56, s56, 0x100
	v_mfma_f32_16x16x32_bf16 v[40:43], v[170:173], v[192:195], v[40:43]
	s_addc_u32 s57, s57, 0
	v_mfma_f32_16x16x32_bf16 v[32:35], v[158:161], v[200:203], v[32:35]
	s_add_u32 s42, s42, 0x100
	v_mfma_f32_16x16x32_bf16 v[24:27], v[170:173], v[200:203], v[24:27]
	s_addc_u32 s43, s43, 0
	v_mfma_f32_16x16x32_bf16 v[16:19], v[158:161], v[208:211], v[16:19]
	s_add_u32 s44, s42, 0xfffc0080
	v_mfma_f32_16x16x32_bf16 v[8:11], v[170:173], v[208:211], v[8:11]
	s_addc_u32 s45, s43, -1
	v_mfma_f32_16x16x32_bf16 v[4:7], v[158:161], v[216:219], v[4:7]
	s_add_i32 s59, 0, 0x10000
	v_mfma_f32_16x16x32_bf16 v[0:3], v[170:173], v[216:219], v[0:3]
	s_cmp_eq_u32 s58, 12
	v_mfma_f32_16x16x32_bf16 v[48:51], v[162:165], v[196:199], v[48:51]
	s_cselect_b32 s47, s27, s45
	v_mfma_f32_16x16x32_bf16 v[40:43], v[188:191], v[196:199], v[40:43]
	s_cselect_b32 s46, s54, s44
	v_mfma_f32_16x16x32_bf16 v[32:35], v[162:165], v[204:207], v[32:35]
	s_cselect_b32 s45, s25, s57
	v_mfma_f32_16x16x32_bf16 v[24:27], v[188:191], v[204:207], v[24:27]
	s_cselect_b32 s44, s55, s56
	v_mfma_f32_16x16x32_bf16 v[16:19], v[162:165], v[212:215], v[16:19]
	s_add_i32 s62, 0, 0x14000
	v_mfma_f32_16x16x32_bf16 v[8:11], v[188:191], v[212:215], v[8:11]
	v_add_u32_e32 v242, s59, v143
	v_mfma_f32_16x16x32_bf16 v[4:7], v[162:165], v[220:223], v[4:7]
	v_add_u32_e32 v166, s62, v143
	v_mfma_f32_16x16x32_bf16 v[0:3], v[188:191], v[220:223], v[0:3]
	s_setprio 0
	s_barrier

; #define PG8_STAGE(bufoff, gbase, voff) do { _Pragma("unroll") for (int _i = 0; _i < 2; ++_i) \
;         __builtin_amdgcn_global_load_lds((const unsigned*)((const char*)(gbase) + (voff)[_i]), (PG8_LAS unsigned*)(lds + (bufoff) + ldsw + _i * 8192), 16, 0, 0); } while (0)
; #define PG8_LDA(dst, b, h) do { _Pragma("unroll") for (int m = 0; m < 4; ++m) _Pragma("unroll") for (int k = 0; k < 2; ++k) dst[m][k] = *(const PG8_LAS bf16x8*)(lds + PG8_SA(b, h) + aoff + m * 2048 + k * 1024); } while (0)
; #define PG8_LDB(dst, b, h) do { _Pragma("unroll") for (int n = 0; n < 2; ++n) _Pragma("unroll") for (int k = 0; k < 2; ++k) dst[n][k] = *(const PG8_LAS bf16x8*)(lds + PG8_SB(b, h) + boff + n * 2048 + k * 1024); } while (0)
; #define PG8_BAR __builtin_amdgcn_s_barrier()
;     __host__ __device__ bool next(int i, Unit& u) const {
;         const long L = (long)i * G + c; if (L >= nwg) return false;
;         int wgid = (int)L; { const int q = nwg / NXCD, r = nwg % NXCD, xcd = wgid % NXCD, off = wgid / NXCD; wgid = (xcd < r ? xcd * (q + 1) : r * (q + 1) + (xcd - r) * q) + off; }
;         const int nig = WGM * nN, gid = wgid / nig, fm = gid * WGM, gsz = (nM - fm) < WGM ? (nM - fm) : WGM;
;         u.pm = fm + ((wgid % nig) % gsz); u.pn = (wgid % nig) / gsz; return true;
; template <class Epi, class Sched, bool ALIGN_EPI = false, bool SP2 = false>
; __device__ __forceinline__ void gemm_phase(PG8_LAS unsigned char* lds, const Gemm g, const Sched& S, const Epi& E) {
;     ...
;         const bool has_next = S.next(ui + 1, nxt);
;         const char* nA = has_next ? (const char*)g.A + (size_t)nxt.pm * tstepA : cA; const char* nB = has_next ? (const char*)g.Bt + (size_t)nxt.pn * tstep : cB;
;         for (int t = 0; t < nt; t += 2) {
;             const bool last = (t == nt - 2);
;             const char* a1 = cA + (size_t)(t + 1) * kstepA;
;             const char* a2 = last ? nA : cA + (size_t)(t + 2) * kstepA; const char* b2 = last ? nB : cB + (size_t)(t + 2) * kstep;
;             const char* a3 = a2 + kstepA; const char* b3 = b2 + kstep;
;             if (last && has_next) S.a_ready(nxt);
;             if constexpr (SP2) {
;             PG8_LDB(B0, 0, 0); PG8_LDB(B1, 0, 1); PG8_SCHED; PG8_LDA(At, 0, 0); PG8_STAGE(PG8_SA(1, 1), a1 + hstepA, voffA);
;             PG8_WAIT_V(8); PG8_WAIT_L(0); PG8_BAR; PG8_MMA(0, 0, At, B0); PG8_MMA(0, 1, At, B1); PG8_BAR; PG8_SCHED;
.LBB0_431:
	v_add_u32_e32 v244, 0x10000, v143
	v_add_u32_e32 v245, 0x14000, v143
	ds_read_b128 v[138:141], v244
	ds_read_b128 v[146:149], v244 offset:1024
	ds_read_b128 v[150:153], v244 offset:2048
	ds_read_b128 v[154:157], v244 offset:3072
	ds_read_b128 v[158:161], v245
	ds_read_b128 v[162:165], v245 offset:1024
	ds_read_b128 v[188:191], v245 offset:2048
	ds_read_b128 v[192:195], v245 offset:3072
	ds_read_b128 v[196:199], v145
	ds_read_b128 v[200:203], v145 offset:1024
	ds_read_b128 v[204:207], v145 offset:2048
	ds_read_b128 v[208:211], v145 offset:3072
	ds_read_b128 v[212:215], v145 offset:4096
	ds_read_b128 v[216:219], v145 offset:5120
	ds_read_b128 v[220:223], v145 offset:6144
	ds_read_b128 v[234:237], v145 offset:7168
	s_add_i32 s51, s51, 1
	s_mul_i32 s27, s51, s11
	s_mul_hi_u32 s36, s51, s10
	s_add_i32 s36, s36, s27
	s_mul_i32 s27, s51, s10
	s_add_u32 s42, s27, s93
	s_addc_u32 s43, s36, s9
	v_cmp_gt_i64_e32 vcc, s[42:43], v[176:177]
	v_cmp_lt_i64_e64 s[36:37], s[42:43], v[174:175]
	s_cbranch_vccnz .LBB0_433
	s_ashr_i32 s26, s42, 31
	s_lshr_b32 s26, s26, 29
	s_add_i32 s26, s42, s26
	s_ashr_i32 s27, s26, 3
	s_and_b32 s26, s26, -8
	s_sub_i32 s26, s42, s26
	s_cmp_lt_i32 s26, 0
	s_movk_i32 s40, 0x161
	s_cselect_b32 s40, s40, 0x160
	s_mul_i32 s26, s26, s40
	s_add_i32 s26, s26, s27
	s_mul_hi_i32 s27, s26, 0x2e8ba2e9
	s_lshr_b32 s40, s27, 31
	s_ashr_i32 s27, s27, 4
	s_add_i32 s27, s27, s40
	s_lshl_b32 s40, s27, 3
	s_sub_i32 s41, 0x100, s40
	s_min_i32 s41, s41, 8
	s_abs_i32 s42, s41
	v_cvt_f32_u32_e32 v0, s42
	s_sub_i32 s44, 0, s42
	s_mulk_i32 s27, 0x58
	s_sub_i32 s27, s26, s27
	v_rcp_iflag_f32_e32 v0, v0
	s_abs_i32 s26, s27
	s_xor_b32 s43, s27, s41
	s_ashr_i32 s43, s43, 31
	v_mul_f32_e32 v0, 0x4f7ffffe, v0
	v_cvt_u32_f32_e32 v0, v0
	s_nop 0
	v_readfirstlane_b32 s45, v0
	s_mul_i32 s44, s44, s45
	s_mul_hi_u32 s44, s45, s44
	s_add_i32 s45, s45, s44
	s_mul_hi_u32 s44, s26, s45
	s_mul_i32 s45, s44, s42
	s_sub_i32 s26, s26, s45
	s_add_i32 s46, s44, 1
	s_sub_i32 s45, s26, s42
	s_cmp_ge_u32 s26, s42
	s_cselect_b32 s44, s46, s44
	s_cselect_b32 s26, s45, s26
	s_add_i32 s45, s44, 1
	s_cmp_ge_u32 s26, s42
	s_cselect_b32 s26, s45, s44
	s_xor_b32 s26, s26, s43
	s_sub_i32 s26, s26, s43
	s_mul_i32 s41, s26, s41
	s_sub_i32 s27, s27, s41
	s_add_i32 s40, s40, s27
.LBB0_433:
	s_ashr_i32 s41, s40, 31
	s_lshl_b64 s[42:43], s[40:41], 19
	s_add_u32 s42, s20, s42
	s_addc_u32 s43, s21, s43
	s_and_b64 s[44:45], s[36:37], exec
	s_cselect_b32 s41, s43, s39
	s_cselect_b32 s54, s42, s38
	s_ashr_i32 s27, s26, 31
	s_lshl_b64 s[44:45], s[26:27], 19
	s_add_u32 s44, s3, s44
	s_addc_u32 s45, s6, s45
	s_and_b64 s[46:47], s[36:37], exec
	s_cselect_b32 s27, s45, s5
	s_cselect_b32 s55, s44, s4
	s_add_u32 s56, s4, 0x100
	s_addc_u32 s57, s5, 0
	s_add_u32 s4, s38, 0x40080
	s_addc_u32 s5, s39, 0
	s_mov_b32 s58, -2
	s_add_u32 s38, s4, 0xfffc0080
	s_addc_u32 s39, s5, -1
	s_add_i32 s59, 0, 0x10000
	s_cmp_eq_u32 s58, 12
	s_cselect_b32 s47, s41, s39
	s_cselect_b32 s46, s54, s38
	s_cselect_b32 s39, s27, s57
	s_cselect_b32 s38, s55, s56
	s_add_i32 s62, 0, 0x14000
	v_lshl_add_u64 v[166:167], s[4:5], 0, v[136:137]
	s_add_i32 m0, s2, 0xc000
	global_load_lds_dwordx4 v[166:167], off
	v_lshl_add_u64 v[166:167], s[4:5], 0, v[134:135]
	s_add_i32 m0, s2, 0xe000
	s_nop 0
	global_load_lds_dwordx4 v[166:167], off
	s_waitcnt vmcnt(8)
	s_waitcnt lgkmcnt(0)
	s_barrier
	s_setprio 1
	s_waitcnt lgkmcnt(0)
	v_mfma_f32_16x16x32_bf16 v[124:127], v[138:141], v[196:199], 0
	v_mfma_f32_16x16x32_bf16 v[120:123], v[150:153], v[196:199], 0
	v_mfma_f32_16x16x32_bf16 v[108:111], v[138:141], v[204:207], 0
	v_mfma_f32_16x16x32_bf16 v[104:107], v[150:153], v[204:207], 0
	v_mfma_f32_16x16x32_bf16 v[92:95], v[138:141], v[212:215], 0
	v_mfma_f32_16x16x32_bf16 v[88:91], v[150:153], v[212:215], 0
	v_mfma_f32_16x16x32_bf16 v[76:79], v[138:141], v[220:223], 0
	v_mfma_f32_16x16x32_bf16 v[72:75], v[150:153], v[220:223], 0
	v_mfma_f32_16x16x32_bf16 v[124:127], v[146:149], v[200:203], v[124:127]
	v_mfma_f32_16x16x32_bf16 v[120:123], v[154:157], v[200:203], v[120:123]
	v_mfma_f32_16x16x32_bf16 v[108:111], v[146:149], v[208:211], v[108:111]
	v_mfma_f32_16x16x32_bf16 v[104:107], v[154:157], v[208:211], v[104:107]
	v_mfma_f32_16x16x32_bf16 v[92:95], v[146:149], v[216:219], v[92:95]
	v_mfma_f32_16x16x32_bf16 v[88:91], v[154:157], v[216:219], v[88:91]
	v_mfma_f32_16x16x32_bf16 v[76:79], v[146:149], v[234:237], v[76:79]
	v_mfma_f32_16x16x32_bf16 v[72:75], v[154:157], v[234:237], v[72:75]
	s_setprio 0
	s_setprio 1
	v_mfma_f32_16x16x32_bf16 v[116:119], v[158:161], v[196:199], 0
	v_mfma_f32_16x16x32_bf16 v[112:115], v[188:191], v[196:199], 0
	v_mfma_f32_16x16x32_bf16 v[100:103], v[158:161], v[204:207], 0
	v_mfma_f32_16x16x32_bf16 v[96:99], v[188:191], v[204:207], 0
	v_mfma_f32_16x16x32_bf16 v[84:87], v[158:161], v[212:215], 0
	v_mfma_f32_16x16x32_bf16 v[80:83], v[188:191], v[212:215], 0
	v_mfma_f32_16x16x32_bf16 v[68:71], v[158:161], v[220:223], 0
	v_mfma_f32_16x16x32_bf16 v[64:67], v[188:191], v[220:223], 0
	v_mfma_f32_16x16x32_bf16 v[116:119], v[162:165], v[200:203], v[116:119]
	v_mfma_f32_16x16x32_bf16 v[112:115], v[192:195], v[200:203], v[112:115]
	v_mfma_f32_16x16x32_bf16 v[100:103], v[162:165], v[208:211], v[100:103]
	v_mfma_f32_16x16x32_bf16 v[96:99], v[192:195], v[208:211], v[96:99]
	v_mfma_f32_16x16x32_bf16 v[84:87], v[162:165], v[216:219], v[84:87]
	s_add_i32 s59, s59, s7
	v_mfma_f32_16x16x32_bf16 v[80:83], v[192:195], v[216:219], v[80:83]
	v_lshl_add_u64 v[166:167], s[38:39], 0, v[168:169]
	v_mfma_f32_16x16x32_bf16 v[68:71], v[162:165], v[234:237], v[68:71]
	s_mov_b32 m0, s59
	v_mfma_f32_16x16x32_bf16 v[64:67], v[192:195], v[234:237], v[64:67]
	s_setprio 0
	s_barrier
; #define PG8_STAGE(bufoff, gbase, voff) do { _Pragma("unroll") for (int _i = 0; _i < 2; ++_i) \
;         __builtin_amdgcn_global_load_lds((const unsigned*)((const char*)(gbase) + (voff)[_i]), (PG8_LAS unsigned*)(lds + (bufoff) + ldsw + _i * 8192), 16, 0, 0); } while (0)
; #define PG8_LDA(dst, b, h) do { _Pragma("unroll") for (int m = 0; m < 4; ++m) _Pragma("unroll") for (int k = 0; k < 2; ++k) dst[m][k] = *(const PG8_LAS bf16x8*)(lds + PG8_SA(b, h) + aoff + m * 2048 + k * 1024); } while (0)
; #define PG8_LDB(dst, b, h) do { _Pragma("unroll") for (int n = 0; n < 2; ++n) _Pragma("unroll") for (int k = 0; k < 2; ++k) dst[n][k] = *(const PG8_LAS bf16x8*)(lds + PG8_SB(b, h) + boff + n * 2048 + k * 1024); } while (0)
; #define PG8_MMA(ai, bj, At, Bt) do { __builtin_amdgcn_s_setprio(1); _Pragma("unroll") for (int m = 0; m < 4; ++m) _Pragma("unroll") for (int n = 0; n < 2; ++n) _Pragma("unroll") for (int k = 0; k < 2; ++k) \
;         acc[ai][bj][m][n] = __builtin_amdgcn_mfma_f32_16x16x32_bf16(Bt[n][k], At[m][k], acc[ai][bj][m][n], 0, 0, 0); __builtin_amdgcn_s_setprio(0); } while (0)
; #define PG8_WAIT_V(n) asm volatile("s_waitcnt vmcnt(" #n ")" ::: "memory")
; #define PG8_WAIT_L(n) asm volatile("s_waitcnt lgkmcnt(" #n ")" ::: "memory")
; #define PG8_BAR __builtin_amdgcn_s_barrier()
; #define PG8_SCHED __builtin_amdgcn_sched_barrier(0)
; template <class Epi, class Sched, bool ALIGN_EPI = false, bool SP2 = false>
; __device__ __forceinline__ void gemm_phase(PG8_LAS unsigned char* lds, const Gemm g, const Sched& S, const Epi& E) {
;     ...
;             PG8_LDA(At, 0, 1); PG8_STAGE(PG8_SB(0, 0), b2, voffB); PG8_STAGE(PG8_SB(0, 1), b2 + hstep, voffB); PG8_STAGE(PG8_SA(0, 0), a2, voffA);
;             PG8_WAIT_V(8); PG8_WAIT_L(0); PG8_BAR; PG8_MMA(1, 0, At, B0); PG8_MMA(1, 1, At, B1); PG8_BAR; PG8_SCHED;
;             PG8_LDB(B0, 1, 0); PG8_LDB(B1, 1, 1); PG8_SCHED; PG8_LDA(At, 1, 0); PG8_STAGE(PG8_SA(0, 1), a2 + hstepA, voffA);
	ds_read_b128 v[196:199], v145 offset:16384
	ds_read_b128 v[200:203], v145 offset:17408
	ds_read_b128 v[204:207], v145 offset:18432
	ds_read_b128 v[208:211], v145 offset:19456
	ds_read_b128 v[212:215], v145 offset:20480
	ds_read_b128 v[216:219], v145 offset:21504
	ds_read_b128 v[220:223], v145 offset:22528
	ds_read_b128 v[234:237], v145 offset:23552
	global_load_lds_dwordx4 v[166:167], off
	s_add_i32 m0, s59, 0x2000
	s_add_u32 s60, s38, 0x40000
	v_lshl_add_u64 v[170:171], s[38:39], 0, v[128:129]
	s_addc_u32 s61, s39, 0
	s_add_i32 s59, s62, s7
	global_load_lds_dwordx4 v[170:171], off
	v_lshl_add_u64 v[172:173], s[60:61], 0, v[168:169]
	s_mov_b32 m0, s59
	v_lshl_add_u64 v[224:225], s[46:47], 0, v[130:131]
	global_load_lds_dwordx4 v[172:173], off
	v_lshl_add_u64 v[172:173], s[60:61], 0, v[128:129]
	s_add_i32 m0, s59, 0x2000
	s_nop 0
	global_load_lds_dwordx4 v[172:173], off
	v_lshl_add_u64 v[172:173], s[46:47], 0, v[132:133]
	s_mov_b32 m0, s2
	s_nop 0
	global_load_lds_dwordx4 v[172:173], off
	s_mov_b32 m0, s34
	s_nop 0
	global_load_lds_dwordx4 v[224:225], off
	s_waitcnt vmcnt(8)
	s_waitcnt lgkmcnt(0)
	s_barrier
	s_setprio 1
	s_waitcnt lgkmcnt(0)
	v_mfma_f32_16x16x32_bf16 v[60:63], v[138:141], v[196:199], 0
	v_mfma_f32_16x16x32_bf16 v[56:59], v[150:153], v[196:199], 0
	v_mfma_f32_16x16x32_bf16 v[44:47], v[138:141], v[204:207], 0
	v_mfma_f32_16x16x32_bf16 v[40:43], v[150:153], v[204:207], 0
	v_mfma_f32_16x16x32_bf16 v[28:31], v[138:141], v[212:215], 0
	v_mfma_f32_16x16x32_bf16 v[24:27], v[150:153], v[212:215], 0
	v_mfma_f32_16x16x32_bf16 v[12:15], v[138:141], v[220:223], 0
	v_mfma_f32_16x16x32_bf16 v[8:11], v[150:153], v[220:223], 0
	v_mfma_f32_16x16x32_bf16 v[60:63], v[146:149], v[200:203], v[60:63]
	v_mfma_f32_16x16x32_bf16 v[56:59], v[154:157], v[200:203], v[56:59]
	v_mfma_f32_16x16x32_bf16 v[44:47], v[146:149], v[208:211], v[44:47]
	v_mfma_f32_16x16x32_bf16 v[40:43], v[154:157], v[208:211], v[40:43]
	v_mfma_f32_16x16x32_bf16 v[28:31], v[146:149], v[216:219], v[28:31]
	v_mfma_f32_16x16x32_bf16 v[24:27], v[154:157], v[216:219], v[24:27]
	v_mfma_f32_16x16x32_bf16 v[12:15], v[146:149], v[234:237], v[12:15]
	v_mfma_f32_16x16x32_bf16 v[8:11], v[154:157], v[234:237], v[8:11]
	s_setprio 0
	s_setprio 1
	v_mfma_f32_16x16x32_bf16 v[52:55], v[158:161], v[196:199], 0
	v_mfma_f32_16x16x32_bf16 v[48:51], v[188:191], v[196:199], 0
	v_mfma_f32_16x16x32_bf16 v[36:39], v[158:161], v[204:207], 0
	v_mfma_f32_16x16x32_bf16 v[32:35], v[188:191], v[204:207], 0
	v_mfma_f32_16x16x32_bf16 v[20:23], v[158:161], v[212:215], 0
	v_mfma_f32_16x16x32_bf16 v[16:19], v[188:191], v[212:215], 0
	v_mfma_f32_16x16x32_bf16 v[4:7], v[158:161], v[220:223], 0
	v_mfma_f32_16x16x32_bf16 v[0:3], v[188:191], v[220:223], 0
	v_mfma_f32_16x16x32_bf16 v[52:55], v[162:165], v[200:203], v[52:55]
	v_mfma_f32_16x16x32_bf16 v[48:51], v[192:195], v[200:203], v[48:51]
	v_mfma_f32_16x16x32_bf16 v[36:39], v[162:165], v[208:211], v[36:39]
	v_mfma_f32_16x16x32_bf16 v[32:35], v[192:195], v[208:211], v[32:35]
	s_add_i32 s59, 0, 0x18000
	v_mfma_f32_16x16x32_bf16 v[20:23], v[162:165], v[216:219], v[20:23]
	s_add_i32 s60, 0, 0x1c000
	v_mfma_f32_16x16x32_bf16 v[16:19], v[192:195], v[216:219], v[16:19]
	v_add_u32_e32 v240, s59, v143
	v_mfma_f32_16x16x32_bf16 v[4:7], v[162:165], v[234:237], v[4:7]
	v_add_u32_e32 v178, s60, v143
	v_mfma_f32_16x16x32_bf16 v[0:3], v[192:195], v[234:237], v[0:3]
	s_setprio 0
	s_barrier
	ds_read_b128 v[138:141], v240
	ds_read_b128 v[146:149], v240 offset:1024
	ds_read_b128 v[150:153], v240 offset:2048
	ds_read_b128 v[154:157], v240 offset:3072
	ds_read_b128 v[158:161], v178
	ds_read_b128 v[162:165], v178 offset:1024
	ds_read_b128 v[188:191], v178 offset:2048
	ds_read_b128 v[192:195], v178 offset:3072
	s_add_u32 s46, s46, 0x40000
	s_addc_u32 s47, s47, 0
	s_mov_b32 m0, s35
	v_lshl_add_u64 v[238:239], s[46:47], 0, v[132:133]
	ds_read_b128 v[196:199], v145 offset:32768
	ds_read_b128 v[200:203], v145 offset:33792
	ds_read_b128 v[204:207], v145 offset:34816
	ds_read_b128 v[208:211], v145 offset:35840
	ds_read_b128 v[212:215], v145 offset:36864
	ds_read_b128 v[216:219], v145 offset:37888
	ds_read_b128 v[220:223], v145 offset:38912
	ds_read_b128 v[234:237], v145 offset:39936
	global_load_lds_dwordx4 v[238:239], off
	v_lshl_add_u64 v[238:239], s[46:47], 0, v[130:131]
	s_mov_b32 m0, s48
	s_nop 0
	global_load_lds_dwordx4 v[238:239], off
	s_waitcnt vmcnt(8)
	s_waitcnt lgkmcnt(0)
	s_barrier
; #define PG8_STAGE(bufoff, gbase, voff) do { _Pragma("unroll") for (int _i = 0; _i < 2; ++_i) \
;         __builtin_amdgcn_global_load_lds((const unsigned*)((const char*)(gbase) + (voff)[_i]), (PG8_LAS unsigned*)(lds + (bufoff) + ldsw + _i * 8192), 16, 0, 0); } while (0)
; #define PG8_LDA(dst, b, h) do { _Pragma("unroll") for (int m = 0; m < 4; ++m) _Pragma("unroll") for (int k = 0; k < 2; ++k) dst[m][k] = *(const PG8_LAS bf16x8*)(lds + PG8_SA(b, h) + aoff + m * 2048 + k * 1024); } while (0)
; #define PG8_MMA(ai, bj, At, Bt) do { __builtin_amdgcn_s_setprio(1); _Pragma("unroll") for (int m = 0; m < 4; ++m) _Pragma("unroll") for (int n = 0; n < 2; ++n) _Pragma("unroll") for (int k = 0; k < 2; ++k) \
;         acc[ai][bj][m][n] = __builtin_amdgcn_mfma_f32_16x16x32_bf16(Bt[n][k], At[m][k], acc[ai][bj][m][n], 0, 0, 0); __builtin_amdgcn_s_setprio(0); } while (0)
; #define PG8_WAIT_V(n) asm volatile("s_waitcnt vmcnt(" #n ")" ::: "memory")
; #define PG8_WAIT_L(n) asm volatile("s_waitcnt lgkmcnt(" #n ")" ::: "memory")
; #define PG8_BAR __builtin_amdgcn_s_barrier()
; #define PG8_SCHED __builtin_amdgcn_sched_barrier(0)
; template <class Epi, class Sched, bool ALIGN_EPI = false, bool SP2 = false>
; __device__ __forceinline__ void gemm_phase(PG8_LAS unsigned char* lds, const Gemm g, const Sched& S, const Epi& E) {
;     ...
;         for (int t = 0; t < nt; t += 2) {
;             const bool last = (t == nt - 2);
;             const char* a1 = cA + (size_t)(t + 1) * kstepA;
;             const char* a2 = last ? nA : cA + (size_t)(t + 2) * kstepA; const char* b2 = last ? nB : cB + (size_t)(t + 2) * kstep;
;             const char* a3 = a2 + kstepA; const char* b3 = b2 + kstep;
;     ...
;             PG8_WAIT_V(8); PG8_WAIT_L(0); PG8_BAR; PG8_MMA(0, 0, At, B0); PG8_MMA(0, 1, At, B1); PG8_BAR; PG8_SCHED;
;             PG8_LDA(At, 1, 1); PG8_STAGE(PG8_SB(1, 0), b3, voffB); PG8_STAGE(PG8_SB(1, 1), b3 + hstep, voffB); PG8_STAGE(PG8_SA(1, 0), a3, voffA);
;             PG8_WAIT_V(8); PG8_WAIT_L(0); PG8_BAR; PG8_MMA(1, 0, At, B0); PG8_MMA(1, 1, At, B1); PG8_BAR; PG8_SCHED;
	s_setprio 1
	s_waitcnt lgkmcnt(0)
	v_mfma_f32_16x16x32_bf16 v[124:127], v[138:141], v[196:199], v[124:127]
	v_mfma_f32_16x16x32_bf16 v[120:123], v[150:153], v[196:199], v[120:123]
	v_mfma_f32_16x16x32_bf16 v[108:111], v[138:141], v[204:207], v[108:111]
	v_mfma_f32_16x16x32_bf16 v[104:107], v[150:153], v[204:207], v[104:107]
	v_mfma_f32_16x16x32_bf16 v[92:95], v[138:141], v[212:215], v[92:95]
	v_mfma_f32_16x16x32_bf16 v[88:91], v[150:153], v[212:215], v[88:91]
	v_mfma_f32_16x16x32_bf16 v[76:79], v[138:141], v[220:223], v[76:79]
	v_mfma_f32_16x16x32_bf16 v[72:75], v[150:153], v[220:223], v[72:75]
	v_mfma_f32_16x16x32_bf16 v[124:127], v[146:149], v[200:203], v[124:127]
	v_mfma_f32_16x16x32_bf16 v[120:123], v[154:157], v[200:203], v[120:123]
	v_mfma_f32_16x16x32_bf16 v[108:111], v[146:149], v[208:211], v[108:111]
	v_mfma_f32_16x16x32_bf16 v[104:107], v[154:157], v[208:211], v[104:107]
	v_mfma_f32_16x16x32_bf16 v[92:95], v[146:149], v[216:219], v[92:95]
	v_mfma_f32_16x16x32_bf16 v[88:91], v[154:157], v[216:219], v[88:91]
	v_mfma_f32_16x16x32_bf16 v[76:79], v[146:149], v[234:237], v[76:79]
	v_mfma_f32_16x16x32_bf16 v[72:75], v[154:157], v[234:237], v[72:75]
	s_setprio 0
	s_setprio 1
	v_mfma_f32_16x16x32_bf16 v[116:119], v[158:161], v[196:199], v[116:119]
	v_mfma_f32_16x16x32_bf16 v[112:115], v[188:191], v[196:199], v[112:115]
	v_mfma_f32_16x16x32_bf16 v[100:103], v[158:161], v[204:207], v[100:103]
	v_mfma_f32_16x16x32_bf16 v[96:99], v[188:191], v[204:207], v[96:99]
	v_mfma_f32_16x16x32_bf16 v[84:87], v[158:161], v[212:215], v[84:87]
	v_mfma_f32_16x16x32_bf16 v[80:83], v[188:191], v[212:215], v[80:83]
	v_mfma_f32_16x16x32_bf16 v[68:71], v[158:161], v[220:223], v[68:71]
	v_mfma_f32_16x16x32_bf16 v[64:67], v[188:191], v[220:223], v[64:67]
	v_mfma_f32_16x16x32_bf16 v[116:119], v[162:165], v[200:203], v[116:119]
	v_mfma_f32_16x16x32_bf16 v[112:115], v[192:195], v[200:203], v[112:115]
	v_mfma_f32_16x16x32_bf16 v[100:103], v[162:165], v[208:211], v[100:103]
	v_mfma_f32_16x16x32_bf16 v[96:99], v[192:195], v[208:211], v[96:99]
	v_mfma_f32_16x16x32_bf16 v[84:87], v[162:165], v[216:219], v[84:87]
	s_add_i32 s46, s59, s7
	v_mfma_f32_16x16x32_bf16 v[80:83], v[192:195], v[216:219], v[80:83]
	v_lshl_add_u64 v[166:167], v[166:167], 0, s[30:31]
	v_mfma_f32_16x16x32_bf16 v[68:71], v[162:165], v[234:237], v[68:71]
	s_mov_b32 m0, s46
	v_mfma_f32_16x16x32_bf16 v[64:67], v[192:195], v[234:237], v[64:67]
	s_setprio 0
	s_barrier
	ds_read_b128 v[196:199], v145 offset:49152
	ds_read_b128 v[200:203], v145 offset:50176
	ds_read_b128 v[204:207], v145 offset:51200
	ds_read_b128 v[208:211], v145 offset:52224
	ds_read_b128 v[212:215], v145 offset:53248
	ds_read_b128 v[216:219], v145 offset:54272
	ds_read_b128 v[220:223], v145 offset:55296
	ds_read_b128 v[234:237], v145 offset:56320
	global_load_lds_dwordx4 v[166:167], off
	s_add_i32 m0, s46, 0x2000
	s_add_u32 s38, s38, 0x40080
	v_lshl_add_u64 v[166:167], v[170:171], 0, s[30:31]
	s_addc_u32 s39, s39, 0
	s_add_i32 s46, s60, s7
	global_load_lds_dwordx4 v[166:167], off
	v_lshl_add_u64 v[166:167], s[38:39], 0, v[168:169]
	s_mov_b32 m0, s46
	s_nop 0
	global_load_lds_dwordx4 v[166:167], off
	v_lshl_add_u64 v[166:167], s[38:39], 0, v[128:129]
	s_add_i32 m0, s46, 0x2000
	s_nop 0
	global_load_lds_dwordx4 v[166:167], off
	v_lshl_add_u64 v[166:167], v[172:173], 0, s[30:31]
	s_mov_b32 m0, s49
	s_nop 0
	global_load_lds_dwordx4 v[166:167], off
	v_lshl_add_u64 v[166:167], v[224:225], 0, s[30:31]
	s_mov_b32 m0, s50
	s_nop 0
	global_load_lds_dwordx4 v[166:167], off
	s_waitcnt vmcnt(8)
	s_waitcnt lgkmcnt(0)
	s_barrier
	s_setprio 1
	s_waitcnt lgkmcnt(0)
	v_mfma_f32_16x16x32_bf16 v[60:63], v[138:141], v[196:199], v[60:63]
	v_mfma_f32_16x16x32_bf16 v[56:59], v[150:153], v[196:199], v[56:59]
	v_mfma_f32_16x16x32_bf16 v[44:47], v[138:141], v[204:207], v[44:47]
	v_mfma_f32_16x16x32_bf16 v[40:43], v[150:153], v[204:207], v[40:43]
	v_mfma_f32_16x16x32_bf16 v[28:31], v[138:141], v[212:215], v[28:31]
	v_mfma_f32_16x16x32_bf16 v[24:27], v[150:153], v[212:215], v[24:27]
	v_mfma_f32_16x16x32_bf16 v[12:15], v[138:141], v[220:223], v[12:15]
	v_mfma_f32_16x16x32_bf16 v[8:11], v[150:153], v[220:223], v[8:11]
	v_mfma_f32_16x16x32_bf16 v[60:63], v[146:149], v[200:203], v[60:63]
	v_mfma_f32_16x16x32_bf16 v[56:59], v[154:157], v[200:203], v[56:59]
	v_mfma_f32_16x16x32_bf16 v[44:47], v[146:149], v[208:211], v[44:47]
	v_mfma_f32_16x16x32_bf16 v[40:43], v[154:157], v[208:211], v[40:43]
	v_mfma_f32_16x16x32_bf16 v[28:31], v[146:149], v[216:219], v[28:31]
	v_mfma_f32_16x16x32_bf16 v[24:27], v[154:157], v[216:219], v[24:27]
	v_mfma_f32_16x16x32_bf16 v[12:15], v[146:149], v[234:237], v[12:15]
	v_mfma_f32_16x16x32_bf16 v[8:11], v[154:157], v[234:237], v[8:11]
	s_add_i32 s58, s58, 2
	s_setprio 0
	s_setprio 1
	v_mfma_f32_16x16x32_bf16 v[52:55], v[158:161], v[196:199], v[52:55]
	s_add_u32 s56, s56, 0x100
	v_mfma_f32_16x16x32_bf16 v[48:51], v[188:191], v[196:199], v[48:51]
	s_addc_u32 s57, s57, 0
	v_mfma_f32_16x16x32_bf16 v[36:39], v[158:161], v[204:207], v[36:39]
	s_add_u32 s4, s4, 0x100
	v_mfma_f32_16x16x32_bf16 v[32:35], v[188:191], v[204:207], v[32:35]
	s_addc_u32 s5, s5, 0
	v_mfma_f32_16x16x32_bf16 v[20:23], v[158:161], v[212:215], v[20:23]
	s_add_u32 s38, s4, 0xfffc0080
	v_mfma_f32_16x16x32_bf16 v[16:19], v[188:191], v[212:215], v[16:19]
	s_addc_u32 s39, s5, -1
	v_mfma_f32_16x16x32_bf16 v[4:7], v[158:161], v[220:223], v[4:7]
	s_add_i32 s59, 0, 0x10000
	v_mfma_f32_16x16x32_bf16 v[0:3], v[188:191], v[220:223], v[0:3]
	s_cmp_eq_u32 s58, 12
	v_mfma_f32_16x16x32_bf16 v[52:55], v[162:165], v[200:203], v[52:55]
	s_cselect_b32 s47, s41, s39
	v_mfma_f32_16x16x32_bf16 v[48:51], v[192:195], v[200:203], v[48:51]
	s_cselect_b32 s46, s54, s38
	v_mfma_f32_16x16x32_bf16 v[36:39], v[162:165], v[208:211], v[36:39]
	s_cselect_b32 s39, s27, s57
	v_mfma_f32_16x16x32_bf16 v[32:35], v[192:195], v[208:211], v[32:35]
	s_cselect_b32 s38, s55, s56
	v_mfma_f32_16x16x32_bf16 v[20:23], v[162:165], v[216:219], v[20:23]
	s_add_i32 s62, 0, 0x14000
	v_mfma_f32_16x16x32_bf16 v[16:19], v[192:195], v[216:219], v[16:19]
	v_add_u32_e32 v241, s59, v143
	v_mfma_f32_16x16x32_bf16 v[4:7], v[162:165], v[234:237], v[4:7]
	v_add_u32_e32 v166, s62, v143
	v_mfma_f32_16x16x32_bf16 v[0:3], v[192:195], v[234:237], v[0:3]
	s_setprio 0
	s_barrier

; #define PG8_STAGE(bufoff, gbase, voff) do { _Pragma("unroll") for (int _i = 0; _i < 2; ++_i) \
;         __builtin_amdgcn_global_load_lds((const unsigned*)((const char*)(gbase) + (voff)[_i]), (PG8_LAS unsigned*)(lds + (bufoff) + ldsw + _i * 8192), 16, 0, 0); } while (0)
; #define PG8_LDA(dst, b, h) do { _Pragma("unroll") for (int m = 0; m < 4; ++m) _Pragma("unroll") for (int k = 0; k < 2; ++k) dst[m][k] = *(const PG8_LAS bf16x8*)(lds + PG8_SA(b, h) + aoff + m * 2048 + k * 1024); } while (0)
; #define PG8_LDB(dst, b, h) do { _Pragma("unroll") for (int n = 0; n < 2; ++n) _Pragma("unroll") for (int k = 0; k < 2; ++k) dst[n][k] = *(const PG8_LAS bf16x8*)(lds + PG8_SB(b, h) + boff + n * 2048 + k * 1024); } while (0)
; #define PG8_SCHED __builtin_amdgcn_sched_barrier(0)
;     __host__ __device__ bool next(int i, Unit& u) const {
;         const long L = (long)i * G + c; if (L >= nwg) return false;
;         int wgid = (int)L; { const int q = nwg / NXCD, r = nwg % NXCD, xcd = wgid % NXCD, off = wgid / NXCD; wgid = (xcd < r ? xcd * (q + 1) : r * (q + 1) + (xcd - r) * q) + off; }
; template <class Epi, class Sched, bool ALIGN_EPI = false, bool SP2 = false>
; __device__ __forceinline__ void gemm_phase(PG8_LAS unsigned char* lds, const Gemm g, const Sched& S, const Epi& E) {
;     ...
;         const bool has_next = S.next(ui + 1, nxt);
;         const char* nA = has_next ? (const char*)g.A + (size_t)nxt.pm * tstepA : cA; const char* nB = has_next ? (const char*)g.Bt + (size_t)nxt.pn * tstep : cB;
;         for (int t = 0; t < nt; t += 2) {
;             const bool last = (t == nt - 2);
;             const char* a1 = cA + (size_t)(t + 1) * kstepA;
;             const char* a2 = last ? nA : cA + (size_t)(t + 2) * kstepA; const char* b2 = last ? nB : cB + (size_t)(t + 2) * kstep;
;             const char* a3 = a2 + kstepA; const char* b3 = b2 + kstep;
;             if (last && has_next) S.a_ready(nxt);
;             if constexpr (SP2) {
;             PG8_LDB(B0, 0, 0); PG8_LDB(B1, 0, 1); PG8_SCHED; PG8_LDA(At, 0, 0); PG8_STAGE(PG8_SA(1, 1), a1 + hstepA, voffA);
.LBB0_726:
	v_add_u32_e32 v244, 0x10000, v224
	v_add_u32_e32 v245, 0x14000, v224
	ds_read_b128 v[128:131], v244
	ds_read_b128 v[132:135], v244 offset:1024
	ds_read_b128 v[136:139], v244 offset:2048
	ds_read_b128 v[140:143], v244 offset:3072
	ds_read_b128 v[144:147], v245
	ds_read_b128 v[148:151], v245 offset:1024
	ds_read_b128 v[152:155], v245 offset:2048
	ds_read_b128 v[156:159], v245 offset:3072
	ds_read_b128 v[160:163], v225
	ds_read_b128 v[164:167], v225 offset:1024
	ds_read_b128 v[170:173], v225 offset:2048
	ds_read_b128 v[198:201], v225 offset:3072
	ds_read_b128 v[202:205], v225 offset:4096
	ds_read_b128 v[206:209], v225 offset:5120
	ds_read_b128 v[210:213], v225 offset:6144
	ds_read_b128 v[214:217], v225 offset:7168
	s_add_i32 s87, s87, 1
	s_mul_i32 s5, s87, s11
	s_mul_hi_u32 s6, s87, s10
	s_add_i32 s6, s6, s5
	s_mul_i32 s5, s87, s10
	s_add_u32 s54, s5, s93
	s_addc_u32 s55, s6, s9
	v_cmp_gt_i64_e32 vcc, s[54:55], v[182:183]
	v_cmp_lt_i64_e64 s[38:39], s[54:55], v[180:181]
	s_cbranch_vccnz .LBB0_732
	s_ashr_i32 s5, s54, 31
	s_lshr_b32 s5, s5, 29
	s_add_i32 s5, s54, s5
	s_and_b32 s6, s5, -8
	s_sub_i32 s6, s54, s6
	s_cmp_gt_i32 s6, -1
	s_mov_b64 s[50:51], -1
	s_cbranch_scc0 .LBB0_729
	s_lshl_b32 s7, s6, 7
	s_mov_b64 s[50:51], 0

; #define PG8_STAGE(bufoff, gbase, voff) do { _Pragma("unroll") for (int _i = 0; _i < 2; ++_i) \
;         __builtin_amdgcn_global_load_lds((const unsigned*)((const char*)(gbase) + (voff)[_i]), (PG8_LAS unsigned*)(lds + (bufoff) + ldsw + _i * 8192), 16, 0, 0); } while (0)
; #define PG8_LDA(dst, b, h) do { _Pragma("unroll") for (int m = 0; m < 4; ++m) _Pragma("unroll") for (int k = 0; k < 2; ++k) dst[m][k] = *(const PG8_LAS bf16x8*)(lds + PG8_SA(b, h) + aoff + m * 2048 + k * 1024); } while (0)
; #define PG8_LDB(dst, b, h) do { _Pragma("unroll") for (int n = 0; n < 2; ++n) _Pragma("unroll") for (int k = 0; k < 2; ++k) dst[n][k] = *(const PG8_LAS bf16x8*)(lds + PG8_SB(b, h) + boff + n * 2048 + k * 1024); } while (0)
; #define PG8_MMA(ai, bj, At, Bt) do { __builtin_amdgcn_s_setprio(1); _Pragma("unroll") for (int m = 0; m < 4; ++m) _Pragma("unroll") for (int n = 0; n < 2; ++n) _Pragma("unroll") for (int k = 0; k < 2; ++k) \
;         acc[ai][bj][m][n] = __builtin_amdgcn_mfma_f32_16x16x32_bf16(Bt[n][k], At[m][k], acc[ai][bj][m][n], 0, 0, 0); __builtin_amdgcn_s_setprio(0); } while (0)
; #define PG8_WAIT_V(n) asm volatile("s_waitcnt vmcnt(" #n ")" ::: "memory")
; template <class Epi, class Sched, bool ALIGN_EPI = false, bool SP2 = false>
; __device__ __forceinline__ void gemm_phase(PG8_LAS unsigned char* lds, const Gemm g, const Sched& S, const Epi& E) {
;     ...
;         const char* nA = has_next ? (const char*)g.A + (size_t)nxt.pm * tstepA : cA; const char* nB = has_next ? (const char*)g.Bt + (size_t)nxt.pn * tstep : cB;
;         for (int t = 0; t < nt; t += 2) {
;             const bool last = (t == nt - 2);
;             const char* a1 = cA + (size_t)(t + 1) * kstepA;
;             const char* a2 = last ? nA : cA + (size_t)(t + 2) * kstepA; const char* b2 = last ? nB : cB + (size_t)(t + 2) * kstep;
;             const char* a3 = a2 + kstepA; const char* b3 = b2 + kstep;
;             if (last && has_next) S.a_ready(nxt);
;             if constexpr (SP2) {
;             PG8_LDB(B0, 0, 0); PG8_LDB(B1, 0, 1); PG8_SCHED; PG8_LDA(At, 0, 0); PG8_STAGE(PG8_SA(1, 1), a1 + hstepA, voffA);
;             PG8_WAIT_V(8); PG8_WAIT_L(0); PG8_BAR; PG8_MMA(0, 0, At, B0); PG8_MMA(0, 1, At, B1); PG8_BAR; PG8_SCHED;
;             PG8_LDA(At, 0, 1); PG8_STAGE(PG8_SB(0, 0), b2, voffB); PG8_STAGE(PG8_SB(0, 1), b2 + hstep, voffB); PG8_STAGE(PG8_SA(0, 0), a2, voffA);
.LBB0_732:
	s_ashr_i32 s53, s52, 31
	s_lshl_b64 s[6:7], s[52:53], 19
	s_add_u32 s54, s78, s6
	s_addc_u32 s55, s79, s7
	s_and_b64 s[6:7], s[38:39], exec
	s_cselect_b32 s5, s55, s37
	s_cselect_b32 s6, s54, s36
	s_ashr_i32 s51, s50, 31
	s_lshl_b64 s[56:57], s[50:51], 19
	s_add_u32 s56, s2, s56
	s_addc_u32 s57, s3, s57
	s_and_b64 s[60:61], s[38:39], exec
	s_cselect_b32 s7, s57, s41
	s_cselect_b32 s51, s56, s40
	s_add_u32 s53, s40, 0x100
	s_addc_u32 s64, s41, 0
	s_add_u32 s40, s36, 0x40080
	s_addc_u32 s41, s37, 0
	s_mov_b32 s65, -2
	s_add_u32 s58, s40, 0xfffc0080
	s_addc_u32 s59, s41, -1
	s_add_i32 s74, 0, 0x10000
	s_cmp_eq_u32 s65, 12
	s_cselect_b32 s61, s5, s59
	s_cselect_b32 s60, s6, s58
	s_cselect_b32 s59, s7, s64
	s_cselect_b32 s58, s51, s53
	s_add_i32 s91, 0, 0x14000
	v_lshl_add_u64 v[178:179], s[40:41], 0, v[196:197]
	s_add_i32 m0, s35, 0xc000
	global_load_lds_dwordx4 v[178:179], off
	v_lshl_add_u64 v[178:179], s[40:41], 0, v[194:195]
	s_add_i32 m0, s35, 0xe000
	s_nop 0
	global_load_lds_dwordx4 v[178:179], off
	s_waitcnt vmcnt(8)
	s_waitcnt lgkmcnt(0)
	s_barrier
	s_setprio 1
	s_waitcnt lgkmcnt(0)
	v_mfma_f32_16x16x32_bf16 v[124:127], v[128:131], v[160:163], 0
	v_mfma_f32_16x16x32_bf16 v[120:123], v[136:139], v[160:163], 0
	v_mfma_f32_16x16x32_bf16 v[108:111], v[128:131], v[170:173], 0
	v_mfma_f32_16x16x32_bf16 v[104:107], v[136:139], v[170:173], 0
	v_mfma_f32_16x16x32_bf16 v[92:95], v[128:131], v[202:205], 0
	v_mfma_f32_16x16x32_bf16 v[88:91], v[136:139], v[202:205], 0
	v_mfma_f32_16x16x32_bf16 v[76:79], v[128:131], v[210:213], 0
	v_mfma_f32_16x16x32_bf16 v[72:75], v[136:139], v[210:213], 0
	v_mfma_f32_16x16x32_bf16 v[124:127], v[132:135], v[164:167], v[124:127]
	v_mfma_f32_16x16x32_bf16 v[120:123], v[140:143], v[164:167], v[120:123]
	v_mfma_f32_16x16x32_bf16 v[108:111], v[132:135], v[198:201], v[108:111]
	v_mfma_f32_16x16x32_bf16 v[104:107], v[140:143], v[198:201], v[104:107]
	v_mfma_f32_16x16x32_bf16 v[92:95], v[132:135], v[206:209], v[92:95]
	v_mfma_f32_16x16x32_bf16 v[88:91], v[140:143], v[206:209], v[88:91]
	v_mfma_f32_16x16x32_bf16 v[76:79], v[132:135], v[214:217], v[76:79]
	v_mfma_f32_16x16x32_bf16 v[72:75], v[140:143], v[214:217], v[72:75]
	s_setprio 0
	s_setprio 1
	v_mfma_f32_16x16x32_bf16 v[116:119], v[144:147], v[160:163], 0
	v_mfma_f32_16x16x32_bf16 v[112:115], v[152:155], v[160:163], 0
	v_mfma_f32_16x16x32_bf16 v[100:103], v[144:147], v[170:173], 0
	v_mfma_f32_16x16x32_bf16 v[96:99], v[152:155], v[170:173], 0
	v_mfma_f32_16x16x32_bf16 v[84:87], v[144:147], v[202:205], 0
	v_mfma_f32_16x16x32_bf16 v[80:83], v[152:155], v[202:205], 0
	v_mfma_f32_16x16x32_bf16 v[68:71], v[144:147], v[210:213], 0
	v_mfma_f32_16x16x32_bf16 v[64:67], v[152:155], v[210:213], 0
	v_mfma_f32_16x16x32_bf16 v[116:119], v[148:151], v[164:167], v[116:119]
	v_mfma_f32_16x16x32_bf16 v[112:115], v[156:159], v[164:167], v[112:115]
	v_mfma_f32_16x16x32_bf16 v[100:103], v[148:151], v[198:201], v[100:103]
	v_mfma_f32_16x16x32_bf16 v[96:99], v[156:159], v[198:201], v[96:99]
	v_mfma_f32_16x16x32_bf16 v[84:87], v[148:151], v[206:209], v[84:87]
	s_add_i32 s74, s74, s34
	v_mfma_f32_16x16x32_bf16 v[80:83], v[156:159], v[206:209], v[80:83]
	v_lshl_add_u64 v[178:179], s[58:59], 0, v[168:169]
	v_mfma_f32_16x16x32_bf16 v[68:71], v[148:151], v[214:217], v[68:71]
	s_mov_b32 m0, s74
	v_mfma_f32_16x16x32_bf16 v[64:67], v[156:159], v[214:217], v[64:67]
	s_setprio 0
	s_barrier
	ds_read_b128 v[160:163], v225 offset:16384
	ds_read_b128 v[164:167], v225 offset:17408
	ds_read_b128 v[170:173], v225 offset:18432
	ds_read_b128 v[198:201], v225 offset:19456
	ds_read_b128 v[202:205], v225 offset:20480
	ds_read_b128 v[206:209], v225 offset:21504
	ds_read_b128 v[210:213], v225 offset:22528
	ds_read_b128 v[214:217], v225 offset:23552
	global_load_lds_dwordx4 v[178:179], off
	s_add_i32 m0, s74, 0x2000
	s_add_u32 s74, s58, 0x40000
	v_lshl_add_u64 v[218:219], s[58:59], 0, v[188:189]
	s_addc_u32 s75, s59, 0
	s_add_i32 s91, s91, s34
	global_load_lds_dwordx4 v[218:219], off
	v_lshl_add_u64 v[220:221], s[74:75], 0, v[168:169]
	s_mov_b32 m0, s91
	v_lshl_add_u64 v[234:235], s[60:61], 0, v[190:191]
	global_load_lds_dwordx4 v[220:221], off
	v_lshl_add_u64 v[220:221], s[74:75], 0, v[188:189]
	s_add_i32 m0, s91, 0x2000
	s_nop 0
	global_load_lds_dwordx4 v[220:221], off
	v_lshl_add_u64 v[220:221], s[60:61], 0, v[192:193]
	s_mov_b32 m0, s35
	s_nop 0
	global_load_lds_dwordx4 v[220:221], off
	s_mov_b32 m0, s69
	s_nop 0
	global_load_lds_dwordx4 v[234:235], off
	s_waitcnt vmcnt(8)
	s_waitcnt lgkmcnt(0)
	s_barrier
; #define PG8_STAGE(bufoff, gbase, voff) do { _Pragma("unroll") for (int _i = 0; _i < 2; ++_i) \
;         __builtin_amdgcn_global_load_lds((const unsigned*)((const char*)(gbase) + (voff)[_i]), (PG8_LAS unsigned*)(lds + (bufoff) + ldsw + _i * 8192), 16, 0, 0); } while (0)
; #define PG8_LDA(dst, b, h) do { _Pragma("unroll") for (int m = 0; m < 4; ++m) _Pragma("unroll") for (int k = 0; k < 2; ++k) dst[m][k] = *(const PG8_LAS bf16x8*)(lds + PG8_SA(b, h) + aoff + m * 2048 + k * 1024); } while (0)
; #define PG8_LDB(dst, b, h) do { _Pragma("unroll") for (int n = 0; n < 2; ++n) _Pragma("unroll") for (int k = 0; k < 2; ++k) dst[n][k] = *(const PG8_LAS bf16x8*)(lds + PG8_SB(b, h) + boff + n * 2048 + k * 1024); } while (0)
; #define PG8_MMA(ai, bj, At, Bt) do { __builtin_amdgcn_s_setprio(1); _Pragma("unroll") for (int m = 0; m < 4; ++m) _Pragma("unroll") for (int n = 0; n < 2; ++n) _Pragma("unroll") for (int k = 0; k < 2; ++k) \
;         acc[ai][bj][m][n] = __builtin_amdgcn_mfma_f32_16x16x32_bf16(Bt[n][k], At[m][k], acc[ai][bj][m][n], 0, 0, 0); __builtin_amdgcn_s_setprio(0); } while (0)
; #define PG8_WAIT_V(n) asm volatile("s_waitcnt vmcnt(" #n ")" ::: "memory")
; #define PG8_WAIT_L(n) asm volatile("s_waitcnt lgkmcnt(" #n ")" ::: "memory")
; #define PG8_BAR __builtin_amdgcn_s_barrier()
; #define PG8_SCHED __builtin_amdgcn_sched_barrier(0)
; template <class Epi, class Sched, bool ALIGN_EPI = false, bool SP2 = false>
; __device__ __forceinline__ void gemm_phase(PG8_LAS unsigned char* lds, const Gemm g, const Sched& S, const Epi& E) {
;     ...
;             PG8_WAIT_V(8); PG8_WAIT_L(0); PG8_BAR; PG8_MMA(1, 0, At, B0); PG8_MMA(1, 1, At, B1); PG8_BAR; PG8_SCHED;
;             PG8_LDB(B0, 1, 0); PG8_LDB(B1, 1, 1); PG8_SCHED; PG8_LDA(At, 1, 0); PG8_STAGE(PG8_SA(0, 1), a2 + hstepA, voffA);
;             PG8_WAIT_V(8); PG8_WAIT_L(0); PG8_BAR; PG8_MMA(0, 0, At, B0); PG8_MMA(0, 1, At, B1); PG8_BAR; PG8_SCHED;
	s_setprio 1
	s_waitcnt lgkmcnt(0)
	v_mfma_f32_16x16x32_bf16 v[60:63], v[128:131], v[160:163], 0
	v_mfma_f32_16x16x32_bf16 v[56:59], v[136:139], v[160:163], 0
	v_mfma_f32_16x16x32_bf16 v[44:47], v[128:131], v[170:173], 0
	v_mfma_f32_16x16x32_bf16 v[40:43], v[136:139], v[170:173], 0
	v_mfma_f32_16x16x32_bf16 v[28:31], v[128:131], v[202:205], 0
	v_mfma_f32_16x16x32_bf16 v[24:27], v[136:139], v[202:205], 0
	v_mfma_f32_16x16x32_bf16 v[12:15], v[128:131], v[210:213], 0
	v_mfma_f32_16x16x32_bf16 v[8:11], v[136:139], v[210:213], 0
	v_mfma_f32_16x16x32_bf16 v[60:63], v[132:135], v[164:167], v[60:63]
	v_mfma_f32_16x16x32_bf16 v[56:59], v[140:143], v[164:167], v[56:59]
	v_mfma_f32_16x16x32_bf16 v[44:47], v[132:135], v[198:201], v[44:47]
	v_mfma_f32_16x16x32_bf16 v[40:43], v[140:143], v[198:201], v[40:43]
	v_mfma_f32_16x16x32_bf16 v[28:31], v[132:135], v[206:209], v[28:31]
	v_mfma_f32_16x16x32_bf16 v[24:27], v[140:143], v[206:209], v[24:27]
	v_mfma_f32_16x16x32_bf16 v[12:15], v[132:135], v[214:217], v[12:15]
	v_mfma_f32_16x16x32_bf16 v[8:11], v[140:143], v[214:217], v[8:11]
	s_setprio 0
	s_setprio 1
	v_mfma_f32_16x16x32_bf16 v[52:55], v[144:147], v[160:163], 0
	v_mfma_f32_16x16x32_bf16 v[48:51], v[152:155], v[160:163], 0
	v_mfma_f32_16x16x32_bf16 v[36:39], v[144:147], v[170:173], 0
	v_mfma_f32_16x16x32_bf16 v[32:35], v[152:155], v[170:173], 0
	v_mfma_f32_16x16x32_bf16 v[20:23], v[144:147], v[202:205], 0
	v_mfma_f32_16x16x32_bf16 v[16:19], v[152:155], v[202:205], 0
	v_mfma_f32_16x16x32_bf16 v[4:7], v[144:147], v[210:213], 0
	v_mfma_f32_16x16x32_bf16 v[0:3], v[152:155], v[210:213], 0
	v_mfma_f32_16x16x32_bf16 v[52:55], v[148:151], v[164:167], v[52:55]
	v_mfma_f32_16x16x32_bf16 v[48:51], v[156:159], v[164:167], v[48:51]
	v_mfma_f32_16x16x32_bf16 v[36:39], v[148:151], v[198:201], v[36:39]
	v_mfma_f32_16x16x32_bf16 v[32:35], v[156:159], v[198:201], v[32:35]
	s_add_i32 s74, 0, 0x18000
	v_mfma_f32_16x16x32_bf16 v[20:23], v[148:151], v[206:209], v[20:23]
	s_add_i32 s75, 0, 0x1c000
	v_mfma_f32_16x16x32_bf16 v[16:19], v[156:159], v[206:209], v[16:19]
	v_add_u32_e32 v240, s74, v224
	v_mfma_f32_16x16x32_bf16 v[4:7], v[148:151], v[214:217], v[4:7]
	v_add_u32_e32 v241, s75, v224
	v_mfma_f32_16x16x32_bf16 v[0:3], v[156:159], v[214:217], v[0:3]
	s_setprio 0
	s_barrier
	ds_read_b128 v[128:131], v240
	ds_read_b128 v[132:135], v240 offset:1024
	ds_read_b128 v[136:139], v240 offset:2048
	ds_read_b128 v[140:143], v240 offset:3072
	ds_read_b128 v[144:147], v241
	ds_read_b128 v[148:151], v241 offset:1024
	ds_read_b128 v[152:155], v241 offset:2048
	ds_read_b128 v[156:159], v241 offset:3072
	s_add_u32 s60, s60, 0x40000
	s_addc_u32 s61, s61, 0
	s_mov_b32 m0, s73
	v_lshl_add_u64 v[236:237], s[60:61], 0, v[192:193]
	ds_read_b128 v[160:163], v225 offset:32768
	ds_read_b128 v[164:167], v225 offset:33792
	ds_read_b128 v[170:173], v225 offset:34816
	ds_read_b128 v[198:201], v225 offset:35840
	ds_read_b128 v[202:205], v225 offset:36864
	ds_read_b128 v[206:209], v225 offset:37888
	ds_read_b128 v[210:213], v225 offset:38912
	ds_read_b128 v[214:217], v225 offset:39936
	global_load_lds_dwordx4 v[236:237], off
	v_lshl_add_u64 v[236:237], s[60:61], 0, v[190:191]
	s_mov_b32 m0, s80
	s_nop 0
	global_load_lds_dwordx4 v[236:237], off
	s_waitcnt vmcnt(8)
	s_waitcnt lgkmcnt(0)
	s_barrier
	s_setprio 1
	s_waitcnt lgkmcnt(0)
	v_mfma_f32_16x16x32_bf16 v[124:127], v[128:131], v[160:163], v[124:127]
	v_mfma_f32_16x16x32_bf16 v[120:123], v[136:139], v[160:163], v[120:123]
	v_mfma_f32_16x16x32_bf16 v[108:111], v[128:131], v[170:173], v[108:111]
	v_mfma_f32_16x16x32_bf16 v[104:107], v[136:139], v[170:173], v[104:107]
	v_mfma_f32_16x16x32_bf16 v[92:95], v[128:131], v[202:205], v[92:95]
	v_mfma_f32_16x16x32_bf16 v[88:91], v[136:139], v[202:205], v[88:91]
	v_mfma_f32_16x16x32_bf16 v[76:79], v[128:131], v[210:213], v[76:79]
	v_mfma_f32_16x16x32_bf16 v[72:75], v[136:139], v[210:213], v[72:75]
	v_mfma_f32_16x16x32_bf16 v[124:127], v[132:135], v[164:167], v[124:127]
	v_mfma_f32_16x16x32_bf16 v[120:123], v[140:143], v[164:167], v[120:123]
	v_mfma_f32_16x16x32_bf16 v[108:111], v[132:135], v[198:201], v[108:111]
	v_mfma_f32_16x16x32_bf16 v[104:107], v[140:143], v[198:201], v[104:107]
	v_mfma_f32_16x16x32_bf16 v[92:95], v[132:135], v[206:209], v[92:95]
	v_mfma_f32_16x16x32_bf16 v[88:91], v[140:143], v[206:209], v[88:91]
	v_mfma_f32_16x16x32_bf16 v[76:79], v[132:135], v[214:217], v[76:79]
	v_mfma_f32_16x16x32_bf16 v[72:75], v[140:143], v[214:217], v[72:75]
	s_setprio 0
	s_setprio 1
	v_mfma_f32_16x16x32_bf16 v[116:119], v[144:147], v[160:163], v[116:119]
	v_mfma_f32_16x16x32_bf16 v[112:115], v[152:155], v[160:163], v[112:115]
	v_mfma_f32_16x16x32_bf16 v[100:103], v[144:147], v[170:173], v[100:103]
	v_mfma_f32_16x16x32_bf16 v[96:99], v[152:155], v[170:173], v[96:99]
	v_mfma_f32_16x16x32_bf16 v[84:87], v[144:147], v[202:205], v[84:87]
	v_mfma_f32_16x16x32_bf16 v[80:83], v[152:155], v[202:205], v[80:83]
	v_mfma_f32_16x16x32_bf16 v[68:71], v[144:147], v[210:213], v[68:71]
	v_mfma_f32_16x16x32_bf16 v[64:67], v[152:155], v[210:213], v[64:67]
	v_mfma_f32_16x16x32_bf16 v[116:119], v[148:151], v[164:167], v[116:119]
	v_mfma_f32_16x16x32_bf16 v[112:115], v[156:159], v[164:167], v[112:115]
	v_mfma_f32_16x16x32_bf16 v[100:103], v[148:151], v[198:201], v[100:103]
	v_mfma_f32_16x16x32_bf16 v[96:99], v[156:159], v[198:201], v[96:99]
	v_mfma_f32_16x16x32_bf16 v[84:87], v[148:151], v[206:209], v[84:87]
	s_add_i32 s60, s74, s34
	v_mfma_f32_16x16x32_bf16 v[80:83], v[156:159], v[206:209], v[80:83]
	v_lshl_add_u64 v[178:179], v[178:179], 0, s[30:31]
	v_mfma_f32_16x16x32_bf16 v[68:71], v[148:151], v[214:217], v[68:71]
	s_mov_b32 m0, s60
	v_mfma_f32_16x16x32_bf16 v[64:67], v[156:159], v[214:217], v[64:67]
	s_setprio 0
	s_barrier
; #define PG8_STAGE(bufoff, gbase, voff) do { _Pragma("unroll") for (int _i = 0; _i < 2; ++_i) \
;         __builtin_amdgcn_global_load_lds((const unsigned*)((const char*)(gbase) + (voff)[_i]), (PG8_LAS unsigned*)(lds + (bufoff) + ldsw + _i * 8192), 16, 0, 0); } while (0)
; #define PG8_LDA(dst, b, h) do { _Pragma("unroll") for (int m = 0; m < 4; ++m) _Pragma("unroll") for (int k = 0; k < 2; ++k) dst[m][k] = *(const PG8_LAS bf16x8*)(lds + PG8_SA(b, h) + aoff + m * 2048 + k * 1024); } while (0)
; #define PG8_MMA(ai, bj, At, Bt) do { __builtin_amdgcn_s_setprio(1); _Pragma("unroll") for (int m = 0; m < 4; ++m) _Pragma("unroll") for (int n = 0; n < 2; ++n) _Pragma("unroll") for (int k = 0; k < 2; ++k) \
;         acc[ai][bj][m][n] = __builtin_amdgcn_mfma_f32_16x16x32_bf16(Bt[n][k], At[m][k], acc[ai][bj][m][n], 0, 0, 0); __builtin_amdgcn_s_setprio(0); } while (0)
; #define PG8_WAIT_V(n) asm volatile("s_waitcnt vmcnt(" #n ")" ::: "memory")
; #define PG8_WAIT_L(n) asm volatile("s_waitcnt lgkmcnt(" #n ")" ::: "memory")
; #define PG8_BAR __builtin_amdgcn_s_barrier()
; #define PG8_SCHED __builtin_amdgcn_sched_barrier(0)
; template <class Epi, class Sched, bool ALIGN_EPI = false, bool SP2 = false>
; __device__ __forceinline__ void gemm_phase(PG8_LAS unsigned char* lds, const Gemm g, const Sched& S, const Epi& E) {
;     ...
;         for (int t = 0; t < nt; t += 2) {
;             const bool last = (t == nt - 2);
;             const char* a1 = cA + (size_t)(t + 1) * kstepA;
;             const char* a2 = last ? nA : cA + (size_t)(t + 2) * kstepA; const char* b2 = last ? nB : cB + (size_t)(t + 2) * kstep;
;             const char* a3 = a2 + kstepA; const char* b3 = b2 + kstep;
;     ...
;             PG8_LDA(At, 1, 1); PG8_STAGE(PG8_SB(1, 0), b3, voffB); PG8_STAGE(PG8_SB(1, 1), b3 + hstep, voffB); PG8_STAGE(PG8_SA(1, 0), a3, voffA);
;             PG8_WAIT_V(8); PG8_WAIT_L(0); PG8_BAR; PG8_MMA(1, 0, At, B0); PG8_MMA(1, 1, At, B1); PG8_BAR; PG8_SCHED;
	ds_read_b128 v[160:163], v225 offset:49152
	ds_read_b128 v[164:167], v225 offset:50176
	ds_read_b128 v[170:173], v225 offset:51200
	ds_read_b128 v[198:201], v225 offset:52224
	ds_read_b128 v[202:205], v225 offset:53248
	ds_read_b128 v[206:209], v225 offset:54272
	ds_read_b128 v[210:213], v225 offset:55296
	ds_read_b128 v[214:217], v225 offset:56320
	global_load_lds_dwordx4 v[178:179], off
	s_add_i32 m0, s60, 0x2000
	s_add_u32 s58, s58, 0x40080
	v_lshl_add_u64 v[178:179], v[218:219], 0, s[30:31]
	s_addc_u32 s59, s59, 0
	s_add_i32 s60, s75, s34
	global_load_lds_dwordx4 v[178:179], off
	v_lshl_add_u64 v[178:179], s[58:59], 0, v[168:169]
	s_mov_b32 m0, s60
	s_nop 0
	global_load_lds_dwordx4 v[178:179], off
	v_lshl_add_u64 v[178:179], s[58:59], 0, v[188:189]
	s_add_i32 m0, s60, 0x2000
	s_nop 0
	global_load_lds_dwordx4 v[178:179], off
	v_lshl_add_u64 v[178:179], v[220:221], 0, s[30:31]
	s_mov_b32 m0, s84
	s_nop 0
	global_load_lds_dwordx4 v[178:179], off
	v_lshl_add_u64 v[178:179], v[234:235], 0, s[30:31]
	s_mov_b32 m0, s85
	s_nop 0
	global_load_lds_dwordx4 v[178:179], off
	s_waitcnt vmcnt(8)
	s_waitcnt lgkmcnt(0)
	s_barrier
	s_setprio 1
	s_waitcnt lgkmcnt(0)
	v_mfma_f32_16x16x32_bf16 v[60:63], v[128:131], v[160:163], v[60:63]
	v_mfma_f32_16x16x32_bf16 v[56:59], v[136:139], v[160:163], v[56:59]
	v_mfma_f32_16x16x32_bf16 v[44:47], v[128:131], v[170:173], v[44:47]
	v_mfma_f32_16x16x32_bf16 v[40:43], v[136:139], v[170:173], v[40:43]
	v_mfma_f32_16x16x32_bf16 v[28:31], v[128:131], v[202:205], v[28:31]
	v_mfma_f32_16x16x32_bf16 v[24:27], v[136:139], v[202:205], v[24:27]
	v_mfma_f32_16x16x32_bf16 v[12:15], v[128:131], v[210:213], v[12:15]
	v_mfma_f32_16x16x32_bf16 v[8:11], v[136:139], v[210:213], v[8:11]
	v_mfma_f32_16x16x32_bf16 v[60:63], v[132:135], v[164:167], v[60:63]
	v_mfma_f32_16x16x32_bf16 v[56:59], v[140:143], v[164:167], v[56:59]
	v_mfma_f32_16x16x32_bf16 v[44:47], v[132:135], v[198:201], v[44:47]
	v_mfma_f32_16x16x32_bf16 v[40:43], v[140:143], v[198:201], v[40:43]
	v_mfma_f32_16x16x32_bf16 v[28:31], v[132:135], v[206:209], v[28:31]
	v_mfma_f32_16x16x32_bf16 v[24:27], v[140:143], v[206:209], v[24:27]
	v_mfma_f32_16x16x32_bf16 v[12:15], v[132:135], v[214:217], v[12:15]
	v_mfma_f32_16x16x32_bf16 v[8:11], v[140:143], v[214:217], v[8:11]
	s_add_i32 s65, s65, 2
	s_setprio 0
	s_setprio 1
	v_mfma_f32_16x16x32_bf16 v[52:55], v[144:147], v[160:163], v[52:55]
	s_add_u32 s53, s53, 0x100
	v_mfma_f32_16x16x32_bf16 v[48:51], v[152:155], v[160:163], v[48:51]
	s_addc_u32 s64, s64, 0
	v_mfma_f32_16x16x32_bf16 v[36:39], v[144:147], v[170:173], v[36:39]
	s_add_u32 s40, s40, 0x100
	v_mfma_f32_16x16x32_bf16 v[32:35], v[152:155], v[170:173], v[32:35]
	s_addc_u32 s41, s41, 0
	v_mfma_f32_16x16x32_bf16 v[20:23], v[144:147], v[202:205], v[20:23]
	s_add_u32 s58, s40, 0xfffc0080
	v_mfma_f32_16x16x32_bf16 v[16:19], v[152:155], v[202:205], v[16:19]
	s_addc_u32 s59, s41, -1
	v_mfma_f32_16x16x32_bf16 v[4:7], v[144:147], v[210:213], v[4:7]
	s_add_i32 s74, 0, 0x10000
	v_mfma_f32_16x16x32_bf16 v[0:3], v[152:155], v[210:213], v[0:3]
	s_cmp_eq_u32 s65, 12
	v_mfma_f32_16x16x32_bf16 v[52:55], v[148:151], v[164:167], v[52:55]
	s_cselect_b32 s61, s5, s59
	v_mfma_f32_16x16x32_bf16 v[48:51], v[156:159], v[164:167], v[48:51]
	s_cselect_b32 s60, s6, s58
	v_mfma_f32_16x16x32_bf16 v[36:39], v[148:151], v[198:201], v[36:39]
	s_cselect_b32 s59, s7, s64
	v_mfma_f32_16x16x32_bf16 v[32:35], v[156:159], v[198:201], v[32:35]
	s_cselect_b32 s58, s51, s53
	v_mfma_f32_16x16x32_bf16 v[20:23], v[148:151], v[206:209], v[20:23]
	s_add_i32 s91, 0, 0x14000
	v_mfma_f32_16x16x32_bf16 v[16:19], v[156:159], v[206:209], v[16:19]
	v_add_u32_e32 v242, s74, v224
	v_mfma_f32_16x16x32_bf16 v[4:7], v[148:151], v[214:217], v[4:7]
	v_add_u32_e32 v243, s91, v224
	v_mfma_f32_16x16x32_bf16 v[0:3], v[156:159], v[214:217], v[0:3]
	s_setprio 0
	s_barrier

; #define PG8_STAGE(bufoff, gbase, voff) do { _Pragma("unroll") for (int _i = 0; _i < 2; ++_i) \
;         __builtin_amdgcn_global_load_lds((const unsigned*)((const char*)(gbase) + (voff)[_i]), (PG8_LAS unsigned*)(lds + (bufoff) + ldsw + _i * 8192), 16, 0, 0); } while (0)
; #define PG8_LDA(dst, b, h) do { _Pragma("unroll") for (int m = 0; m < 4; ++m) _Pragma("unroll") for (int k = 0; k < 2; ++k) dst[m][k] = *(const PG8_LAS bf16x8*)(lds + PG8_SA(b, h) + aoff + m * 2048 + k * 1024); } while (0)
; #define PG8_LDB(dst, b, h) do { _Pragma("unroll") for (int n = 0; n < 2; ++n) _Pragma("unroll") for (int k = 0; k < 2; ++k) dst[n][k] = *(const PG8_LAS bf16x8*)(lds + PG8_SB(b, h) + boff + n * 2048 + k * 1024); } while (0)
; #define PG8_BAR __builtin_amdgcn_s_barrier()
;     __host__ __device__ bool next(int i, Unit& u) const {
;         const long L = (long)i * G + c; if (L >= nwg) return false;
;         int wgid = (int)L; { const int q = nwg / NXCD, r = nwg % NXCD, xcd = wgid % NXCD, off = wgid / NXCD; wgid = (xcd < r ? xcd * (q + 1) : r * (q + 1) + (xcd - r) * q) + off; }
;         const int nig = WGM * nN, gid = wgid / nig, fm = gid * WGM, gsz = (nM - fm) < WGM ? (nM - fm) : WGM;
;         u.pm = fm + ((wgid % nig) % gsz); u.pn = (wgid % nig) / gsz; return true;
; template <class Epi, class Sched, bool ALIGN_EPI = false, bool SP2 = false>
; __device__ __forceinline__ void gemm_phase(PG8_LAS unsigned char* lds, const Gemm g, const Sched& S, const Epi& E) {
;     ...
;         const bool has_next = S.next(ui + 1, nxt);
;         const char* nA = has_next ? (const char*)g.A + (size_t)nxt.pm * tstepA : cA; const char* nB = has_next ? (const char*)g.Bt + (size_t)nxt.pn * tstep : cB;
;         for (int t = 0; t < nt; t += 2) {
;             const bool last = (t == nt - 2);
;             const char* a1 = cA + (size_t)(t + 1) * kstepA;
;             const char* a2 = last ? nA : cA + (size_t)(t + 2) * kstepA; const char* b2 = last ? nB : cB + (size_t)(t + 2) * kstep;
;             const char* a3 = a2 + kstepA; const char* b3 = b2 + kstep;
;             if (last && has_next) S.a_ready(nxt);
;             if constexpr (SP2) {
;             PG8_LDB(B0, 0, 0); PG8_LDB(B1, 0, 1); PG8_SCHED; PG8_LDA(At, 0, 0); PG8_STAGE(PG8_SA(1, 1), a1 + hstepA, voffA);
;             PG8_WAIT_V(8); PG8_WAIT_L(0); PG8_BAR; PG8_MMA(0, 0, At, B0); PG8_MMA(0, 1, At, B1); PG8_BAR; PG8_SCHED;
.LBB0_833:
	v_add_u32_e32 v244, 0x10000, v142
	v_add_u32_e32 v245, 0x14000, v142
	ds_read_b128 v[144:147], v244
	ds_read_b128 v[148:151], v244 offset:1024
	ds_read_b128 v[152:155], v244 offset:2048
	ds_read_b128 v[156:159], v244 offset:3072
	ds_read_b128 v[160:163], v245
	ds_read_b128 v[164:167], v245 offset:1024
	ds_read_b128 v[170:173], v245 offset:2048
	ds_read_b128 v[188:191], v245 offset:3072
	ds_read_b128 v[192:195], v143
	ds_read_b128 v[196:199], v143 offset:1024
	ds_read_b128 v[200:203], v143 offset:2048
	ds_read_b128 v[204:207], v143 offset:3072
	ds_read_b128 v[208:211], v143 offset:4096
	ds_read_b128 v[212:215], v143 offset:5120
	ds_read_b128 v[216:219], v143 offset:6144
	ds_read_b128 v[220:223], v143 offset:7168
	s_add_i32 s58, s58, 1
	s_mul_i32 s38, s58, s11
	s_mul_hi_u32 s39, s58, s10
	s_add_i32 s39, s39, s38
	s_mul_i32 s38, s58, s10
	s_add_u32 s44, s38, s93
	s_addc_u32 s45, s39, s9
	v_cmp_gt_i64_e32 vcc, s[44:45], v[186:187]
	v_cmp_lt_i64_e64 s[38:39], s[44:45], v[184:185]
	s_cbranch_vccnz .LBB0_835
	s_ashr_i32 s40, s44, 31
	s_lshr_b32 s40, s40, 29
	s_add_i32 s40, s44, s40
	s_ashr_i32 s41, s40, 3
	s_and_b32 s40, s40, -8
	s_sub_i32 s40, s44, s40
	s_cmp_lt_i32 s40, 0
	s_movk_i32 s36, 0x2c1
	s_cselect_b32 s42, s36, 0x2c0
	s_mul_i32 s40, s40, s42
	s_add_i32 s40, s40, s41
	s_mul_hi_i32 s41, s40, 0x2e8ba2e9
	s_lshr_b32 s42, s41, 31
	s_ashr_i32 s41, s41, 5
	s_add_i32 s41, s41, s42
	s_lshl_b32 s42, s41, 3
	s_sub_i32 s43, 0x100, s42
	s_min_i32 s43, s43, 8
	s_abs_i32 s44, s43
	v_cvt_f32_u32_e32 v0, s44
	s_sub_i32 s46, 0, s44
	s_mulk_i32 s41, 0xb0
	s_sub_i32 s41, s40, s41
	v_rcp_iflag_f32_e32 v0, v0
	s_abs_i32 s40, s41
	s_xor_b32 s45, s41, s43
	s_ashr_i32 s45, s45, 31
	v_mul_f32_e32 v0, 0x4f7ffffe, v0
	v_cvt_u32_f32_e32 v0, v0
	s_nop 0
	v_readfirstlane_b32 s47, v0
	s_mul_i32 s46, s46, s47
	s_mul_hi_u32 s46, s47, s46
	s_add_i32 s47, s47, s46
	s_mul_hi_u32 s46, s40, s47
	s_mul_i32 s47, s46, s44
	s_sub_i32 s40, s40, s47
	s_add_i32 s52, s46, 1
	s_sub_i32 s47, s40, s44
	s_cmp_ge_u32 s40, s44
	s_cselect_b32 s46, s52, s46
	s_cselect_b32 s40, s47, s40
	s_add_i32 s47, s46, 1
	s_cmp_ge_u32 s40, s44
	s_cselect_b32 s40, s47, s46
	s_xor_b32 s40, s40, s45
	s_sub_i32 s40, s40, s45
	s_mul_i32 s43, s40, s43
	s_sub_i32 s41, s41, s43
	s_add_i32 s42, s42, s41
.LBB0_835:
	s_ashr_i32 s43, s42, 31
	s_lshl_b64 s[44:45], s[42:43], 19
	s_add_u32 s44, s20, s44
	s_addc_u32 s45, s21, s45
	s_and_b64 s[46:47], s[38:39], exec
	s_cselect_b32 s43, s45, s51
	s_cselect_b32 s61, s44, s50
	s_ashr_i32 s41, s40, 31
	s_lshl_b64 s[46:47], s[40:41], 19
	s_add_u32 s46, s2, s46
	s_addc_u32 s47, s3, s47
	s_and_b64 s[52:53], s[38:39], exec
	s_cselect_b32 s41, s47, s49
	s_cselect_b32 s64, s46, s48
	s_add_u32 s65, s48, 0x100
	s_addc_u32 s69, s49, 0
	s_add_u32 s48, s50, 0x40080
	s_addc_u32 s49, s51, 0
	s_mov_b32 s73, -2
	s_add_u32 s50, s48, 0xfffc0080
	s_addc_u32 s51, s49, -1
	s_add_i32 s74, 0, 0x10000
	s_cmp_eq_u32 s73, 12
	s_cselect_b32 s53, s43, s51
	s_cselect_b32 s52, s61, s50
	s_cselect_b32 s51, s41, s69
	s_cselect_b32 s50, s64, s65
	s_add_i32 s80, 0, 0x14000
	v_lshl_add_u64 v[178:179], s[48:49], 0, v[140:141]
	s_add_i32 m0, s7, 0xc000
	global_load_lds_dwordx4 v[178:179], off
	v_lshl_add_u64 v[178:179], s[48:49], 0, v[138:139]
	s_add_i32 m0, s7, 0xe000
	s_nop 0
	global_load_lds_dwordx4 v[178:179], off
	s_waitcnt vmcnt(8)
	s_waitcnt lgkmcnt(0)
	s_barrier
	s_setprio 1
	s_waitcnt lgkmcnt(0)
	v_mfma_f32_16x16x32_bf16 v[124:127], v[144:147], v[192:195], 0
	v_mfma_f32_16x16x32_bf16 v[116:119], v[152:155], v[192:195], 0
	v_mfma_f32_16x16x32_bf16 v[108:111], v[144:147], v[200:203], 0
	v_mfma_f32_16x16x32_bf16 v[100:103], v[152:155], v[200:203], 0
	v_mfma_f32_16x16x32_bf16 v[92:95], v[144:147], v[208:211], 0
	v_mfma_f32_16x16x32_bf16 v[84:87], v[152:155], v[208:211], 0
	v_mfma_f32_16x16x32_bf16 v[76:79], v[144:147], v[216:219], 0
	v_mfma_f32_16x16x32_bf16 v[68:71], v[152:155], v[216:219], 0
	v_mfma_f32_16x16x32_bf16 v[124:127], v[148:151], v[196:199], v[124:127]
	v_mfma_f32_16x16x32_bf16 v[116:119], v[156:159], v[196:199], v[116:119]
	v_mfma_f32_16x16x32_bf16 v[108:111], v[148:151], v[204:207], v[108:111]
	v_mfma_f32_16x16x32_bf16 v[100:103], v[156:159], v[204:207], v[100:103]
	v_mfma_f32_16x16x32_bf16 v[92:95], v[148:151], v[212:215], v[92:95]
	v_mfma_f32_16x16x32_bf16 v[84:87], v[156:159], v[212:215], v[84:87]
	v_mfma_f32_16x16x32_bf16 v[76:79], v[148:151], v[220:223], v[76:79]
	v_mfma_f32_16x16x32_bf16 v[68:71], v[156:159], v[220:223], v[68:71]
	s_setprio 0
	s_setprio 1
	v_mfma_f32_16x16x32_bf16 v[120:123], v[160:163], v[192:195], 0
	v_mfma_f32_16x16x32_bf16 v[112:115], v[170:173], v[192:195], 0
	v_mfma_f32_16x16x32_bf16 v[104:107], v[160:163], v[200:203], 0
	v_mfma_f32_16x16x32_bf16 v[96:99], v[170:173], v[200:203], 0
	v_mfma_f32_16x16x32_bf16 v[88:91], v[160:163], v[208:211], 0
	v_mfma_f32_16x16x32_bf16 v[80:83], v[170:173], v[208:211], 0
	v_mfma_f32_16x16x32_bf16 v[72:75], v[160:163], v[216:219], 0
	v_mfma_f32_16x16x32_bf16 v[64:67], v[170:173], v[216:219], 0
	v_mfma_f32_16x16x32_bf16 v[120:123], v[164:167], v[196:199], v[120:123]
	v_mfma_f32_16x16x32_bf16 v[112:115], v[188:191], v[196:199], v[112:115]
	v_mfma_f32_16x16x32_bf16 v[104:107], v[164:167], v[204:207], v[104:107]
	v_mfma_f32_16x16x32_bf16 v[96:99], v[188:191], v[204:207], v[96:99]
	v_mfma_f32_16x16x32_bf16 v[88:91], v[164:167], v[212:215], v[88:91]
	s_add_i32 s74, s74, s6
	v_mfma_f32_16x16x32_bf16 v[80:83], v[188:191], v[212:215], v[80:83]
	v_lshl_add_u64 v[178:179], s[50:51], 0, v[132:133]
	v_mfma_f32_16x16x32_bf16 v[72:75], v[164:167], v[220:223], v[72:75]
	s_mov_b32 m0, s74
	v_mfma_f32_16x16x32_bf16 v[64:67], v[188:191], v[220:223], v[64:67]
	s_setprio 0
	s_barrier
; #define PG8_STAGE(bufoff, gbase, voff) do { _Pragma("unroll") for (int _i = 0; _i < 2; ++_i) \
;         __builtin_amdgcn_global_load_lds((const unsigned*)((const char*)(gbase) + (voff)[_i]), (PG8_LAS unsigned*)(lds + (bufoff) + ldsw + _i * 8192), 16, 0, 0); } while (0)
; #define PG8_LDA(dst, b, h) do { _Pragma("unroll") for (int m = 0; m < 4; ++m) _Pragma("unroll") for (int k = 0; k < 2; ++k) dst[m][k] = *(const PG8_LAS bf16x8*)(lds + PG8_SA(b, h) + aoff + m * 2048 + k * 1024); } while (0)
; #define PG8_LDB(dst, b, h) do { _Pragma("unroll") for (int n = 0; n < 2; ++n) _Pragma("unroll") for (int k = 0; k < 2; ++k) dst[n][k] = *(const PG8_LAS bf16x8*)(lds + PG8_SB(b, h) + boff + n * 2048 + k * 1024); } while (0)
; #define PG8_MMA(ai, bj, At, Bt) do { __builtin_amdgcn_s_setprio(1); _Pragma("unroll") for (int m = 0; m < 4; ++m) _Pragma("unroll") for (int n = 0; n < 2; ++n) _Pragma("unroll") for (int k = 0; k < 2; ++k) \
;         acc[ai][bj][m][n] = __builtin_amdgcn_mfma_f32_16x16x32_bf16(Bt[n][k], At[m][k], acc[ai][bj][m][n], 0, 0, 0); __builtin_amdgcn_s_setprio(0); } while (0)
; #define PG8_WAIT_V(n) asm volatile("s_waitcnt vmcnt(" #n ")" ::: "memory")
; #define PG8_WAIT_L(n) asm volatile("s_waitcnt lgkmcnt(" #n ")" ::: "memory")
; #define PG8_BAR __builtin_amdgcn_s_barrier()
; #define PG8_SCHED __builtin_amdgcn_sched_barrier(0)
; template <class Epi, class Sched, bool ALIGN_EPI = false, bool SP2 = false>
; __device__ __forceinline__ void gemm_phase(PG8_LAS unsigned char* lds, const Gemm g, const Sched& S, const Epi& E) {
;     ...
;             PG8_LDA(At, 0, 1); PG8_STAGE(PG8_SB(0, 0), b2, voffB); PG8_STAGE(PG8_SB(0, 1), b2 + hstep, voffB); PG8_STAGE(PG8_SA(0, 0), a2, voffA);
;             PG8_WAIT_V(8); PG8_WAIT_L(0); PG8_BAR; PG8_MMA(1, 0, At, B0); PG8_MMA(1, 1, At, B1); PG8_BAR; PG8_SCHED;
;             PG8_LDB(B0, 1, 0); PG8_LDB(B1, 1, 1); PG8_SCHED; PG8_LDA(At, 1, 0); PG8_STAGE(PG8_SA(0, 1), a2 + hstepA, voffA);
	ds_read_b128 v[192:195], v143 offset:16384
	ds_read_b128 v[196:199], v143 offset:17408
	ds_read_b128 v[200:203], v143 offset:18432
	ds_read_b128 v[204:207], v143 offset:19456
	ds_read_b128 v[208:211], v143 offset:20480
	ds_read_b128 v[212:215], v143 offset:21504
	ds_read_b128 v[216:219], v143 offset:22528
	ds_read_b128 v[220:223], v143 offset:23552
	global_load_lds_dwordx4 v[178:179], off
	s_add_i32 m0, s74, 0x2000
	s_add_u32 s74, s50, 0x40000
	v_lshl_add_u64 v[224:225], s[50:51], 0, v[128:129]
	s_addc_u32 s75, s51, 0
	s_add_i32 s80, s80, s6
	global_load_lds_dwordx4 v[224:225], off
	v_lshl_add_u64 v[234:235], s[74:75], 0, v[132:133]
	s_mov_b32 m0, s80
	v_lshl_add_u64 v[236:237], s[52:53], 0, v[130:131]
	global_load_lds_dwordx4 v[234:235], off
	v_lshl_add_u64 v[234:235], s[74:75], 0, v[128:129]
	s_add_i32 m0, s80, 0x2000
	s_nop 0
	global_load_lds_dwordx4 v[234:235], off
	v_lshl_add_u64 v[234:235], s[52:53], 0, v[134:135]
	s_mov_b32 m0, s7
	s_nop 0
	global_load_lds_dwordx4 v[234:235], off
	s_mov_b32 m0, s34
	s_nop 0
	global_load_lds_dwordx4 v[236:237], off
	s_waitcnt vmcnt(8)
	s_waitcnt lgkmcnt(0)
	s_barrier
	s_setprio 1
	s_waitcnt lgkmcnt(0)
	v_mfma_f32_16x16x32_bf16 v[60:63], v[144:147], v[192:195], 0
	v_mfma_f32_16x16x32_bf16 v[52:55], v[152:155], v[192:195], 0
	v_mfma_f32_16x16x32_bf16 v[44:47], v[144:147], v[200:203], 0
	v_mfma_f32_16x16x32_bf16 v[36:39], v[152:155], v[200:203], 0
	v_mfma_f32_16x16x32_bf16 v[28:31], v[144:147], v[208:211], 0
	v_mfma_f32_16x16x32_bf16 v[20:23], v[152:155], v[208:211], 0
	v_mfma_f32_16x16x32_bf16 v[12:15], v[144:147], v[216:219], 0
	v_mfma_f32_16x16x32_bf16 v[4:7], v[152:155], v[216:219], 0
	v_mfma_f32_16x16x32_bf16 v[60:63], v[148:151], v[196:199], v[60:63]
	v_mfma_f32_16x16x32_bf16 v[52:55], v[156:159], v[196:199], v[52:55]
	v_mfma_f32_16x16x32_bf16 v[44:47], v[148:151], v[204:207], v[44:47]
	v_mfma_f32_16x16x32_bf16 v[36:39], v[156:159], v[204:207], v[36:39]
	v_mfma_f32_16x16x32_bf16 v[28:31], v[148:151], v[212:215], v[28:31]
	v_mfma_f32_16x16x32_bf16 v[20:23], v[156:159], v[212:215], v[20:23]
	v_mfma_f32_16x16x32_bf16 v[12:15], v[148:151], v[220:223], v[12:15]
	v_mfma_f32_16x16x32_bf16 v[4:7], v[156:159], v[220:223], v[4:7]
	s_setprio 0
	s_setprio 1
	v_mfma_f32_16x16x32_bf16 v[56:59], v[160:163], v[192:195], 0
	v_mfma_f32_16x16x32_bf16 v[48:51], v[170:173], v[192:195], 0
	v_mfma_f32_16x16x32_bf16 v[40:43], v[160:163], v[200:203], 0
	v_mfma_f32_16x16x32_bf16 v[32:35], v[170:173], v[200:203], 0
	v_mfma_f32_16x16x32_bf16 v[24:27], v[160:163], v[208:211], 0
	v_mfma_f32_16x16x32_bf16 v[16:19], v[170:173], v[208:211], 0
	v_mfma_f32_16x16x32_bf16 v[8:11], v[160:163], v[216:219], 0
	v_mfma_f32_16x16x32_bf16 v[0:3], v[170:173], v[216:219], 0
	v_mfma_f32_16x16x32_bf16 v[56:59], v[164:167], v[196:199], v[56:59]
	v_mfma_f32_16x16x32_bf16 v[48:51], v[188:191], v[196:199], v[48:51]
	v_mfma_f32_16x16x32_bf16 v[40:43], v[164:167], v[204:207], v[40:43]
	v_mfma_f32_16x16x32_bf16 v[32:35], v[188:191], v[204:207], v[32:35]
	s_add_i32 s74, 0, 0x18000
	v_mfma_f32_16x16x32_bf16 v[24:27], v[164:167], v[212:215], v[24:27]
	s_add_i32 s75, 0, 0x1c000
	v_mfma_f32_16x16x32_bf16 v[16:19], v[188:191], v[212:215], v[16:19]
	v_add_u32_e32 v240, s74, v142
	v_mfma_f32_16x16x32_bf16 v[8:11], v[164:167], v[220:223], v[8:11]
	v_add_u32_e32 v241, s75, v142
	v_mfma_f32_16x16x32_bf16 v[0:3], v[188:191], v[220:223], v[0:3]
	s_setprio 0
	s_barrier
	ds_read_b128 v[144:147], v240
	ds_read_b128 v[148:151], v240 offset:1024
	ds_read_b128 v[152:155], v240 offset:2048
	ds_read_b128 v[156:159], v240 offset:3072
	ds_read_b128 v[160:163], v241
	ds_read_b128 v[164:167], v241 offset:1024
	ds_read_b128 v[170:173], v241 offset:2048
	ds_read_b128 v[188:191], v241 offset:3072
	s_add_u32 s52, s52, 0x40000
	s_addc_u32 s53, s53, 0
	s_mov_b32 m0, s35
	v_lshl_add_u64 v[238:239], s[52:53], 0, v[134:135]
	ds_read_b128 v[192:195], v143 offset:32768
	ds_read_b128 v[196:199], v143 offset:33792
	ds_read_b128 v[200:203], v143 offset:34816
	ds_read_b128 v[204:207], v143 offset:35840
	ds_read_b128 v[208:211], v143 offset:36864
	ds_read_b128 v[212:215], v143 offset:37888
	ds_read_b128 v[216:219], v143 offset:38912
	ds_read_b128 v[220:223], v143 offset:39936
	global_load_lds_dwordx4 v[238:239], off
	v_lshl_add_u64 v[238:239], s[52:53], 0, v[130:131]
	s_mov_b32 m0, s54
	s_nop 0
	global_load_lds_dwordx4 v[238:239], off
	s_waitcnt vmcnt(8)
	s_waitcnt lgkmcnt(0)
	s_barrier
; #define PG8_STAGE(bufoff, gbase, voff) do { _Pragma("unroll") for (int _i = 0; _i < 2; ++_i) \
;         __builtin_amdgcn_global_load_lds((const unsigned*)((const char*)(gbase) + (voff)[_i]), (PG8_LAS unsigned*)(lds + (bufoff) + ldsw + _i * 8192), 16, 0, 0); } while (0)
; #define PG8_LDA(dst, b, h) do { _Pragma("unroll") for (int m = 0; m < 4; ++m) _Pragma("unroll") for (int k = 0; k < 2; ++k) dst[m][k] = *(const PG8_LAS bf16x8*)(lds + PG8_SA(b, h) + aoff + m * 2048 + k * 1024); } while (0)
; #define PG8_MMA(ai, bj, At, Bt) do { __builtin_amdgcn_s_setprio(1); _Pragma("unroll") for (int m = 0; m < 4; ++m) _Pragma("unroll") for (int n = 0; n < 2; ++n) _Pragma("unroll") for (int k = 0; k < 2; ++k) \
;         acc[ai][bj][m][n] = __builtin_amdgcn_mfma_f32_16x16x32_bf16(Bt[n][k], At[m][k], acc[ai][bj][m][n], 0, 0, 0); __builtin_amdgcn_s_setprio(0); } while (0)
; #define PG8_WAIT_V(n) asm volatile("s_waitcnt vmcnt(" #n ")" ::: "memory")
; #define PG8_WAIT_L(n) asm volatile("s_waitcnt lgkmcnt(" #n ")" ::: "memory")
; #define PG8_BAR __builtin_amdgcn_s_barrier()
; #define PG8_SCHED __builtin_amdgcn_sched_barrier(0)
; template <class Epi, class Sched, bool ALIGN_EPI = false, bool SP2 = false>
; __device__ __forceinline__ void gemm_phase(PG8_LAS unsigned char* lds, const Gemm g, const Sched& S, const Epi& E) {
;     ...
;         for (int t = 0; t < nt; t += 2) {
;             const bool last = (t == nt - 2);
;             const char* a1 = cA + (size_t)(t + 1) * kstepA;
;             const char* a2 = last ? nA : cA + (size_t)(t + 2) * kstepA; const char* b2 = last ? nB : cB + (size_t)(t + 2) * kstep;
;             const char* a3 = a2 + kstepA; const char* b3 = b2 + kstep;
;     ...
;             PG8_WAIT_V(8); PG8_WAIT_L(0); PG8_BAR; PG8_MMA(0, 0, At, B0); PG8_MMA(0, 1, At, B1); PG8_BAR; PG8_SCHED;
;             PG8_LDA(At, 1, 1); PG8_STAGE(PG8_SB(1, 0), b3, voffB); PG8_STAGE(PG8_SB(1, 1), b3 + hstep, voffB); PG8_STAGE(PG8_SA(1, 0), a3, voffA);
;             PG8_WAIT_V(8); PG8_WAIT_L(0); PG8_BAR; PG8_MMA(1, 0, At, B0); PG8_MMA(1, 1, At, B1); PG8_BAR; PG8_SCHED;
	s_setprio 1
	s_waitcnt lgkmcnt(0)
	v_mfma_f32_16x16x32_bf16 v[124:127], v[144:147], v[192:195], v[124:127]
	v_mfma_f32_16x16x32_bf16 v[116:119], v[152:155], v[192:195], v[116:119]
	v_mfma_f32_16x16x32_bf16 v[108:111], v[144:147], v[200:203], v[108:111]
	v_mfma_f32_16x16x32_bf16 v[100:103], v[152:155], v[200:203], v[100:103]
	v_mfma_f32_16x16x32_bf16 v[92:95], v[144:147], v[208:211], v[92:95]
	v_mfma_f32_16x16x32_bf16 v[84:87], v[152:155], v[208:211], v[84:87]
	v_mfma_f32_16x16x32_bf16 v[76:79], v[144:147], v[216:219], v[76:79]
	v_mfma_f32_16x16x32_bf16 v[68:71], v[152:155], v[216:219], v[68:71]
	v_mfma_f32_16x16x32_bf16 v[124:127], v[148:151], v[196:199], v[124:127]
	v_mfma_f32_16x16x32_bf16 v[116:119], v[156:159], v[196:199], v[116:119]
	v_mfma_f32_16x16x32_bf16 v[108:111], v[148:151], v[204:207], v[108:111]
	v_mfma_f32_16x16x32_bf16 v[100:103], v[156:159], v[204:207], v[100:103]
	v_mfma_f32_16x16x32_bf16 v[92:95], v[148:151], v[212:215], v[92:95]
	v_mfma_f32_16x16x32_bf16 v[84:87], v[156:159], v[212:215], v[84:87]
	v_mfma_f32_16x16x32_bf16 v[76:79], v[148:151], v[220:223], v[76:79]
	v_mfma_f32_16x16x32_bf16 v[68:71], v[156:159], v[220:223], v[68:71]
	s_setprio 0
	s_setprio 1
	v_mfma_f32_16x16x32_bf16 v[120:123], v[160:163], v[192:195], v[120:123]
	v_mfma_f32_16x16x32_bf16 v[112:115], v[170:173], v[192:195], v[112:115]
	v_mfma_f32_16x16x32_bf16 v[104:107], v[160:163], v[200:203], v[104:107]
	v_mfma_f32_16x16x32_bf16 v[96:99], v[170:173], v[200:203], v[96:99]
	v_mfma_f32_16x16x32_bf16 v[88:91], v[160:163], v[208:211], v[88:91]
	v_mfma_f32_16x16x32_bf16 v[80:83], v[170:173], v[208:211], v[80:83]
	v_mfma_f32_16x16x32_bf16 v[72:75], v[160:163], v[216:219], v[72:75]
	v_mfma_f32_16x16x32_bf16 v[64:67], v[170:173], v[216:219], v[64:67]
	v_mfma_f32_16x16x32_bf16 v[120:123], v[164:167], v[196:199], v[120:123]
	v_mfma_f32_16x16x32_bf16 v[112:115], v[188:191], v[196:199], v[112:115]
	v_mfma_f32_16x16x32_bf16 v[104:107], v[164:167], v[204:207], v[104:107]
	v_mfma_f32_16x16x32_bf16 v[96:99], v[188:191], v[204:207], v[96:99]
	v_mfma_f32_16x16x32_bf16 v[88:91], v[164:167], v[212:215], v[88:91]
	s_add_i32 s52, s74, s6
	v_mfma_f32_16x16x32_bf16 v[80:83], v[188:191], v[212:215], v[80:83]
	v_lshl_add_u64 v[178:179], v[178:179], 0, s[30:31]
	v_mfma_f32_16x16x32_bf16 v[72:75], v[164:167], v[220:223], v[72:75]
	s_mov_b32 m0, s52
	v_mfma_f32_16x16x32_bf16 v[64:67], v[188:191], v[220:223], v[64:67]
	s_setprio 0
	s_barrier
	ds_read_b128 v[192:195], v143 offset:49152
	ds_read_b128 v[196:199], v143 offset:50176
	ds_read_b128 v[200:203], v143 offset:51200
	ds_read_b128 v[204:207], v143 offset:52224
	ds_read_b128 v[208:211], v143 offset:53248
	ds_read_b128 v[212:215], v143 offset:54272
	ds_read_b128 v[216:219], v143 offset:55296
	ds_read_b128 v[220:223], v143 offset:56320
	global_load_lds_dwordx4 v[178:179], off
	s_add_i32 m0, s52, 0x2000
	s_add_u32 s50, s50, 0x40080
	v_lshl_add_u64 v[178:179], v[224:225], 0, s[30:31]
	s_addc_u32 s51, s51, 0
	s_add_i32 s52, s75, s6
	global_load_lds_dwordx4 v[178:179], off
	v_lshl_add_u64 v[178:179], s[50:51], 0, v[132:133]
	s_mov_b32 m0, s52
	s_nop 0
	global_load_lds_dwordx4 v[178:179], off
	v_lshl_add_u64 v[178:179], s[50:51], 0, v[128:129]
	s_add_i32 m0, s52, 0x2000
	s_nop 0
	global_load_lds_dwordx4 v[178:179], off
	v_lshl_add_u64 v[178:179], v[234:235], 0, s[30:31]
	s_mov_b32 m0, s55
	s_nop 0
	global_load_lds_dwordx4 v[178:179], off
	v_lshl_add_u64 v[178:179], v[236:237], 0, s[30:31]
	s_mov_b32 m0, s56
	s_nop 0
	global_load_lds_dwordx4 v[178:179], off
	s_waitcnt vmcnt(8)
	s_waitcnt lgkmcnt(0)
	s_barrier
	s_setprio 1
	s_waitcnt lgkmcnt(0)
	v_mfma_f32_16x16x32_bf16 v[60:63], v[144:147], v[192:195], v[60:63]
	v_mfma_f32_16x16x32_bf16 v[52:55], v[152:155], v[192:195], v[52:55]
	v_mfma_f32_16x16x32_bf16 v[44:47], v[144:147], v[200:203], v[44:47]
	v_mfma_f32_16x16x32_bf16 v[36:39], v[152:155], v[200:203], v[36:39]
	v_mfma_f32_16x16x32_bf16 v[28:31], v[144:147], v[208:211], v[28:31]
	v_mfma_f32_16x16x32_bf16 v[20:23], v[152:155], v[208:211], v[20:23]
	v_mfma_f32_16x16x32_bf16 v[12:15], v[144:147], v[216:219], v[12:15]
	v_mfma_f32_16x16x32_bf16 v[4:7], v[152:155], v[216:219], v[4:7]
	v_mfma_f32_16x16x32_bf16 v[60:63], v[148:151], v[196:199], v[60:63]
	v_mfma_f32_16x16x32_bf16 v[52:55], v[156:159], v[196:199], v[52:55]
	v_mfma_f32_16x16x32_bf16 v[44:47], v[148:151], v[204:207], v[44:47]
	v_mfma_f32_16x16x32_bf16 v[36:39], v[156:159], v[204:207], v[36:39]
	v_mfma_f32_16x16x32_bf16 v[28:31], v[148:151], v[212:215], v[28:31]
	v_mfma_f32_16x16x32_bf16 v[20:23], v[156:159], v[212:215], v[20:23]
	v_mfma_f32_16x16x32_bf16 v[12:15], v[148:151], v[220:223], v[12:15]
	v_mfma_f32_16x16x32_bf16 v[4:7], v[156:159], v[220:223], v[4:7]
	s_add_i32 s73, s73, 2
	s_setprio 0
	s_setprio 1
	v_mfma_f32_16x16x32_bf16 v[56:59], v[160:163], v[192:195], v[56:59]
	s_add_u32 s65, s65, 0x100
	v_mfma_f32_16x16x32_bf16 v[48:51], v[170:173], v[192:195], v[48:51]
	s_addc_u32 s69, s69, 0
	v_mfma_f32_16x16x32_bf16 v[40:43], v[160:163], v[200:203], v[40:43]
	s_add_u32 s48, s48, 0x100
	v_mfma_f32_16x16x32_bf16 v[32:35], v[170:173], v[200:203], v[32:35]
	s_addc_u32 s49, s49, 0
	v_mfma_f32_16x16x32_bf16 v[24:27], v[160:163], v[208:211], v[24:27]
	s_add_u32 s50, s48, 0xfffc0080
	v_mfma_f32_16x16x32_bf16 v[16:19], v[170:173], v[208:211], v[16:19]
	s_addc_u32 s51, s49, -1
	v_mfma_f32_16x16x32_bf16 v[8:11], v[160:163], v[216:219], v[8:11]
	s_add_i32 s74, 0, 0x10000
	v_mfma_f32_16x16x32_bf16 v[0:3], v[170:173], v[216:219], v[0:3]
	s_cmp_eq_u32 s73, 12
	v_mfma_f32_16x16x32_bf16 v[56:59], v[164:167], v[196:199], v[56:59]
	s_cselect_b32 s53, s43, s51
	v_mfma_f32_16x16x32_bf16 v[48:51], v[188:191], v[196:199], v[48:51]
	s_cselect_b32 s52, s61, s50
	v_mfma_f32_16x16x32_bf16 v[40:43], v[164:167], v[204:207], v[40:43]
	s_cselect_b32 s51, s41, s69
	v_mfma_f32_16x16x32_bf16 v[32:35], v[188:191], v[204:207], v[32:35]
	s_cselect_b32 s50, s64, s65
	v_mfma_f32_16x16x32_bf16 v[24:27], v[164:167], v[212:215], v[24:27]
	s_add_i32 s80, 0, 0x14000
	v_mfma_f32_16x16x32_bf16 v[16:19], v[188:191], v[212:215], v[16:19]
	v_add_u32_e32 v242, s74, v142
	v_mfma_f32_16x16x32_bf16 v[8:11], v[164:167], v[220:223], v[8:11]
	v_add_u32_e32 v178, s80, v142
	v_mfma_f32_16x16x32_bf16 v[0:3], v[188:191], v[220:223], v[0:3]
	s_setprio 0
	s_barrier

; #define PG8_STAGE(bufoff, gbase, voff) do { _Pragma("unroll") for (int _i = 0; _i < 2; ++_i) \
;         __builtin_amdgcn_global_load_lds((const unsigned*)((const char*)(gbase) + (voff)[_i]), (PG8_LAS unsigned*)(lds + (bufoff) + ldsw + _i * 8192), 16, 0, 0); } while (0)
; #define PG8_LDA(dst, b, h) do { _Pragma("unroll") for (int m = 0; m < 4; ++m) _Pragma("unroll") for (int k = 0; k < 2; ++k) dst[m][k] = *(const PG8_LAS bf16x8*)(lds + PG8_SA(b, h) + aoff + m * 2048 + k * 1024); } while (0)
; #define PG8_LDB(dst, b, h) do { _Pragma("unroll") for (int n = 0; n < 2; ++n) _Pragma("unroll") for (int k = 0; k < 2; ++k) dst[n][k] = *(const PG8_LAS bf16x8*)(lds + PG8_SB(b, h) + boff + n * 2048 + k * 1024); } while (0)
; #define PG8_SCHED __builtin_amdgcn_sched_barrier(0)
;     __host__ __device__ bool next(int i, Unit& u) const {
;         const long L = (long)i * G + c; if (L >= nwg) return false;
;         int wgid = (int)L; { const int q = nwg / NXCD, r = nwg % NXCD, xcd = wgid % NXCD, off = wgid / NXCD; wgid = (xcd < r ? xcd * (q + 1) : r * (q + 1) + (xcd - r) * q) + off; }
; template <class Epi, class Sched, bool ALIGN_EPI = false, bool SP2 = false>
; __device__ __forceinline__ void gemm_phase(PG8_LAS unsigned char* lds, const Gemm g, const Sched& S, const Epi& E) {
;     ...
;         const bool has_next = S.next(ui + 1, nxt);
;         const char* nA = has_next ? (const char*)g.A + (size_t)nxt.pm * tstepA : cA; const char* nB = has_next ? (const char*)g.Bt + (size_t)nxt.pn * tstep : cB;
;         for (int t = 0; t < nt; t += 2) {
;             const bool last = (t == nt - 2);
;             const char* a1 = cA + (size_t)(t + 1) * kstepA;
;             const char* a2 = last ? nA : cA + (size_t)(t + 2) * kstepA; const char* b2 = last ? nB : cB + (size_t)(t + 2) * kstep;
;             const char* a3 = a2 + kstepA; const char* b3 = b2 + kstep;
;             if (last && has_next) S.a_ready(nxt);
;             if constexpr (SP2) {
;             PG8_LDB(B0, 0, 0); PG8_LDB(B1, 0, 1); PG8_SCHED; PG8_LDA(At, 0, 0); PG8_STAGE(PG8_SA(1, 1), a1 + hstepA, voffA);
.LBB0_902:
	v_add_u32_e32 v244, 0x10000, v224
	v_add_u32_e32 v245, 0x14000, v224
	ds_read_b128 v[128:131], v244
	ds_read_b128 v[132:135], v244 offset:1024
	ds_read_b128 v[136:139], v244 offset:2048
	ds_read_b128 v[140:143], v244 offset:3072
	ds_read_b128 v[144:147], v245
	ds_read_b128 v[148:151], v245 offset:1024
	ds_read_b128 v[152:155], v245 offset:2048
	ds_read_b128 v[156:159], v245 offset:3072
	ds_read_b128 v[160:163], v225
	ds_read_b128 v[164:167], v225 offset:1024
	ds_read_b128 v[170:173], v225 offset:2048
	ds_read_b128 v[198:201], v225 offset:3072
	ds_read_b128 v[202:205], v225 offset:4096
	ds_read_b128 v[206:209], v225 offset:5120
	ds_read_b128 v[210:213], v225 offset:6144
	ds_read_b128 v[214:217], v225 offset:7168
	s_add_i32 s81, s81, 1
	s_mul_i32 s5, s81, s11
	s_mul_hi_u32 s6, s81, s10
	s_add_i32 s6, s6, s5
	s_mul_i32 s5, s81, s10
	s_add_u32 s38, s5, s93
	s_addc_u32 s39, s6, s9
	v_cmp_gt_i64_e32 vcc, s[38:39], v[182:183]
	v_cmp_lt_i64_e64 s[40:41], s[38:39], v[180:181]
	s_cbranch_vccnz .LBB0_908
	s_ashr_i32 s5, s38, 31
	s_lshr_b32 s5, s5, 29
	s_add_i32 s5, s38, s5
	s_and_b32 s6, s5, -8
	s_sub_i32 s6, s38, s6
	s_cmp_gt_i32 s6, -1
	s_mov_b64 s[38:39], -1
	s_cbranch_scc0 .LBB0_905
	s_lshl_b32 s7, s6, 7
	s_mov_b64 s[38:39], 0

; #define PG8_STAGE(bufoff, gbase, voff) do { _Pragma("unroll") for (int _i = 0; _i < 2; ++_i) \
;         __builtin_amdgcn_global_load_lds((const unsigned*)((const char*)(gbase) + (voff)[_i]), (PG8_LAS unsigned*)(lds + (bufoff) + ldsw + _i * 8192), 16, 0, 0); } while (0)
; #define PG8_LDA(dst, b, h) do { _Pragma("unroll") for (int m = 0; m < 4; ++m) _Pragma("unroll") for (int k = 0; k < 2; ++k) dst[m][k] = *(const PG8_LAS bf16x8*)(lds + PG8_SA(b, h) + aoff + m * 2048 + k * 1024); } while (0)
; #define PG8_LDB(dst, b, h) do { _Pragma("unroll") for (int n = 0; n < 2; ++n) _Pragma("unroll") for (int k = 0; k < 2; ++k) dst[n][k] = *(const PG8_LAS bf16x8*)(lds + PG8_SB(b, h) + boff + n * 2048 + k * 1024); } while (0)
; #define PG8_MMA(ai, bj, At, Bt) do { __builtin_amdgcn_s_setprio(1); _Pragma("unroll") for (int m = 0; m < 4; ++m) _Pragma("unroll") for (int n = 0; n < 2; ++n) _Pragma("unroll") for (int k = 0; k < 2; ++k) \
;         acc[ai][bj][m][n] = __builtin_amdgcn_mfma_f32_16x16x32_bf16(Bt[n][k], At[m][k], acc[ai][bj][m][n], 0, 0, 0); __builtin_amdgcn_s_setprio(0); } while (0)
; #define PG8_WAIT_V(n) asm volatile("s_waitcnt vmcnt(" #n ")" ::: "memory")
; #define PG8_BAR __builtin_amdgcn_s_barrier()
; template <class Epi, class Sched, bool ALIGN_EPI = false, bool SP2 = false>
; __device__ __forceinline__ void gemm_phase(PG8_LAS unsigned char* lds, const Gemm g, const Sched& S, const Epi& E) {
;     ...
;         for (int t = 0; t < nt; t += 2) {
;             const bool last = (t == nt - 2);
;             const char* a1 = cA + (size_t)(t + 1) * kstepA;
;             const char* a2 = last ? nA : cA + (size_t)(t + 2) * kstepA; const char* b2 = last ? nB : cB + (size_t)(t + 2) * kstep;
;             const char* a3 = a2 + kstepA; const char* b3 = b2 + kstep;
;             if (last && has_next) S.a_ready(nxt);
;             if constexpr (SP2) {
;             PG8_LDB(B0, 0, 0); PG8_LDB(B1, 0, 1); PG8_SCHED; PG8_LDA(At, 0, 0); PG8_STAGE(PG8_SA(1, 1), a1 + hstepA, voffA);
;             PG8_WAIT_V(8); PG8_WAIT_L(0); PG8_BAR; PG8_MMA(0, 0, At, B0); PG8_MMA(0, 1, At, B1); PG8_BAR; PG8_SCHED;
;             PG8_LDA(At, 0, 1); PG8_STAGE(PG8_SB(0, 0), b2, voffB); PG8_STAGE(PG8_SB(0, 1), b2 + hstep, voffB); PG8_STAGE(PG8_SA(0, 0), a2, voffA);
;             PG8_WAIT_V(8); PG8_WAIT_L(0); PG8_BAR; PG8_MMA(1, 0, At, B0); PG8_MMA(1, 1, At, B1); PG8_BAR; PG8_SCHED;
.LBB0_912:
	s_add_u32 s5, s52, 0x100
	s_addc_u32 s6, s53, 0
	s_add_u32 s40, s54, 0xb4000
	s_addc_u32 s41, s55, 0
	s_mov_b32 s7, -2
	s_add_u32 s52, s40, 0xfff54000
	s_addc_u32 s53, s41, -1
	s_cmp_eq_u32 s7, 40
	s_cselect_b32 s56, s48, s52
	s_cselect_b32 s57, s49, s53
	s_cselect_b32 s54, s50, s5
	s_cselect_b32 s55, s51, s6
	s_add_u32 s52, s56, 0x4000
	s_addc_u32 s53, s57, 0
	s_add_i32 s64, 0, 0x10000
	s_add_i32 s74, 0, 0x14000
	v_lshl_add_u64 v[178:179], s[40:41], 0, v[196:197]
	s_add_i32 m0, s3, 0xc000
	global_load_lds_dwordx4 v[178:179], off
	v_lshl_add_u64 v[178:179], s[40:41], 0, v[194:195]
	s_add_i32 m0, s3, 0xe000
	s_nop 0
	global_load_lds_dwordx4 v[178:179], off
	s_waitcnt vmcnt(8)
	s_waitcnt lgkmcnt(0)
	s_barrier
	s_setprio 1
	s_waitcnt lgkmcnt(0)
	v_mfma_f32_16x16x32_bf16 v[124:127], v[128:131], v[160:163], 0
	v_mfma_f32_16x16x32_bf16 v[120:123], v[136:139], v[160:163], 0
	v_mfma_f32_16x16x32_bf16 v[108:111], v[128:131], v[170:173], 0
	v_mfma_f32_16x16x32_bf16 v[104:107], v[136:139], v[170:173], 0
	v_mfma_f32_16x16x32_bf16 v[92:95], v[128:131], v[202:205], 0
	v_mfma_f32_16x16x32_bf16 v[88:91], v[136:139], v[202:205], 0
	v_mfma_f32_16x16x32_bf16 v[76:79], v[128:131], v[210:213], 0
	v_mfma_f32_16x16x32_bf16 v[72:75], v[136:139], v[210:213], 0
	v_mfma_f32_16x16x32_bf16 v[124:127], v[132:135], v[164:167], v[124:127]
	v_mfma_f32_16x16x32_bf16 v[120:123], v[140:143], v[164:167], v[120:123]
	v_mfma_f32_16x16x32_bf16 v[108:111], v[132:135], v[198:201], v[108:111]
	v_mfma_f32_16x16x32_bf16 v[104:107], v[140:143], v[198:201], v[104:107]
	v_mfma_f32_16x16x32_bf16 v[92:95], v[132:135], v[206:209], v[92:95]
	v_mfma_f32_16x16x32_bf16 v[88:91], v[140:143], v[206:209], v[88:91]
	v_mfma_f32_16x16x32_bf16 v[76:79], v[132:135], v[214:217], v[76:79]
	v_mfma_f32_16x16x32_bf16 v[72:75], v[140:143], v[214:217], v[72:75]
	s_setprio 0
	s_setprio 1
	v_mfma_f32_16x16x32_bf16 v[116:119], v[144:147], v[160:163], 0
	v_mfma_f32_16x16x32_bf16 v[112:115], v[152:155], v[160:163], 0
	v_mfma_f32_16x16x32_bf16 v[100:103], v[144:147], v[170:173], 0
	v_mfma_f32_16x16x32_bf16 v[96:99], v[152:155], v[170:173], 0
	v_mfma_f32_16x16x32_bf16 v[84:87], v[144:147], v[202:205], 0
	v_mfma_f32_16x16x32_bf16 v[80:83], v[152:155], v[202:205], 0
	v_mfma_f32_16x16x32_bf16 v[68:71], v[144:147], v[210:213], 0
	v_mfma_f32_16x16x32_bf16 v[64:67], v[152:155], v[210:213], 0
	v_mfma_f32_16x16x32_bf16 v[116:119], v[148:151], v[164:167], v[116:119]
	v_mfma_f32_16x16x32_bf16 v[112:115], v[156:159], v[164:167], v[112:115]
	v_mfma_f32_16x16x32_bf16 v[100:103], v[148:151], v[198:201], v[100:103]
	v_mfma_f32_16x16x32_bf16 v[96:99], v[156:159], v[198:201], v[96:99]
	v_mfma_f32_16x16x32_bf16 v[84:87], v[148:151], v[206:209], v[84:87]
	s_add_i32 s64, s64, s2
	v_mfma_f32_16x16x32_bf16 v[80:83], v[156:159], v[206:209], v[80:83]
	v_lshl_add_u64 v[178:179], s[54:55], 0, v[168:169]
	v_mfma_f32_16x16x32_bf16 v[68:71], v[148:151], v[214:217], v[68:71]
	s_mov_b32 m0, s64
	v_mfma_f32_16x16x32_bf16 v[64:67], v[156:159], v[214:217], v[64:67]
	s_setprio 0
	s_barrier
	ds_read_b128 v[160:163], v225 offset:16384
	ds_read_b128 v[164:167], v225 offset:17408
	ds_read_b128 v[170:173], v225 offset:18432
	ds_read_b128 v[198:201], v225 offset:19456
	ds_read_b128 v[202:205], v225 offset:20480
	ds_read_b128 v[206:209], v225 offset:21504
	ds_read_b128 v[210:213], v225 offset:22528
	ds_read_b128 v[214:217], v225 offset:23552
	global_load_lds_dwordx4 v[178:179], off
	s_add_i32 m0, s64, 0x2000
	s_add_u32 s64, s54, 0xb0000
	v_lshl_add_u64 v[218:219], s[54:55], 0, v[188:189]
	s_addc_u32 s65, s55, 0
	s_add_i32 s74, s74, s2
	global_load_lds_dwordx4 v[218:219], off
	v_lshl_add_u64 v[220:221], s[64:65], 0, v[168:169]
	s_mov_b32 m0, s74
	s_nop 0
	global_load_lds_dwordx4 v[220:221], off
	v_lshl_add_u64 v[220:221], s[64:65], 0, v[188:189]
	s_add_i32 m0, s74, 0x2000
	s_nop 0
	global_load_lds_dwordx4 v[220:221], off
	v_lshl_add_u64 v[220:221], s[56:57], 0, v[192:193]
	s_mov_b32 m0, s3
	s_nop 0
	global_load_lds_dwordx4 v[220:221], off
	v_lshl_add_u64 v[220:221], s[56:57], 0, v[190:191]
	s_mov_b32 m0, s34
	s_nop 0
	global_load_lds_dwordx4 v[220:221], off
	s_waitcnt vmcnt(8)
	s_waitcnt lgkmcnt(0)
	s_barrier
	s_setprio 1
	s_waitcnt lgkmcnt(0)
	v_mfma_f32_16x16x32_bf16 v[60:63], v[128:131], v[160:163], 0
	v_mfma_f32_16x16x32_bf16 v[56:59], v[136:139], v[160:163], 0
	v_mfma_f32_16x16x32_bf16 v[44:47], v[128:131], v[170:173], 0
	v_mfma_f32_16x16x32_bf16 v[40:43], v[136:139], v[170:173], 0
	v_mfma_f32_16x16x32_bf16 v[28:31], v[128:131], v[202:205], 0
	v_mfma_f32_16x16x32_bf16 v[24:27], v[136:139], v[202:205], 0
	v_mfma_f32_16x16x32_bf16 v[12:15], v[128:131], v[210:213], 0
	v_mfma_f32_16x16x32_bf16 v[8:11], v[136:139], v[210:213], 0
	v_mfma_f32_16x16x32_bf16 v[60:63], v[132:135], v[164:167], v[60:63]
	v_mfma_f32_16x16x32_bf16 v[56:59], v[140:143], v[164:167], v[56:59]
	v_mfma_f32_16x16x32_bf16 v[44:47], v[132:135], v[198:201], v[44:47]
	v_mfma_f32_16x16x32_bf16 v[40:43], v[140:143], v[198:201], v[40:43]
	v_mfma_f32_16x16x32_bf16 v[28:31], v[132:135], v[206:209], v[28:31]
	v_mfma_f32_16x16x32_bf16 v[24:27], v[140:143], v[206:209], v[24:27]
	v_mfma_f32_16x16x32_bf16 v[12:15], v[132:135], v[214:217], v[12:15]
	v_mfma_f32_16x16x32_bf16 v[8:11], v[140:143], v[214:217], v[8:11]
	s_setprio 0
	s_setprio 1
	v_mfma_f32_16x16x32_bf16 v[52:55], v[144:147], v[160:163], 0
	v_mfma_f32_16x16x32_bf16 v[48:51], v[152:155], v[160:163], 0
	v_mfma_f32_16x16x32_bf16 v[36:39], v[144:147], v[170:173], 0
	v_mfma_f32_16x16x32_bf16 v[32:35], v[152:155], v[170:173], 0
	v_mfma_f32_16x16x32_bf16 v[20:23], v[144:147], v[202:205], 0
	v_mfma_f32_16x16x32_bf16 v[16:19], v[152:155], v[202:205], 0
	v_mfma_f32_16x16x32_bf16 v[4:7], v[144:147], v[210:213], 0
	v_mfma_f32_16x16x32_bf16 v[0:3], v[152:155], v[210:213], 0
	v_mfma_f32_16x16x32_bf16 v[52:55], v[148:151], v[164:167], v[52:55]
	v_mfma_f32_16x16x32_bf16 v[48:51], v[156:159], v[164:167], v[48:51]
	v_mfma_f32_16x16x32_bf16 v[36:39], v[148:151], v[198:201], v[36:39]
	v_mfma_f32_16x16x32_bf16 v[32:35], v[156:159], v[198:201], v[32:35]
	s_add_i32 s64, 0, 0x18000
	v_mfma_f32_16x16x32_bf16 v[20:23], v[148:151], v[206:209], v[20:23]
	s_add_i32 s65, 0, 0x1c000
	v_mfma_f32_16x16x32_bf16 v[16:19], v[156:159], v[206:209], v[16:19]
	v_add_u32_e32 v240, s64, v224
	v_mfma_f32_16x16x32_bf16 v[4:7], v[148:151], v[214:217], v[4:7]
	v_add_u32_e32 v241, s65, v224
	v_mfma_f32_16x16x32_bf16 v[0:3], v[156:159], v[214:217], v[0:3]
	s_setprio 0
	s_barrier
; #define PG8_STAGE(bufoff, gbase, voff) do { _Pragma("unroll") for (int _i = 0; _i < 2; ++_i) \
;         __builtin_amdgcn_global_load_lds((const unsigned*)((const char*)(gbase) + (voff)[_i]), (PG8_LAS unsigned*)(lds + (bufoff) + ldsw + _i * 8192), 16, 0, 0); } while (0)
; #define PG8_LDA(dst, b, h) do { _Pragma("unroll") for (int m = 0; m < 4; ++m) _Pragma("unroll") for (int k = 0; k < 2; ++k) dst[m][k] = *(const PG8_LAS bf16x8*)(lds + PG8_SA(b, h) + aoff + m * 2048 + k * 1024); } while (0)
; #define PG8_LDB(dst, b, h) do { _Pragma("unroll") for (int n = 0; n < 2; ++n) _Pragma("unroll") for (int k = 0; k < 2; ++k) dst[n][k] = *(const PG8_LAS bf16x8*)(lds + PG8_SB(b, h) + boff + n * 2048 + k * 1024); } while (0)
; #define PG8_MMA(ai, bj, At, Bt) do { __builtin_amdgcn_s_setprio(1); _Pragma("unroll") for (int m = 0; m < 4; ++m) _Pragma("unroll") for (int n = 0; n < 2; ++n) _Pragma("unroll") for (int k = 0; k < 2; ++k) \
;         acc[ai][bj][m][n] = __builtin_amdgcn_mfma_f32_16x16x32_bf16(Bt[n][k], At[m][k], acc[ai][bj][m][n], 0, 0, 0); __builtin_amdgcn_s_setprio(0); } while (0)
; #define PG8_WAIT_V(n) asm volatile("s_waitcnt vmcnt(" #n ")" ::: "memory")
; #define PG8_WAIT_L(n) asm volatile("s_waitcnt lgkmcnt(" #n ")" ::: "memory")
; #define PG8_BAR __builtin_amdgcn_s_barrier()
; #define PG8_SCHED __builtin_amdgcn_sched_barrier(0)
; template <class Epi, class Sched, bool ALIGN_EPI = false, bool SP2 = false>
; __device__ __forceinline__ void gemm_phase(PG8_LAS unsigned char* lds, const Gemm g, const Sched& S, const Epi& E) {
;     ...
;             PG8_LDB(B0, 1, 0); PG8_LDB(B1, 1, 1); PG8_SCHED; PG8_LDA(At, 1, 0); PG8_STAGE(PG8_SA(0, 1), a2 + hstepA, voffA);
;             PG8_WAIT_V(8); PG8_WAIT_L(0); PG8_BAR; PG8_MMA(0, 0, At, B0); PG8_MMA(0, 1, At, B1); PG8_BAR; PG8_SCHED;
	ds_read_b128 v[128:131], v240
	ds_read_b128 v[132:135], v240 offset:1024
	ds_read_b128 v[136:139], v240 offset:2048
	ds_read_b128 v[140:143], v240 offset:3072
	ds_read_b128 v[144:147], v241
	ds_read_b128 v[148:151], v241 offset:1024
	ds_read_b128 v[152:155], v241 offset:2048
	ds_read_b128 v[156:159], v241 offset:3072
	s_add_u32 s56, s56, 0xb0000
	s_addc_u32 s57, s57, 0
	s_mov_b32 m0, s35
	v_lshl_add_u64 v[220:221], s[56:57], 0, v[192:193]
	ds_read_b128 v[160:163], v225 offset:32768
	ds_read_b128 v[164:167], v225 offset:33792
	ds_read_b128 v[170:173], v225 offset:34816
	ds_read_b128 v[198:201], v225 offset:35840
	ds_read_b128 v[202:205], v225 offset:36864
	ds_read_b128 v[206:209], v225 offset:37888
	ds_read_b128 v[210:213], v225 offset:38912
	ds_read_b128 v[214:217], v225 offset:39936
	global_load_lds_dwordx4 v[220:221], off
	v_lshl_add_u64 v[220:221], s[56:57], 0, v[190:191]
	s_mov_b32 m0, s60
	s_nop 0
	global_load_lds_dwordx4 v[220:221], off
	s_waitcnt vmcnt(8)
	s_waitcnt lgkmcnt(0)
	s_barrier
	s_setprio 1
	s_waitcnt lgkmcnt(0)
	v_mfma_f32_16x16x32_bf16 v[124:127], v[128:131], v[160:163], v[124:127]
	v_mfma_f32_16x16x32_bf16 v[120:123], v[136:139], v[160:163], v[120:123]
	v_mfma_f32_16x16x32_bf16 v[108:111], v[128:131], v[170:173], v[108:111]
	v_mfma_f32_16x16x32_bf16 v[104:107], v[136:139], v[170:173], v[104:107]
	v_mfma_f32_16x16x32_bf16 v[92:95], v[128:131], v[202:205], v[92:95]
	v_mfma_f32_16x16x32_bf16 v[88:91], v[136:139], v[202:205], v[88:91]
	v_mfma_f32_16x16x32_bf16 v[76:79], v[128:131], v[210:213], v[76:79]
	v_mfma_f32_16x16x32_bf16 v[72:75], v[136:139], v[210:213], v[72:75]
	v_mfma_f32_16x16x32_bf16 v[124:127], v[132:135], v[164:167], v[124:127]
	v_mfma_f32_16x16x32_bf16 v[120:123], v[140:143], v[164:167], v[120:123]
	v_mfma_f32_16x16x32_bf16 v[108:111], v[132:135], v[198:201], v[108:111]
	v_mfma_f32_16x16x32_bf16 v[104:107], v[140:143], v[198:201], v[104:107]
	v_mfma_f32_16x16x32_bf16 v[92:95], v[132:135], v[206:209], v[92:95]
	v_mfma_f32_16x16x32_bf16 v[88:91], v[140:143], v[206:209], v[88:91]
	v_mfma_f32_16x16x32_bf16 v[76:79], v[132:135], v[214:217], v[76:79]
	v_mfma_f32_16x16x32_bf16 v[72:75], v[140:143], v[214:217], v[72:75]
	s_setprio 0
	s_setprio 1
	v_mfma_f32_16x16x32_bf16 v[116:119], v[144:147], v[160:163], v[116:119]
	v_mfma_f32_16x16x32_bf16 v[112:115], v[152:155], v[160:163], v[112:115]
	v_mfma_f32_16x16x32_bf16 v[100:103], v[144:147], v[170:173], v[100:103]
	v_mfma_f32_16x16x32_bf16 v[96:99], v[152:155], v[170:173], v[96:99]
	v_mfma_f32_16x16x32_bf16 v[84:87], v[144:147], v[202:205], v[84:87]
	v_mfma_f32_16x16x32_bf16 v[80:83], v[152:155], v[202:205], v[80:83]
	v_mfma_f32_16x16x32_bf16 v[68:71], v[144:147], v[210:213], v[68:71]
	v_mfma_f32_16x16x32_bf16 v[64:67], v[152:155], v[210:213], v[64:67]
	v_mfma_f32_16x16x32_bf16 v[116:119], v[148:151], v[164:167], v[116:119]
	v_mfma_f32_16x16x32_bf16 v[112:115], v[156:159], v[164:167], v[112:115]
	v_mfma_f32_16x16x32_bf16 v[100:103], v[148:151], v[198:201], v[100:103]
	v_mfma_f32_16x16x32_bf16 v[96:99], v[156:159], v[198:201], v[96:99]
	v_mfma_f32_16x16x32_bf16 v[84:87], v[148:151], v[206:209], v[84:87]
	s_add_i32 s56, s64, s2
	v_mfma_f32_16x16x32_bf16 v[80:83], v[156:159], v[206:209], v[80:83]
	v_lshl_add_u64 v[178:179], v[178:179], 0, s[30:31]
	v_mfma_f32_16x16x32_bf16 v[68:71], v[148:151], v[214:217], v[68:71]
	s_mov_b32 m0, s56
	v_mfma_f32_16x16x32_bf16 v[64:67], v[156:159], v[214:217], v[64:67]
	s_setprio 0
	s_barrier
; #define PG8_STAGE(bufoff, gbase, voff) do { _Pragma("unroll") for (int _i = 0; _i < 2; ++_i) \
;         __builtin_amdgcn_global_load_lds((const unsigned*)((const char*)(gbase) + (voff)[_i]), (PG8_LAS unsigned*)(lds + (bufoff) + ldsw + _i * 8192), 16, 0, 0); } while (0)
; #define PG8_LDA(dst, b, h) do { _Pragma("unroll") for (int m = 0; m < 4; ++m) _Pragma("unroll") for (int k = 0; k < 2; ++k) dst[m][k] = *(const PG8_LAS bf16x8*)(lds + PG8_SA(b, h) + aoff + m * 2048 + k * 1024); } while (0)
; #define PG8_MMA(ai, bj, At, Bt) do { __builtin_amdgcn_s_setprio(1); _Pragma("unroll") for (int m = 0; m < 4; ++m) _Pragma("unroll") for (int n = 0; n < 2; ++n) _Pragma("unroll") for (int k = 0; k < 2; ++k) \
;         acc[ai][bj][m][n] = __builtin_amdgcn_mfma_f32_16x16x32_bf16(Bt[n][k], At[m][k], acc[ai][bj][m][n], 0, 0, 0); __builtin_amdgcn_s_setprio(0); } while (0)
; #define PG8_WAIT_V(n) asm volatile("s_waitcnt vmcnt(" #n ")" ::: "memory")
; #define PG8_WAIT_L(n) asm volatile("s_waitcnt lgkmcnt(" #n ")" ::: "memory")
; #define PG8_BAR __builtin_amdgcn_s_barrier()
; #define PG8_SCHED __builtin_amdgcn_sched_barrier(0)
; template <class Epi, class Sched, bool ALIGN_EPI = false, bool SP2 = false>
; __device__ __forceinline__ void gemm_phase(PG8_LAS unsigned char* lds, const Gemm g, const Sched& S, const Epi& E) {
;     ...
;         for (int t = 0; t < nt; t += 2) {
;             const bool last = (t == nt - 2);
;             const char* a1 = cA + (size_t)(t + 1) * kstepA;
;             const char* a2 = last ? nA : cA + (size_t)(t + 2) * kstepA; const char* b2 = last ? nB : cB + (size_t)(t + 2) * kstep;
;             const char* a3 = a2 + kstepA; const char* b3 = b2 + kstep;
;     ...
;             PG8_LDA(At, 1, 1); PG8_STAGE(PG8_SB(1, 0), b3, voffB); PG8_STAGE(PG8_SB(1, 1), b3 + hstep, voffB); PG8_STAGE(PG8_SA(1, 0), a3, voffA);
;             PG8_WAIT_V(8); PG8_WAIT_L(0); PG8_BAR; PG8_MMA(1, 0, At, B0); PG8_MMA(1, 1, At, B1); PG8_BAR; PG8_SCHED;
	ds_read_b128 v[160:163], v225 offset:49152
	ds_read_b128 v[164:167], v225 offset:50176
	ds_read_b128 v[170:173], v225 offset:51200
	ds_read_b128 v[198:201], v225 offset:52224
	ds_read_b128 v[202:205], v225 offset:53248
	ds_read_b128 v[206:209], v225 offset:54272
	ds_read_b128 v[210:213], v225 offset:55296
	ds_read_b128 v[214:217], v225 offset:56320
	global_load_lds_dwordx4 v[178:179], off
	s_add_i32 m0, s56, 0x2000
	s_add_u32 s54, s54, 0xb0080
	v_lshl_add_u64 v[178:179], v[218:219], 0, s[30:31]
	s_addc_u32 s55, s55, 0
	s_add_i32 s56, s65, s2
	global_load_lds_dwordx4 v[178:179], off
	v_lshl_add_u64 v[178:179], s[54:55], 0, v[168:169]
	s_mov_b32 m0, s56
	s_nop 0
	global_load_lds_dwordx4 v[178:179], off
	v_lshl_add_u64 v[178:179], s[54:55], 0, v[188:189]
	s_add_i32 m0, s56, 0x2000
	s_nop 0
	global_load_lds_dwordx4 v[178:179], off
	v_lshl_add_u64 v[178:179], s[52:53], 0, v[192:193]
	s_mov_b32 m0, s69
	s_nop 0
	global_load_lds_dwordx4 v[178:179], off
	v_lshl_add_u64 v[178:179], s[52:53], 0, v[190:191]
	s_mov_b32 m0, s73
	s_nop 0
	global_load_lds_dwordx4 v[178:179], off
	s_waitcnt vmcnt(8)
	s_waitcnt lgkmcnt(0)
	s_barrier
	s_setprio 1
	s_waitcnt lgkmcnt(0)
	v_mfma_f32_16x16x32_bf16 v[60:63], v[128:131], v[160:163], v[60:63]
	v_mfma_f32_16x16x32_bf16 v[56:59], v[136:139], v[160:163], v[56:59]
	v_mfma_f32_16x16x32_bf16 v[44:47], v[128:131], v[170:173], v[44:47]
	v_mfma_f32_16x16x32_bf16 v[40:43], v[136:139], v[170:173], v[40:43]
	v_mfma_f32_16x16x32_bf16 v[28:31], v[128:131], v[202:205], v[28:31]
	v_mfma_f32_16x16x32_bf16 v[24:27], v[136:139], v[202:205], v[24:27]
	v_mfma_f32_16x16x32_bf16 v[12:15], v[128:131], v[210:213], v[12:15]
	v_mfma_f32_16x16x32_bf16 v[8:11], v[136:139], v[210:213], v[8:11]
	v_mfma_f32_16x16x32_bf16 v[60:63], v[132:135], v[164:167], v[60:63]
	v_mfma_f32_16x16x32_bf16 v[56:59], v[140:143], v[164:167], v[56:59]
	v_mfma_f32_16x16x32_bf16 v[44:47], v[132:135], v[198:201], v[44:47]
	v_mfma_f32_16x16x32_bf16 v[40:43], v[140:143], v[198:201], v[40:43]
	v_mfma_f32_16x16x32_bf16 v[28:31], v[132:135], v[206:209], v[28:31]
	v_mfma_f32_16x16x32_bf16 v[24:27], v[140:143], v[206:209], v[24:27]
	s_add_i32 s7, s7, 2
	v_mfma_f32_16x16x32_bf16 v[12:15], v[132:135], v[214:217], v[12:15]
	s_add_u32 s5, s5, 0x100
	v_mfma_f32_16x16x32_bf16 v[8:11], v[140:143], v[214:217], v[8:11]
	s_addc_u32 s6, s6, 0
	s_setprio 0
	s_setprio 1
	v_mfma_f32_16x16x32_bf16 v[52:55], v[144:147], v[160:163], v[52:55]
	s_add_u32 s40, s40, 0x8000
	v_mfma_f32_16x16x32_bf16 v[48:51], v[152:155], v[160:163], v[48:51]
	s_addc_u32 s41, s41, 0
	v_mfma_f32_16x16x32_bf16 v[36:39], v[144:147], v[170:173], v[36:39]
	s_add_u32 s52, s40, 0xfff54000
	v_mfma_f32_16x16x32_bf16 v[32:35], v[152:155], v[170:173], v[32:35]
	s_addc_u32 s53, s41, -1
	v_mfma_f32_16x16x32_bf16 v[20:23], v[144:147], v[202:205], v[20:23]
	s_cmp_eq_u32 s7, 40
	v_mfma_f32_16x16x32_bf16 v[16:19], v[152:155], v[202:205], v[16:19]
	s_cselect_b32 s56, s48, s52
	v_mfma_f32_16x16x32_bf16 v[4:7], v[144:147], v[210:213], v[4:7]
	s_cselect_b32 s57, s49, s53
	v_mfma_f32_16x16x32_bf16 v[0:3], v[152:155], v[210:213], v[0:3]
	s_cselect_b32 s54, s50, s5
	v_mfma_f32_16x16x32_bf16 v[52:55], v[148:151], v[164:167], v[52:55]
	s_cselect_b32 s55, s51, s6
	v_mfma_f32_16x16x32_bf16 v[48:51], v[156:159], v[164:167], v[48:51]
	s_add_u32 s52, s56, 0x4000
	v_mfma_f32_16x16x32_bf16 v[36:39], v[148:151], v[198:201], v[36:39]
	s_addc_u32 s53, s57, 0
	v_mfma_f32_16x16x32_bf16 v[32:35], v[156:159], v[198:201], v[32:35]
	s_add_i32 s64, 0, 0x10000
	v_mfma_f32_16x16x32_bf16 v[20:23], v[148:151], v[206:209], v[20:23]
	s_add_i32 s74, 0, 0x14000
	v_mfma_f32_16x16x32_bf16 v[16:19], v[156:159], v[206:209], v[16:19]
	v_add_u32_e32 v242, s64, v224
	v_mfma_f32_16x16x32_bf16 v[4:7], v[148:151], v[214:217], v[4:7]
	v_add_u32_e32 v243, s74, v224
	v_mfma_f32_16x16x32_bf16 v[0:3], v[156:159], v[214:217], v[0:3]
	s_setprio 0
	s_barrier

; #define PG8_STAGE(bufoff, gbase, voff) do { _Pragma("unroll") for (int _i = 0; _i < 2; ++_i) \
;         __builtin_amdgcn_global_load_lds((const unsigned*)((const char*)(gbase) + (voff)[_i]), (PG8_LAS unsigned*)(lds + (bufoff) + ldsw + _i * 8192), 16, 0, 0); } while (0)
; #define PG8_LDA(dst, b, h) do { _Pragma("unroll") for (int m = 0; m < 4; ++m) _Pragma("unroll") for (int k = 0; k < 2; ++k) dst[m][k] = *(const PG8_LAS bf16x8*)(lds + PG8_SA(b, h) + aoff + m * 2048 + k * 1024); } while (0)
; #define PG8_LDB(dst, b, h) do { _Pragma("unroll") for (int n = 0; n < 2; ++n) _Pragma("unroll") for (int k = 0; k < 2; ++k) dst[n][k] = *(const PG8_LAS bf16x8*)(lds + PG8_SB(b, h) + boff + n * 2048 + k * 1024); } while (0)
; #define PG8_SCHED __builtin_amdgcn_sched_barrier(0)
;     __host__ __device__ bool next(int i, Unit& u) const {
;         const long L = (long)i * G + c; if (L >= nwg) return false;
;         int wgid = (int)L; { const int q = nwg / NXCD, r = nwg % NXCD, xcd = wgid % NXCD, off = wgid / NXCD; wgid = (xcd < r ? xcd * (q + 1) : r * (q + 1) + (xcd - r) * q) + off; }
; template <class Epi, class Sched, bool ALIGN_EPI = false, bool SP2 = false>
; __device__ __forceinline__ void gemm_phase(PG8_LAS unsigned char* lds, const Gemm g, const Sched& S, const Epi& E) {
;     ...
;         const bool has_next = S.next(ui + 1, nxt);
;         const char* nA = has_next ? (const char*)g.A + (size_t)nxt.pm * tstepA : cA; const char* nB = has_next ? (const char*)g.Bt + (size_t)nxt.pn * tstep : cB;
;         for (int t = 0; t < nt; t += 2) {
;             const bool last = (t == nt - 2);
;             const char* a1 = cA + (size_t)(t + 1) * kstepA;
;             const char* a2 = last ? nA : cA + (size_t)(t + 2) * kstepA; const char* b2 = last ? nB : cB + (size_t)(t + 2) * kstep;
;             const char* a3 = a2 + kstepA; const char* b3 = b2 + kstep;
;             if (last && has_next) S.a_ready(nxt);
;             if constexpr (SP2) {
;             PG8_LDB(B0, 0, 0); PG8_LDB(B1, 0, 1); PG8_SCHED; PG8_LDA(At, 0, 0); PG8_STAGE(PG8_SA(1, 1), a1 + hstepA, voffA);
.LBB0_963:
	v_add_u32_e32 v244, 0x10000, v236
	v_add_u32_e32 v245, 0x14000, v236
	ds_read_b128 v[128:131], v244
	ds_read_b128 v[132:135], v244 offset:1024
	ds_read_b128 v[136:139], v244 offset:2048
	ds_read_b128 v[140:143], v244 offset:3072
	ds_read_b128 v[144:147], v245
	ds_read_b128 v[148:151], v245 offset:1024
	ds_read_b128 v[152:155], v245 offset:2048
	ds_read_b128 v[156:159], v245 offset:3072
	ds_read_b128 v[160:163], v237
	ds_read_b128 v[164:167], v237 offset:1024
	ds_read_b128 v[170:173], v237 offset:2048
	ds_read_b128 v[198:201], v237 offset:3072
	ds_read_b128 v[202:205], v237 offset:4096
	ds_read_b128 v[206:209], v237 offset:5120
	ds_read_b128 v[210:213], v237 offset:6144
	ds_read_b128 v[214:217], v237 offset:7168
	s_add_i32 s62, s62, 1
	s_mul_i32 s5, s62, s11
	s_mul_hi_u32 s6, s62, s10
	s_add_i32 s6, s6, s5
	s_mul_i32 s5, s62, s10
	v_readlane_b32 s7, v255, 3
	s_add_u32 s36, s5, s7
	s_addc_u32 s37, s6, s9
	v_cmp_gt_i64_e32 vcc, s[36:37], v[182:183]
	v_cmp_lt_i64_e64 s[38:39], s[36:37], v[180:181]
	s_cbranch_vccnz .LBB0_969
	s_ashr_i32 s5, s36, 31
	s_lshr_b32 s5, s5, 29
	s_add_i32 s5, s36, s5
	s_and_b32 s6, s5, -8
	s_sub_i32 s6, s36, s6
	s_cmp_gt_i32 s6, -1
	s_mov_b64 s[36:37], -1
	s_cbranch_scc0 .LBB0_966
	s_lshl_b32 s7, s6, 7
	s_mov_b64 s[36:37], 0

; #define PG8_STAGE(bufoff, gbase, voff) do { _Pragma("unroll") for (int _i = 0; _i < 2; ++_i) \
;         __builtin_amdgcn_global_load_lds((const unsigned*)((const char*)(gbase) + (voff)[_i]), (PG8_LAS unsigned*)(lds + (bufoff) + ldsw + _i * 8192), 16, 0, 0); } while (0)
; #define PG8_LDA(dst, b, h) do { _Pragma("unroll") for (int m = 0; m < 4; ++m) _Pragma("unroll") for (int k = 0; k < 2; ++k) dst[m][k] = *(const PG8_LAS bf16x8*)(lds + PG8_SA(b, h) + aoff + m * 2048 + k * 1024); } while (0)
; #define PG8_LDB(dst, b, h) do { _Pragma("unroll") for (int n = 0; n < 2; ++n) _Pragma("unroll") for (int k = 0; k < 2; ++k) dst[n][k] = *(const PG8_LAS bf16x8*)(lds + PG8_SB(b, h) + boff + n * 2048 + k * 1024); } while (0)
; #define PG8_MMA(ai, bj, At, Bt) do { __builtin_amdgcn_s_setprio(1); _Pragma("unroll") for (int m = 0; m < 4; ++m) _Pragma("unroll") for (int n = 0; n < 2; ++n) _Pragma("unroll") for (int k = 0; k < 2; ++k) \
;         acc[ai][bj][m][n] = __builtin_amdgcn_mfma_f32_16x16x32_bf16(Bt[n][k], At[m][k], acc[ai][bj][m][n], 0, 0, 0); __builtin_amdgcn_s_setprio(0); } while (0)
; #define PG8_WAIT_V(n) asm volatile("s_waitcnt vmcnt(" #n ")" ::: "memory")
; #define PG8_BAR __builtin_amdgcn_s_barrier()
; template <class Epi, class Sched, bool ALIGN_EPI = false, bool SP2 = false>
; __device__ __forceinline__ void gemm_phase(PG8_LAS unsigned char* lds, const Gemm g, const Sched& S, const Epi& E) {
;     ...
;         for (int t = 0; t < nt; t += 2) {
;             const bool last = (t == nt - 2);
;             const char* a1 = cA + (size_t)(t + 1) * kstepA;
;             const char* a2 = last ? nA : cA + (size_t)(t + 2) * kstepA; const char* b2 = last ? nB : cB + (size_t)(t + 2) * kstep;
;             const char* a3 = a2 + kstepA; const char* b3 = b2 + kstep;
;             if (last && has_next) S.a_ready(nxt);
;             if constexpr (SP2) {
;             PG8_LDB(B0, 0, 0); PG8_LDB(B1, 0, 1); PG8_SCHED; PG8_LDA(At, 0, 0); PG8_STAGE(PG8_SA(1, 1), a1 + hstepA, voffA);
;             PG8_WAIT_V(8); PG8_WAIT_L(0); PG8_BAR; PG8_MMA(0, 0, At, B0); PG8_MMA(0, 1, At, B1); PG8_BAR; PG8_SCHED;
;             PG8_LDA(At, 0, 1); PG8_STAGE(PG8_SB(0, 0), b2, voffB); PG8_STAGE(PG8_SB(0, 1), b2 + hstep, voffB); PG8_STAGE(PG8_SA(0, 0), a2, voffA);
;             PG8_WAIT_V(8); PG8_WAIT_L(0); PG8_BAR; PG8_MMA(1, 0, At, B0); PG8_MMA(1, 1, At, B1); PG8_BAR; PG8_SCHED;
.LBB0_973:
	s_add_u32 s5, s48, 0x100
	s_addc_u32 s6, s49, 0
	s_add_u32 s38, s50, 0xb4000
	s_addc_u32 s39, s51, 0
	s_mov_b32 s7, -2
	s_add_u32 s48, s38, 0xfff54000
	s_addc_u32 s49, s39, -1
	s_cmp_eq_u32 s7, 40
	s_cselect_b32 s52, s44, s48
	s_cselect_b32 s53, s45, s49
	s_cselect_b32 s50, s46, s5
	s_cselect_b32 s51, s47, s6
	s_add_u32 s48, s52, 0x4000
	s_addc_u32 s49, s53, 0
	s_add_i32 s64, 0, 0x10000
	s_add_i32 s74, 0, 0x14000
	v_lshl_add_u64 v[178:179], s[38:39], 0, v[196:197]
	s_add_i32 m0, s3, 0xc000
	global_load_lds_dwordx4 v[178:179], off
	v_lshl_add_u64 v[178:179], s[38:39], 0, v[194:195]
	s_add_i32 m0, s3, 0xe000
	s_nop 0
	global_load_lds_dwordx4 v[178:179], off
	s_waitcnt vmcnt(8)
	s_waitcnt lgkmcnt(0)
	s_barrier
	s_setprio 1
	s_waitcnt lgkmcnt(0)
	v_mfma_f32_16x16x32_bf16 v[124:127], v[128:131], v[160:163], 0
	v_mfma_f32_16x16x32_bf16 v[120:123], v[136:139], v[160:163], 0
	v_mfma_f32_16x16x32_bf16 v[108:111], v[128:131], v[170:173], 0
	v_mfma_f32_16x16x32_bf16 v[104:107], v[136:139], v[170:173], 0
	v_mfma_f32_16x16x32_bf16 v[92:95], v[128:131], v[202:205], 0
	v_mfma_f32_16x16x32_bf16 v[88:91], v[136:139], v[202:205], 0
	v_mfma_f32_16x16x32_bf16 v[76:79], v[128:131], v[210:213], 0
	v_mfma_f32_16x16x32_bf16 v[72:75], v[136:139], v[210:213], 0
	v_mfma_f32_16x16x32_bf16 v[124:127], v[132:135], v[164:167], v[124:127]
	v_mfma_f32_16x16x32_bf16 v[120:123], v[140:143], v[164:167], v[120:123]
	v_mfma_f32_16x16x32_bf16 v[108:111], v[132:135], v[198:201], v[108:111]
	v_mfma_f32_16x16x32_bf16 v[104:107], v[140:143], v[198:201], v[104:107]
	v_mfma_f32_16x16x32_bf16 v[92:95], v[132:135], v[206:209], v[92:95]
	v_mfma_f32_16x16x32_bf16 v[88:91], v[140:143], v[206:209], v[88:91]
	v_mfma_f32_16x16x32_bf16 v[76:79], v[132:135], v[214:217], v[76:79]
	v_mfma_f32_16x16x32_bf16 v[72:75], v[140:143], v[214:217], v[72:75]
	s_setprio 0
	s_setprio 1
	v_mfma_f32_16x16x32_bf16 v[116:119], v[144:147], v[160:163], 0
	v_mfma_f32_16x16x32_bf16 v[112:115], v[152:155], v[160:163], 0
	v_mfma_f32_16x16x32_bf16 v[100:103], v[144:147], v[170:173], 0
	v_mfma_f32_16x16x32_bf16 v[96:99], v[152:155], v[170:173], 0
	v_mfma_f32_16x16x32_bf16 v[84:87], v[144:147], v[202:205], 0
	v_mfma_f32_16x16x32_bf16 v[80:83], v[152:155], v[202:205], 0
	v_mfma_f32_16x16x32_bf16 v[68:71], v[144:147], v[210:213], 0
	v_mfma_f32_16x16x32_bf16 v[64:67], v[152:155], v[210:213], 0
	v_mfma_f32_16x16x32_bf16 v[116:119], v[148:151], v[164:167], v[116:119]
	v_mfma_f32_16x16x32_bf16 v[112:115], v[156:159], v[164:167], v[112:115]
	v_mfma_f32_16x16x32_bf16 v[100:103], v[148:151], v[198:201], v[100:103]
	v_mfma_f32_16x16x32_bf16 v[96:99], v[156:159], v[198:201], v[96:99]
	v_mfma_f32_16x16x32_bf16 v[84:87], v[148:151], v[206:209], v[84:87]
	s_add_i32 s64, s64, s2
	v_mfma_f32_16x16x32_bf16 v[80:83], v[156:159], v[206:209], v[80:83]
	v_lshl_add_u64 v[178:179], s[50:51], 0, v[168:169]
	v_mfma_f32_16x16x32_bf16 v[68:71], v[148:151], v[214:217], v[68:71]
	s_mov_b32 m0, s64
	v_mfma_f32_16x16x32_bf16 v[64:67], v[156:159], v[214:217], v[64:67]
	s_setprio 0
	s_barrier
	ds_read_b128 v[160:163], v237 offset:16384
	ds_read_b128 v[164:167], v237 offset:17408
	ds_read_b128 v[170:173], v237 offset:18432
	ds_read_b128 v[198:201], v237 offset:19456
	ds_read_b128 v[202:205], v237 offset:20480
	ds_read_b128 v[206:209], v237 offset:21504
	ds_read_b128 v[210:213], v237 offset:22528
	ds_read_b128 v[214:217], v237 offset:23552
	global_load_lds_dwordx4 v[178:179], off
	s_add_i32 m0, s64, 0x2000
	s_add_u32 s64, s50, 0xb0000
	v_lshl_add_u64 v[218:219], s[50:51], 0, v[188:189]
	s_addc_u32 s65, s51, 0
	s_add_i32 s74, s74, s2
	global_load_lds_dwordx4 v[218:219], off
	v_lshl_add_u64 v[220:221], s[64:65], 0, v[168:169]
	s_mov_b32 m0, s74
	s_nop 0
	global_load_lds_dwordx4 v[220:221], off
	v_lshl_add_u64 v[220:221], s[64:65], 0, v[188:189]
	s_add_i32 m0, s74, 0x2000
	s_nop 0
	global_load_lds_dwordx4 v[220:221], off
	v_lshl_add_u64 v[220:221], s[52:53], 0, v[192:193]
	s_mov_b32 m0, s3
	s_nop 0
	global_load_lds_dwordx4 v[220:221], off
	v_lshl_add_u64 v[220:221], s[52:53], 0, v[190:191]
	s_mov_b32 m0, s34
	s_nop 0
	global_load_lds_dwordx4 v[220:221], off
	s_waitcnt vmcnt(8)
	s_waitcnt lgkmcnt(0)
	s_barrier
	s_setprio 1
	s_waitcnt lgkmcnt(0)
	v_mfma_f32_16x16x32_bf16 v[60:63], v[128:131], v[160:163], 0
	v_mfma_f32_16x16x32_bf16 v[56:59], v[136:139], v[160:163], 0
	v_mfma_f32_16x16x32_bf16 v[44:47], v[128:131], v[170:173], 0
	v_mfma_f32_16x16x32_bf16 v[40:43], v[136:139], v[170:173], 0
	v_mfma_f32_16x16x32_bf16 v[28:31], v[128:131], v[202:205], 0
	v_mfma_f32_16x16x32_bf16 v[24:27], v[136:139], v[202:205], 0
	v_mfma_f32_16x16x32_bf16 v[12:15], v[128:131], v[210:213], 0
	v_mfma_f32_16x16x32_bf16 v[8:11], v[136:139], v[210:213], 0
	v_mfma_f32_16x16x32_bf16 v[60:63], v[132:135], v[164:167], v[60:63]
	v_mfma_f32_16x16x32_bf16 v[56:59], v[140:143], v[164:167], v[56:59]
	v_mfma_f32_16x16x32_bf16 v[44:47], v[132:135], v[198:201], v[44:47]
	v_mfma_f32_16x16x32_bf16 v[40:43], v[140:143], v[198:201], v[40:43]
	v_mfma_f32_16x16x32_bf16 v[28:31], v[132:135], v[206:209], v[28:31]
	v_mfma_f32_16x16x32_bf16 v[24:27], v[140:143], v[206:209], v[24:27]
	v_mfma_f32_16x16x32_bf16 v[12:15], v[132:135], v[214:217], v[12:15]
	v_mfma_f32_16x16x32_bf16 v[8:11], v[140:143], v[214:217], v[8:11]
	s_setprio 0
	s_setprio 1
	v_mfma_f32_16x16x32_bf16 v[52:55], v[144:147], v[160:163], 0
	v_mfma_f32_16x16x32_bf16 v[48:51], v[152:155], v[160:163], 0
	v_mfma_f32_16x16x32_bf16 v[36:39], v[144:147], v[170:173], 0
	v_mfma_f32_16x16x32_bf16 v[32:35], v[152:155], v[170:173], 0
	v_mfma_f32_16x16x32_bf16 v[20:23], v[144:147], v[202:205], 0
	v_mfma_f32_16x16x32_bf16 v[16:19], v[152:155], v[202:205], 0
	v_mfma_f32_16x16x32_bf16 v[4:7], v[144:147], v[210:213], 0
	v_mfma_f32_16x16x32_bf16 v[0:3], v[152:155], v[210:213], 0
	v_mfma_f32_16x16x32_bf16 v[52:55], v[148:151], v[164:167], v[52:55]
	v_mfma_f32_16x16x32_bf16 v[48:51], v[156:159], v[164:167], v[48:51]
	v_mfma_f32_16x16x32_bf16 v[36:39], v[148:151], v[198:201], v[36:39]
	v_mfma_f32_16x16x32_bf16 v[32:35], v[156:159], v[198:201], v[32:35]
	s_add_i32 s64, 0, 0x18000
	v_mfma_f32_16x16x32_bf16 v[20:23], v[148:151], v[206:209], v[20:23]
	s_add_i32 s65, 0, 0x1c000
	v_mfma_f32_16x16x32_bf16 v[16:19], v[156:159], v[206:209], v[16:19]
	v_add_u32_e32 v240, s64, v236
	v_mfma_f32_16x16x32_bf16 v[4:7], v[148:151], v[214:217], v[4:7]
	v_add_u32_e32 v241, s65, v236
	v_mfma_f32_16x16x32_bf16 v[0:3], v[156:159], v[214:217], v[0:3]
	s_setprio 0
	s_barrier
; #define PG8_STAGE(bufoff, gbase, voff) do { _Pragma("unroll") for (int _i = 0; _i < 2; ++_i) \
;         __builtin_amdgcn_global_load_lds((const unsigned*)((const char*)(gbase) + (voff)[_i]), (PG8_LAS unsigned*)(lds + (bufoff) + ldsw + _i * 8192), 16, 0, 0); } while (0)
; #define PG8_LDA(dst, b, h) do { _Pragma("unroll") for (int m = 0; m < 4; ++m) _Pragma("unroll") for (int k = 0; k < 2; ++k) dst[m][k] = *(const PG8_LAS bf16x8*)(lds + PG8_SA(b, h) + aoff + m * 2048 + k * 1024); } while (0)
; #define PG8_LDB(dst, b, h) do { _Pragma("unroll") for (int n = 0; n < 2; ++n) _Pragma("unroll") for (int k = 0; k < 2; ++k) dst[n][k] = *(const PG8_LAS bf16x8*)(lds + PG8_SB(b, h) + boff + n * 2048 + k * 1024); } while (0)
; #define PG8_MMA(ai, bj, At, Bt) do { __builtin_amdgcn_s_setprio(1); _Pragma("unroll") for (int m = 0; m < 4; ++m) _Pragma("unroll") for (int n = 0; n < 2; ++n) _Pragma("unroll") for (int k = 0; k < 2; ++k) \
;         acc[ai][bj][m][n] = __builtin_amdgcn_mfma_f32_16x16x32_bf16(Bt[n][k], At[m][k], acc[ai][bj][m][n], 0, 0, 0); __builtin_amdgcn_s_setprio(0); } while (0)
; #define PG8_WAIT_V(n) asm volatile("s_waitcnt vmcnt(" #n ")" ::: "memory")
; #define PG8_WAIT_L(n) asm volatile("s_waitcnt lgkmcnt(" #n ")" ::: "memory")
; #define PG8_BAR __builtin_amdgcn_s_barrier()
; #define PG8_SCHED __builtin_amdgcn_sched_barrier(0)
; template <class Epi, class Sched, bool ALIGN_EPI = false, bool SP2 = false>
; __device__ __forceinline__ void gemm_phase(PG8_LAS unsigned char* lds, const Gemm g, const Sched& S, const Epi& E) {
;     ...
;             PG8_LDB(B0, 1, 0); PG8_LDB(B1, 1, 1); PG8_SCHED; PG8_LDA(At, 1, 0); PG8_STAGE(PG8_SA(0, 1), a2 + hstepA, voffA);
;             PG8_WAIT_V(8); PG8_WAIT_L(0); PG8_BAR; PG8_MMA(0, 0, At, B0); PG8_MMA(0, 1, At, B1); PG8_BAR; PG8_SCHED;
	ds_read_b128 v[128:131], v240
	ds_read_b128 v[132:135], v240 offset:1024
	ds_read_b128 v[136:139], v240 offset:2048
	ds_read_b128 v[140:143], v240 offset:3072
	ds_read_b128 v[144:147], v241
	ds_read_b128 v[148:151], v241 offset:1024
	ds_read_b128 v[152:155], v241 offset:2048
	ds_read_b128 v[156:159], v241 offset:3072
	s_add_u32 s52, s52, 0xb0000
	s_addc_u32 s53, s53, 0
	s_mov_b32 m0, s35
	v_lshl_add_u64 v[220:221], s[52:53], 0, v[192:193]
	ds_read_b128 v[160:163], v237 offset:32768
	ds_read_b128 v[164:167], v237 offset:33792
	ds_read_b128 v[170:173], v237 offset:34816
	ds_read_b128 v[198:201], v237 offset:35840
	ds_read_b128 v[202:205], v237 offset:36864
	ds_read_b128 v[206:209], v237 offset:37888
	ds_read_b128 v[210:213], v237 offset:38912
	ds_read_b128 v[214:217], v237 offset:39936
	global_load_lds_dwordx4 v[220:221], off
	v_lshl_add_u64 v[220:221], s[52:53], 0, v[190:191]
	s_mov_b32 m0, s54
	s_nop 0
	global_load_lds_dwordx4 v[220:221], off
	s_waitcnt vmcnt(8)
	s_waitcnt lgkmcnt(0)
	s_barrier
	s_setprio 1
	s_waitcnt lgkmcnt(0)
	v_mfma_f32_16x16x32_bf16 v[124:127], v[128:131], v[160:163], v[124:127]
	v_mfma_f32_16x16x32_bf16 v[120:123], v[136:139], v[160:163], v[120:123]
	v_mfma_f32_16x16x32_bf16 v[108:111], v[128:131], v[170:173], v[108:111]
	v_mfma_f32_16x16x32_bf16 v[104:107], v[136:139], v[170:173], v[104:107]
	v_mfma_f32_16x16x32_bf16 v[92:95], v[128:131], v[202:205], v[92:95]
	v_mfma_f32_16x16x32_bf16 v[88:91], v[136:139], v[202:205], v[88:91]
	v_mfma_f32_16x16x32_bf16 v[76:79], v[128:131], v[210:213], v[76:79]
	v_mfma_f32_16x16x32_bf16 v[72:75], v[136:139], v[210:213], v[72:75]
	v_mfma_f32_16x16x32_bf16 v[124:127], v[132:135], v[164:167], v[124:127]
	v_mfma_f32_16x16x32_bf16 v[120:123], v[140:143], v[164:167], v[120:123]
	v_mfma_f32_16x16x32_bf16 v[108:111], v[132:135], v[198:201], v[108:111]
	v_mfma_f32_16x16x32_bf16 v[104:107], v[140:143], v[198:201], v[104:107]
	v_mfma_f32_16x16x32_bf16 v[92:95], v[132:135], v[206:209], v[92:95]
	v_mfma_f32_16x16x32_bf16 v[88:91], v[140:143], v[206:209], v[88:91]
	v_mfma_f32_16x16x32_bf16 v[76:79], v[132:135], v[214:217], v[76:79]
	v_mfma_f32_16x16x32_bf16 v[72:75], v[140:143], v[214:217], v[72:75]
	s_setprio 0
	s_setprio 1
	v_mfma_f32_16x16x32_bf16 v[116:119], v[144:147], v[160:163], v[116:119]
	v_mfma_f32_16x16x32_bf16 v[112:115], v[152:155], v[160:163], v[112:115]
	v_mfma_f32_16x16x32_bf16 v[100:103], v[144:147], v[170:173], v[100:103]
	v_mfma_f32_16x16x32_bf16 v[96:99], v[152:155], v[170:173], v[96:99]
	v_mfma_f32_16x16x32_bf16 v[84:87], v[144:147], v[202:205], v[84:87]
	v_mfma_f32_16x16x32_bf16 v[80:83], v[152:155], v[202:205], v[80:83]
	v_mfma_f32_16x16x32_bf16 v[68:71], v[144:147], v[210:213], v[68:71]
	v_mfma_f32_16x16x32_bf16 v[64:67], v[152:155], v[210:213], v[64:67]
	v_mfma_f32_16x16x32_bf16 v[116:119], v[148:151], v[164:167], v[116:119]
	v_mfma_f32_16x16x32_bf16 v[112:115], v[156:159], v[164:167], v[112:115]
	v_mfma_f32_16x16x32_bf16 v[100:103], v[148:151], v[198:201], v[100:103]
	v_mfma_f32_16x16x32_bf16 v[96:99], v[156:159], v[198:201], v[96:99]
	v_mfma_f32_16x16x32_bf16 v[84:87], v[148:151], v[206:209], v[84:87]
	s_add_i32 s52, s64, s2
	v_mfma_f32_16x16x32_bf16 v[80:83], v[156:159], v[206:209], v[80:83]
	v_lshl_add_u64 v[178:179], v[178:179], 0, s[30:31]
	v_mfma_f32_16x16x32_bf16 v[68:71], v[148:151], v[214:217], v[68:71]
	s_mov_b32 m0, s52
	v_mfma_f32_16x16x32_bf16 v[64:67], v[156:159], v[214:217], v[64:67]
	s_setprio 0
	s_barrier
; #define PG8_STAGE(bufoff, gbase, voff) do { _Pragma("unroll") for (int _i = 0; _i < 2; ++_i) \
;         __builtin_amdgcn_global_load_lds((const unsigned*)((const char*)(gbase) + (voff)[_i]), (PG8_LAS unsigned*)(lds + (bufoff) + ldsw + _i * 8192), 16, 0, 0); } while (0)
; #define PG8_LDA(dst, b, h) do { _Pragma("unroll") for (int m = 0; m < 4; ++m) _Pragma("unroll") for (int k = 0; k < 2; ++k) dst[m][k] = *(const PG8_LAS bf16x8*)(lds + PG8_SA(b, h) + aoff + m * 2048 + k * 1024); } while (0)
; #define PG8_MMA(ai, bj, At, Bt) do { __builtin_amdgcn_s_setprio(1); _Pragma("unroll") for (int m = 0; m < 4; ++m) _Pragma("unroll") for (int n = 0; n < 2; ++n) _Pragma("unroll") for (int k = 0; k < 2; ++k) \
;         acc[ai][bj][m][n] = __builtin_amdgcn_mfma_f32_16x16x32_bf16(Bt[n][k], At[m][k], acc[ai][bj][m][n], 0, 0, 0); __builtin_amdgcn_s_setprio(0); } while (0)
; #define PG8_WAIT_V(n) asm volatile("s_waitcnt vmcnt(" #n ")" ::: "memory")
; #define PG8_WAIT_L(n) asm volatile("s_waitcnt lgkmcnt(" #n ")" ::: "memory")
; #define PG8_BAR __builtin_amdgcn_s_barrier()
; #define PG8_SCHED __builtin_amdgcn_sched_barrier(0)
; template <class Epi, class Sched, bool ALIGN_EPI = false, bool SP2 = false>
; __device__ __forceinline__ void gemm_phase(PG8_LAS unsigned char* lds, const Gemm g, const Sched& S, const Epi& E) {
;     ...
;         for (int t = 0; t < nt; t += 2) {
;             const bool last = (t == nt - 2);
;             const char* a1 = cA + (size_t)(t + 1) * kstepA;
;             const char* a2 = last ? nA : cA + (size_t)(t + 2) * kstepA; const char* b2 = last ? nB : cB + (size_t)(t + 2) * kstep;
;             const char* a3 = a2 + kstepA; const char* b3 = b2 + kstep;
;     ...
;             PG8_LDA(At, 1, 1); PG8_STAGE(PG8_SB(1, 0), b3, voffB); PG8_STAGE(PG8_SB(1, 1), b3 + hstep, voffB); PG8_STAGE(PG8_SA(1, 0), a3, voffA);
;             PG8_WAIT_V(8); PG8_WAIT_L(0); PG8_BAR; PG8_MMA(1, 0, At, B0); PG8_MMA(1, 1, At, B1); PG8_BAR; PG8_SCHED;
	ds_read_b128 v[160:163], v237 offset:49152
	ds_read_b128 v[164:167], v237 offset:50176
	ds_read_b128 v[170:173], v237 offset:51200
	ds_read_b128 v[198:201], v237 offset:52224
	ds_read_b128 v[202:205], v237 offset:53248
	ds_read_b128 v[206:209], v237 offset:54272
	ds_read_b128 v[210:213], v237 offset:55296
	ds_read_b128 v[214:217], v237 offset:56320
	global_load_lds_dwordx4 v[178:179], off
	s_add_i32 m0, s52, 0x2000
	s_add_u32 s50, s50, 0xb0080
	v_lshl_add_u64 v[178:179], v[218:219], 0, s[30:31]
	s_addc_u32 s51, s51, 0
	s_add_i32 s52, s65, s2
	global_load_lds_dwordx4 v[178:179], off
	v_lshl_add_u64 v[178:179], s[50:51], 0, v[168:169]
	s_mov_b32 m0, s52
	s_nop 0
	global_load_lds_dwordx4 v[178:179], off
	v_lshl_add_u64 v[178:179], s[50:51], 0, v[188:189]
	s_add_i32 m0, s52, 0x2000
	s_nop 0
	global_load_lds_dwordx4 v[178:179], off
	v_lshl_add_u64 v[178:179], s[48:49], 0, v[192:193]
	s_mov_b32 m0, s57
	s_nop 0
	global_load_lds_dwordx4 v[178:179], off
	v_lshl_add_u64 v[178:179], s[48:49], 0, v[190:191]
	s_mov_b32 m0, s60
	s_nop 0
	global_load_lds_dwordx4 v[178:179], off
	s_waitcnt vmcnt(8)
	s_waitcnt lgkmcnt(0)
	s_barrier
	s_setprio 1
	s_waitcnt lgkmcnt(0)
	v_mfma_f32_16x16x32_bf16 v[60:63], v[128:131], v[160:163], v[60:63]
	v_mfma_f32_16x16x32_bf16 v[56:59], v[136:139], v[160:163], v[56:59]
	v_mfma_f32_16x16x32_bf16 v[44:47], v[128:131], v[170:173], v[44:47]
	v_mfma_f32_16x16x32_bf16 v[40:43], v[136:139], v[170:173], v[40:43]
	v_mfma_f32_16x16x32_bf16 v[28:31], v[128:131], v[202:205], v[28:31]
	v_mfma_f32_16x16x32_bf16 v[24:27], v[136:139], v[202:205], v[24:27]
	v_mfma_f32_16x16x32_bf16 v[12:15], v[128:131], v[210:213], v[12:15]
	v_mfma_f32_16x16x32_bf16 v[8:11], v[136:139], v[210:213], v[8:11]
	v_mfma_f32_16x16x32_bf16 v[60:63], v[132:135], v[164:167], v[60:63]
	v_mfma_f32_16x16x32_bf16 v[56:59], v[140:143], v[164:167], v[56:59]
	v_mfma_f32_16x16x32_bf16 v[44:47], v[132:135], v[198:201], v[44:47]
	v_mfma_f32_16x16x32_bf16 v[40:43], v[140:143], v[198:201], v[40:43]
	v_mfma_f32_16x16x32_bf16 v[28:31], v[132:135], v[206:209], v[28:31]
	v_mfma_f32_16x16x32_bf16 v[24:27], v[140:143], v[206:209], v[24:27]
	s_add_i32 s7, s7, 2
	v_mfma_f32_16x16x32_bf16 v[12:15], v[132:135], v[214:217], v[12:15]
	s_add_u32 s5, s5, 0x100
	v_mfma_f32_16x16x32_bf16 v[8:11], v[140:143], v[214:217], v[8:11]
	s_addc_u32 s6, s6, 0
	s_setprio 0
	s_setprio 1
	v_mfma_f32_16x16x32_bf16 v[52:55], v[144:147], v[160:163], v[52:55]
	s_add_u32 s38, s38, 0x8000
	v_mfma_f32_16x16x32_bf16 v[48:51], v[152:155], v[160:163], v[48:51]
	s_addc_u32 s39, s39, 0
	v_mfma_f32_16x16x32_bf16 v[36:39], v[144:147], v[170:173], v[36:39]
	s_add_u32 s48, s38, 0xfff54000
	v_mfma_f32_16x16x32_bf16 v[32:35], v[152:155], v[170:173], v[32:35]
	s_addc_u32 s49, s39, -1
	v_mfma_f32_16x16x32_bf16 v[20:23], v[144:147], v[202:205], v[20:23]
	s_cmp_eq_u32 s7, 40
	v_mfma_f32_16x16x32_bf16 v[16:19], v[152:155], v[202:205], v[16:19]
	s_cselect_b32 s52, s44, s48
	v_mfma_f32_16x16x32_bf16 v[4:7], v[144:147], v[210:213], v[4:7]
	s_cselect_b32 s53, s45, s49
	v_mfma_f32_16x16x32_bf16 v[0:3], v[152:155], v[210:213], v[0:3]
	s_cselect_b32 s50, s46, s5
	v_mfma_f32_16x16x32_bf16 v[52:55], v[148:151], v[164:167], v[52:55]
	s_cselect_b32 s51, s47, s6
	v_mfma_f32_16x16x32_bf16 v[48:51], v[156:159], v[164:167], v[48:51]
	s_add_u32 s48, s52, 0x4000
	v_mfma_f32_16x16x32_bf16 v[36:39], v[148:151], v[198:201], v[36:39]
	s_addc_u32 s49, s53, 0
	v_mfma_f32_16x16x32_bf16 v[32:35], v[156:159], v[198:201], v[32:35]
	s_add_i32 s64, 0, 0x10000
	v_mfma_f32_16x16x32_bf16 v[20:23], v[148:151], v[206:209], v[20:23]
	s_add_i32 s74, 0, 0x14000
	v_mfma_f32_16x16x32_bf16 v[16:19], v[156:159], v[206:209], v[16:19]
	v_add_u32_e32 v242, s64, v236
	v_mfma_f32_16x16x32_bf16 v[4:7], v[148:151], v[214:217], v[4:7]
	v_add_u32_e32 v243, s74, v236
	v_mfma_f32_16x16x32_bf16 v[0:3], v[156:159], v[214:217], v[0:3]
	s_setprio 0
	s_barrier
